# GEMM K-loops: s_setprio 1 moved ahead of the load->compute handoff barrier (compute wave holds priority at release); on top of P4 split + P3 carry move
# baseline (speedup 1.0000x reference)
; #define PG8_STAGE(bufoff, gbase, voff) do { _Pragma("unroll") for (int _i = 0; _i < 2; ++_i) \
;         __builtin_amdgcn_global_load_lds((const unsigned*)((const char*)(gbase) + (voff)[_i]), (PG8_LAS unsigned*)(lds + (bufoff) + ldsw + _i * 8192), 16, 0, 0); } while (0)
; #define PG8_LDA(dst, b, h) do { _Pragma("unroll") for (int m = 0; m < 4; ++m) _Pragma("unroll") for (int k = 0; k < 2; ++k) dst[m][k] = *(const PG8_LAS bf16x8*)(lds + PG8_SA(b, h) + aoff + m * 2048 + k * 1024); } while (0)
; #define PG8_LDB(dst, b, h) do { _Pragma("unroll") for (int n = 0; n < 2; ++n) _Pragma("unroll") for (int k = 0; k < 2; ++k) dst[n][k] = *(const PG8_LAS bf16x8*)(lds + PG8_SB(b, h) + boff + n * 2048 + k * 1024); } while (0)
; #define PG8_MMA(ai, bj, At, Bt) do { __builtin_amdgcn_s_setprio(1); _Pragma("unroll") for (int m = 0; m < 4; ++m) _Pragma("unroll") for (int n = 0; n < 2; ++n) _Pragma("unroll") for (int k = 0; k < 2; ++k) \
;         acc[ai][bj][m][n] = __builtin_amdgcn_mfma_f32_16x16x32_bf16(Bt[n][k], At[m][k], acc[ai][bj][m][n], 0, 0, 0); __builtin_amdgcn_s_setprio(0); } while (0)
; #define PG8_WAIT_V(n) asm volatile("s_waitcnt vmcnt(" #n ")" ::: "memory")
; #define PG8_WAIT_L(n) asm volatile("s_waitcnt lgkmcnt(" #n ")" ::: "memory")
; template <class Epi, class Sched, bool ALIGN_EPI = false, bool SP2 = false, bool GRP = false>
; __device__ __forceinline__ void gemm_phase(PG8_LAS unsigned char* lds, const Gemm g, const Sched& S, const Epi& E) {
;     ...
;             const bool last = (t == nt - 2);
;             const char* a1 = cA + (size_t)(t + 1) * kstep;
;             const char* a2 = last ? nA : cA + (size_t)(t + 2) * kstep; const char* b2 = last ? nB : cB + (size_t)(t + 2) * kstep;
;             const char* a3 = a2 + kstep; const char* b3 = b2 + kstep;
;             if (last && has_next) S.a_ready(nxt);
;             if constexpr (SP2) {
;             PG8_LDB(B0, 0, 0); PG8_LDB(B1, 0, 1); PG8_SCHED; PG8_LDA(At, 0, 0); PG8_STAGE(PG8_SA(1, 1), a1 + hstep, voffA);
;             PG8_WAIT_V(8); PG8_WAIT_L(0); PG8_BAR; PG8_MMA(0, 0, At, B0); PG8_MMA(0, 1, At, B1); PG8_BAR; PG8_SCHED;
;             PG8_LDA(At, 0, 1); PG8_STAGE(PG8_SB(0, 0), b2, voffB); PG8_STAGE(PG8_SB(0, 1), b2 + hstep, voffB); PG8_STAGE(PG8_SA(0, 0), a2, voffA);
;             PG8_WAIT_V(8); PG8_WAIT_L(0); PG8_BAR; PG8_MMA(1, 0, At, B0); PG8_MMA(1, 1, At, B1); PG8_BAR; PG8_SCHED;
.LBB0_275:
	s_add_i32 s30, s3, 2
	s_add_u32 s42, s64, 0x80
	s_addc_u32 s43, s65, 0
	s_add_i32 s48, 0, 0x10000
	s_cmp_eq_u32 s76, s3
	s_cselect_b32 s71, s7, s43
	s_cselect_b32 s70, s6, s42
	v_add_u32_e32 v144, s48, v147
	s_cselect_b32 s43, s29, s41
	s_cselect_b32 s42, s28, s40
	s_add_i32 s3, 0, 0x14000
	ds_read_b128 v[140:143], v144
	ds_read_b128 v[150:153], v144 offset:1024
	ds_read_b128 v[154:157], v144 offset:2048
	ds_read_b128 v[158:161], v144 offset:3072
	v_add_u32_e32 v144, s3, v147
	ds_read_b128 v[162:165], v144
	ds_read_b128 v[166:169], v144 offset:1024
	ds_read_b128 v[170:173], v144 offset:2048
	ds_read_b128 v[174:177], v144 offset:3072
	v_lshl_add_u64 v[144:145], s[64:65], 0, v[136:137]
	s_add_i32 m0, s62, 0xc000
	ds_read_b128 v[178:181], v149
	ds_read_b128 v[182:185], v149 offset:1024
	ds_read_b128 v[186:189], v149 offset:2048
	ds_read_b128 v[190:193], v149 offset:3072
	ds_read_b128 v[194:197], v149 offset:4096
	ds_read_b128 v[198:201], v149 offset:5120
	ds_read_b128 v[210:213], v149 offset:6144
	ds_read_b128 v[222:225], v149 offset:7168
	global_load_lds_dwordx4 v[144:145], off
	v_lshl_add_u64 v[144:145], s[64:65], 0, v[138:139]
	s_add_i32 m0, s62, 0xe000
	s_nop 0
	global_load_lds_dwordx4 v[144:145], off
	s_waitcnt vmcnt(8)
	s_waitcnt lgkmcnt(0)
	s_setprio 1
	s_barrier
	s_waitcnt lgkmcnt(0)
	v_mfma_f32_16x16x32_bf16 v[122:125], v[140:143], v[178:181], v[122:125]
	v_mfma_f32_16x16x32_bf16 v[126:129], v[154:157], v[178:181], v[126:129]
	v_mfma_f32_16x16x32_bf16 v[110:113], v[140:143], v[186:189], v[110:113]
	v_mfma_f32_16x16x32_bf16 v[106:109], v[154:157], v[186:189], v[106:109]
	v_mfma_f32_16x16x32_bf16 v[94:97], v[140:143], v[194:197], v[94:97]
	v_mfma_f32_16x16x32_bf16 v[90:93], v[154:157], v[194:197], v[90:93]
	v_mfma_f32_16x16x32_bf16 v[78:81], v[140:143], v[210:213], v[78:81]
	v_mfma_f32_16x16x32_bf16 v[74:77], v[154:157], v[210:213], v[74:77]
	v_mfma_f32_16x16x32_bf16 v[122:125], v[150:153], v[182:185], v[122:125]
	v_mfma_f32_16x16x32_bf16 v[126:129], v[158:161], v[182:185], v[126:129]
	v_mfma_f32_16x16x32_bf16 v[110:113], v[150:153], v[190:193], v[110:113]
	v_mfma_f32_16x16x32_bf16 v[106:109], v[158:161], v[190:193], v[106:109]
	v_mfma_f32_16x16x32_bf16 v[94:97], v[150:153], v[198:201], v[94:97]
	v_mfma_f32_16x16x32_bf16 v[90:93], v[158:161], v[198:201], v[90:93]
	v_mfma_f32_16x16x32_bf16 v[78:81], v[150:153], v[222:225], v[78:81]
	v_mfma_f32_16x16x32_bf16 v[74:77], v[158:161], v[222:225], v[74:77]
	s_setprio 0
	s_setprio 1
	v_mfma_f32_16x16x32_bf16 v[118:121], v[162:165], v[178:181], v[118:121]
	v_mfma_f32_16x16x32_bf16 v[114:117], v[170:173], v[178:181], v[114:117]
	v_mfma_f32_16x16x32_bf16 v[102:105], v[162:165], v[186:189], v[102:105]
	v_mfma_f32_16x16x32_bf16 v[98:101], v[170:173], v[186:189], v[98:101]
	v_mfma_f32_16x16x32_bf16 v[86:89], v[162:165], v[194:197], v[86:89]
	v_mfma_f32_16x16x32_bf16 v[82:85], v[170:173], v[194:197], v[82:85]
	v_mfma_f32_16x16x32_bf16 v[70:73], v[162:165], v[210:213], v[70:73]
	v_mfma_f32_16x16x32_bf16 v[66:69], v[170:173], v[210:213], v[66:69]
	v_mfma_f32_16x16x32_bf16 v[118:121], v[166:169], v[182:185], v[118:121]
	v_mfma_f32_16x16x32_bf16 v[114:117], v[174:177], v[182:185], v[114:117]
	v_mfma_f32_16x16x32_bf16 v[102:105], v[166:169], v[190:193], v[102:105]
	v_mfma_f32_16x16x32_bf16 v[98:101], v[174:177], v[190:193], v[98:101]
	v_mfma_f32_16x16x32_bf16 v[86:89], v[166:169], v[198:201], v[86:89]
	v_mfma_f32_16x16x32_bf16 v[82:85], v[174:177], v[198:201], v[82:85]
	v_mfma_f32_16x16x32_bf16 v[70:73], v[166:169], v[222:225], v[70:73]
	v_mfma_f32_16x16x32_bf16 v[66:69], v[174:177], v[222:225], v[66:69]
	s_setprio 0
	s_barrier
	s_add_i32 s48, s48, s60
	v_lshl_add_u64 v[144:145], s[42:43], 0, v[0:1]
	s_mov_b32 m0, s48
	ds_read_b128 v[178:181], v149 offset:16384
	ds_read_b128 v[182:185], v149 offset:17408
	ds_read_b128 v[186:189], v149 offset:18432
	ds_read_b128 v[190:193], v149 offset:19456
	ds_read_b128 v[194:197], v149 offset:20480
	ds_read_b128 v[198:201], v149 offset:21504
	ds_read_b128 v[210:213], v149 offset:22528
	ds_read_b128 v[222:225], v149 offset:23552
	global_load_lds_dwordx4 v[144:145], off
	s_add_i32 m0, s48, 0x2000
	v_lshl_add_u64 v[202:203], s[42:43], 0, v[130:131]
	s_add_u32 s42, s42, s14
	s_addc_u32 s43, s43, s15
	s_add_i32 s3, s3, s60
	global_load_lds_dwordx4 v[202:203], off
	v_lshl_add_u64 v[214:215], s[42:43], 0, v[0:1]
	s_mov_b32 m0, s3
	v_lshl_add_u64 v[218:219], s[42:43], 0, v[130:131]
	global_load_lds_dwordx4 v[214:215], off
	s_add_i32 m0, s3, 0x2000
	v_lshl_add_u64 v[220:221], s[70:71], 0, v[134:135]
	global_load_lds_dwordx4 v[218:219], off
	s_mov_b32 m0, s62
	v_lshl_add_u64 v[226:227], s[70:71], 0, v[132:133]
	global_load_lds_dwordx4 v[220:221], off
	s_mov_b32 m0, s63
	s_nop 0
	global_load_lds_dwordx4 v[226:227], off
	s_waitcnt vmcnt(8)
	s_waitcnt lgkmcnt(0)
	s_setprio 1
	s_barrier
; #define PG8_STAGE(bufoff, gbase, voff) do { _Pragma("unroll") for (int _i = 0; _i < 2; ++_i) \
;         __builtin_amdgcn_global_load_lds((const unsigned*)((const char*)(gbase) + (voff)[_i]), (PG8_LAS unsigned*)(lds + (bufoff) + ldsw + _i * 8192), 16, 0, 0); } while (0)
; #define PG8_LDA(dst, b, h) do { _Pragma("unroll") for (int m = 0; m < 4; ++m) _Pragma("unroll") for (int k = 0; k < 2; ++k) dst[m][k] = *(const PG8_LAS bf16x8*)(lds + PG8_SA(b, h) + aoff + m * 2048 + k * 1024); } while (0)
; #define PG8_LDB(dst, b, h) do { _Pragma("unroll") for (int n = 0; n < 2; ++n) _Pragma("unroll") for (int k = 0; k < 2; ++k) dst[n][k] = *(const PG8_LAS bf16x8*)(lds + PG8_SB(b, h) + boff + n * 2048 + k * 1024); } while (0)
; #define PG8_MMA(ai, bj, At, Bt) do { __builtin_amdgcn_s_setprio(1); _Pragma("unroll") for (int m = 0; m < 4; ++m) _Pragma("unroll") for (int n = 0; n < 2; ++n) _Pragma("unroll") for (int k = 0; k < 2; ++k) \
;         acc[ai][bj][m][n] = __builtin_amdgcn_mfma_f32_16x16x32_bf16(Bt[n][k], At[m][k], acc[ai][bj][m][n], 0, 0, 0); __builtin_amdgcn_s_setprio(0); } while (0)
; #define PG8_WAIT_V(n) asm volatile("s_waitcnt vmcnt(" #n ")" ::: "memory")
; #define PG8_WAIT_L(n) asm volatile("s_waitcnt lgkmcnt(" #n ")" ::: "memory")
; #define PG8_BAR __builtin_amdgcn_s_barrier()
; #define PG8_SCHED __builtin_amdgcn_sched_barrier(0)
; template <class Epi, class Sched, bool ALIGN_EPI = false, bool SP2 = false, bool GRP = false>
; __device__ __forceinline__ void gemm_phase(PG8_LAS unsigned char* lds, const Gemm g, const Sched& S, const Epi& E) {
;     ...
;             PG8_WAIT_V(8); PG8_WAIT_L(0); PG8_BAR; PG8_MMA(1, 0, At, B0); PG8_MMA(1, 1, At, B1); PG8_BAR; PG8_SCHED;
;             PG8_LDB(B0, 1, 0); PG8_LDB(B1, 1, 1); PG8_SCHED; PG8_LDA(At, 1, 0); PG8_STAGE(PG8_SA(0, 1), a2 + hstep, voffA);
;             PG8_WAIT_V(8); PG8_WAIT_L(0); PG8_BAR; PG8_MMA(0, 0, At, B0); PG8_MMA(0, 1, At, B1); PG8_BAR; PG8_SCHED;
	s_waitcnt lgkmcnt(0)
	v_mfma_f32_16x16x32_bf16 v[62:65], v[140:143], v[178:181], v[62:65]
	v_mfma_f32_16x16x32_bf16 v[58:61], v[154:157], v[178:181], v[58:61]
	v_mfma_f32_16x16x32_bf16 v[46:49], v[140:143], v[186:189], v[46:49]
	v_mfma_f32_16x16x32_bf16 v[42:45], v[154:157], v[186:189], v[42:45]
	v_mfma_f32_16x16x32_bf16 v[30:33], v[140:143], v[194:197], v[30:33]
	v_mfma_f32_16x16x32_bf16 v[26:29], v[154:157], v[194:197], v[26:29]
	v_mfma_f32_16x16x32_bf16 v[14:17], v[140:143], v[210:213], v[14:17]
	v_mfma_f32_16x16x32_bf16 v[10:13], v[154:157], v[210:213], v[10:13]
	v_mfma_f32_16x16x32_bf16 v[62:65], v[150:153], v[182:185], v[62:65]
	v_mfma_f32_16x16x32_bf16 v[58:61], v[158:161], v[182:185], v[58:61]
	v_mfma_f32_16x16x32_bf16 v[46:49], v[150:153], v[190:193], v[46:49]
	v_mfma_f32_16x16x32_bf16 v[42:45], v[158:161], v[190:193], v[42:45]
	v_mfma_f32_16x16x32_bf16 v[30:33], v[150:153], v[198:201], v[30:33]
	v_mfma_f32_16x16x32_bf16 v[26:29], v[158:161], v[198:201], v[26:29]
	v_mfma_f32_16x16x32_bf16 v[14:17], v[150:153], v[222:225], v[14:17]
	v_mfma_f32_16x16x32_bf16 v[10:13], v[158:161], v[222:225], v[10:13]
	s_setprio 0
	s_setprio 1
	v_mfma_f32_16x16x32_bf16 v[54:57], v[162:165], v[178:181], v[54:57]
	v_mfma_f32_16x16x32_bf16 v[50:53], v[170:173], v[178:181], v[50:53]
	v_mfma_f32_16x16x32_bf16 v[38:41], v[162:165], v[186:189], v[38:41]
	v_mfma_f32_16x16x32_bf16 v[34:37], v[170:173], v[186:189], v[34:37]
	v_mfma_f32_16x16x32_bf16 v[22:25], v[162:165], v[194:197], v[22:25]
	v_mfma_f32_16x16x32_bf16 v[18:21], v[170:173], v[194:197], v[18:21]
	v_mfma_f32_16x16x32_bf16 v[6:9], v[162:165], v[210:213], v[6:9]
	v_mfma_f32_16x16x32_bf16 v[2:5], v[170:173], v[210:213], v[2:5]
	v_mfma_f32_16x16x32_bf16 v[54:57], v[166:169], v[182:185], v[54:57]
	v_mfma_f32_16x16x32_bf16 v[50:53], v[174:177], v[182:185], v[50:53]
	v_mfma_f32_16x16x32_bf16 v[38:41], v[166:169], v[190:193], v[38:41]
	v_mfma_f32_16x16x32_bf16 v[34:37], v[174:177], v[190:193], v[34:37]
	v_mfma_f32_16x16x32_bf16 v[22:25], v[166:169], v[198:201], v[22:25]
	v_mfma_f32_16x16x32_bf16 v[18:21], v[174:177], v[198:201], v[18:21]
	v_mfma_f32_16x16x32_bf16 v[6:9], v[166:169], v[222:225], v[6:9]
	v_mfma_f32_16x16x32_bf16 v[2:5], v[174:177], v[222:225], v[2:5]
	s_setprio 0
	s_barrier
	s_add_i32 s3, 0, 0x18000
	s_add_i32 s48, 0, 0x1c000
	v_add_u32_e32 v158, s3, v147
	v_add_u32_e32 v174, s48, v147
	ds_read_b128 v[140:143], v158
	ds_read_b128 v[150:153], v158 offset:1024
	ds_read_b128 v[154:157], v158 offset:2048
	ds_read_b128 v[158:161], v158 offset:3072
	ds_read_b128 v[162:165], v174
	ds_read_b128 v[166:169], v174 offset:1024
	ds_read_b128 v[170:173], v174 offset:2048
	ds_read_b128 v[174:177], v174 offset:3072
	s_add_u32 s42, s70, s14
	s_addc_u32 s43, s71, s15
	s_mov_b32 m0, s67
	v_lshl_add_u64 v[228:229], s[42:43], 0, v[134:135]
	ds_read_b128 v[178:181], v149 offset:32768
	ds_read_b128 v[182:185], v149 offset:33792
	ds_read_b128 v[186:189], v149 offset:34816
	ds_read_b128 v[190:193], v149 offset:35840
	ds_read_b128 v[194:197], v149 offset:36864
	ds_read_b128 v[198:201], v149 offset:37888
	ds_read_b128 v[210:213], v149 offset:38912
	ds_read_b128 v[222:225], v149 offset:39936
	global_load_lds_dwordx4 v[228:229], off
	v_lshl_add_u64 v[228:229], s[42:43], 0, v[132:133]
	s_mov_b32 m0, s72
	s_nop 0
	global_load_lds_dwordx4 v[228:229], off
	s_waitcnt vmcnt(8)
	s_waitcnt lgkmcnt(0)
	s_setprio 1
	s_barrier
	s_waitcnt lgkmcnt(0)
	v_mfma_f32_16x16x32_bf16 v[122:125], v[140:143], v[178:181], v[122:125]
	v_mfma_f32_16x16x32_bf16 v[126:129], v[154:157], v[178:181], v[126:129]
	v_mfma_f32_16x16x32_bf16 v[110:113], v[140:143], v[186:189], v[110:113]
	v_mfma_f32_16x16x32_bf16 v[106:109], v[154:157], v[186:189], v[106:109]
	v_mfma_f32_16x16x32_bf16 v[94:97], v[140:143], v[194:197], v[94:97]
	v_mfma_f32_16x16x32_bf16 v[90:93], v[154:157], v[194:197], v[90:93]
	v_mfma_f32_16x16x32_bf16 v[78:81], v[140:143], v[210:213], v[78:81]
	v_mfma_f32_16x16x32_bf16 v[74:77], v[154:157], v[210:213], v[74:77]
	v_mfma_f32_16x16x32_bf16 v[122:125], v[150:153], v[182:185], v[122:125]
	v_mfma_f32_16x16x32_bf16 v[126:129], v[158:161], v[182:185], v[126:129]
	v_mfma_f32_16x16x32_bf16 v[110:113], v[150:153], v[190:193], v[110:113]
	v_mfma_f32_16x16x32_bf16 v[106:109], v[158:161], v[190:193], v[106:109]
	v_mfma_f32_16x16x32_bf16 v[94:97], v[150:153], v[198:201], v[94:97]
	v_mfma_f32_16x16x32_bf16 v[90:93], v[158:161], v[198:201], v[90:93]
	v_mfma_f32_16x16x32_bf16 v[78:81], v[150:153], v[222:225], v[78:81]
	v_mfma_f32_16x16x32_bf16 v[74:77], v[158:161], v[222:225], v[74:77]
	s_setprio 0
	s_setprio 1
	v_mfma_f32_16x16x32_bf16 v[118:121], v[162:165], v[178:181], v[118:121]
	v_mfma_f32_16x16x32_bf16 v[114:117], v[170:173], v[178:181], v[114:117]
	v_mfma_f32_16x16x32_bf16 v[102:105], v[162:165], v[186:189], v[102:105]
	v_mfma_f32_16x16x32_bf16 v[98:101], v[170:173], v[186:189], v[98:101]
	v_mfma_f32_16x16x32_bf16 v[86:89], v[162:165], v[194:197], v[86:89]
	v_mfma_f32_16x16x32_bf16 v[82:85], v[170:173], v[194:197], v[82:85]
	v_mfma_f32_16x16x32_bf16 v[70:73], v[162:165], v[210:213], v[70:73]
	v_mfma_f32_16x16x32_bf16 v[66:69], v[170:173], v[210:213], v[66:69]
	v_mfma_f32_16x16x32_bf16 v[118:121], v[166:169], v[182:185], v[118:121]
	v_mfma_f32_16x16x32_bf16 v[114:117], v[174:177], v[182:185], v[114:117]
	v_mfma_f32_16x16x32_bf16 v[102:105], v[166:169], v[190:193], v[102:105]
	v_mfma_f32_16x16x32_bf16 v[98:101], v[174:177], v[190:193], v[98:101]
	v_mfma_f32_16x16x32_bf16 v[86:89], v[166:169], v[198:201], v[86:89]
	v_mfma_f32_16x16x32_bf16 v[82:85], v[174:177], v[198:201], v[82:85]
	v_mfma_f32_16x16x32_bf16 v[70:73], v[166:169], v[222:225], v[70:73]
	v_mfma_f32_16x16x32_bf16 v[66:69], v[174:177], v[222:225], v[66:69]
	s_setprio 0
	s_barrier
; #define PG8_STAGE(bufoff, gbase, voff) do { _Pragma("unroll") for (int _i = 0; _i < 2; ++_i) \
;         __builtin_amdgcn_global_load_lds((const unsigned*)((const char*)(gbase) + (voff)[_i]), (PG8_LAS unsigned*)(lds + (bufoff) + ldsw + _i * 8192), 16, 0, 0); } while (0)
; #define PG8_LDA(dst, b, h) do { _Pragma("unroll") for (int m = 0; m < 4; ++m) _Pragma("unroll") for (int k = 0; k < 2; ++k) dst[m][k] = *(const PG8_LAS bf16x8*)(lds + PG8_SA(b, h) + aoff + m * 2048 + k * 1024); } while (0)
; #define PG8_MMA(ai, bj, At, Bt) do { __builtin_amdgcn_s_setprio(1); _Pragma("unroll") for (int m = 0; m < 4; ++m) _Pragma("unroll") for (int n = 0; n < 2; ++n) _Pragma("unroll") for (int k = 0; k < 2; ++k) \
;         acc[ai][bj][m][n] = __builtin_amdgcn_mfma_f32_16x16x32_bf16(Bt[n][k], At[m][k], acc[ai][bj][m][n], 0, 0, 0); __builtin_amdgcn_s_setprio(0); } while (0)
; #define PG8_WAIT_V(n) asm volatile("s_waitcnt vmcnt(" #n ")" ::: "memory")
; #define PG8_WAIT_L(n) asm volatile("s_waitcnt lgkmcnt(" #n ")" ::: "memory")
; #define PG8_BAR __builtin_amdgcn_s_barrier()
; #define PG8_SCHED __builtin_amdgcn_sched_barrier(0)
; template <class Epi, class Sched, bool ALIGN_EPI = false, bool SP2 = false, bool GRP = false>
; __device__ __forceinline__ void gemm_phase(PG8_LAS unsigned char* lds, const Gemm g, const Sched& S, const Epi& E) {
;     ...
;             PG8_LDA(At, 1, 1); PG8_STAGE(PG8_SB(1, 0), b3, voffB); PG8_STAGE(PG8_SB(1, 1), b3 + hstep, voffB); PG8_STAGE(PG8_SA(1, 0), a3, voffA);
;             PG8_WAIT_V(8); PG8_WAIT_L(0); PG8_BAR; PG8_MMA(1, 0, At, B0); PG8_MMA(1, 1, At, B1); PG8_BAR; PG8_SCHED;
	s_add_i32 s3, s3, s60
	v_lshl_add_u64 v[144:145], v[144:145], 0, s[36:37]
	s_mov_b32 m0, s3
	ds_read_b128 v[178:181], v149 offset:49152
	ds_read_b128 v[182:185], v149 offset:50176
	ds_read_b128 v[186:189], v149 offset:51200
	ds_read_b128 v[190:193], v149 offset:52224
	ds_read_b128 v[194:197], v149 offset:53248
	ds_read_b128 v[198:201], v149 offset:54272
	ds_read_b128 v[210:213], v149 offset:55296
	ds_read_b128 v[222:225], v149 offset:56320
	global_load_lds_dwordx4 v[144:145], off
	v_lshl_add_u64 v[144:145], v[202:203], 0, s[36:37]
	s_add_i32 m0, s3, 0x2000
	s_add_i32 s3, s48, s60
	global_load_lds_dwordx4 v[144:145], off
	v_lshl_add_u64 v[144:145], v[214:215], 0, s[36:37]
	s_mov_b32 m0, s3
	s_nop 0
	global_load_lds_dwordx4 v[144:145], off
	v_lshl_add_u64 v[144:145], v[218:219], 0, s[36:37]
	s_add_i32 m0, s3, 0x2000
	s_nop 0
	global_load_lds_dwordx4 v[144:145], off
	v_lshl_add_u64 v[144:145], v[220:221], 0, s[36:37]
	s_mov_b32 m0, s73
	s_nop 0
	global_load_lds_dwordx4 v[144:145], off
	v_lshl_add_u64 v[144:145], v[226:227], 0, s[36:37]
	s_mov_b32 m0, s74
	s_nop 0
	global_load_lds_dwordx4 v[144:145], off
	s_waitcnt vmcnt(8)
	s_waitcnt lgkmcnt(0)
	s_setprio 1
	s_barrier
	s_waitcnt lgkmcnt(0)
	v_mfma_f32_16x16x32_bf16 v[62:65], v[140:143], v[178:181], v[62:65]
	v_mfma_f32_16x16x32_bf16 v[58:61], v[154:157], v[178:181], v[58:61]
	v_mfma_f32_16x16x32_bf16 v[46:49], v[140:143], v[186:189], v[46:49]
	v_mfma_f32_16x16x32_bf16 v[42:45], v[154:157], v[186:189], v[42:45]
	v_mfma_f32_16x16x32_bf16 v[30:33], v[140:143], v[194:197], v[30:33]
	v_mfma_f32_16x16x32_bf16 v[26:29], v[154:157], v[194:197], v[26:29]
	v_mfma_f32_16x16x32_bf16 v[14:17], v[140:143], v[210:213], v[14:17]
	v_mfma_f32_16x16x32_bf16 v[10:13], v[154:157], v[210:213], v[10:13]
	v_mfma_f32_16x16x32_bf16 v[62:65], v[150:153], v[182:185], v[62:65]
	v_mfma_f32_16x16x32_bf16 v[58:61], v[158:161], v[182:185], v[58:61]
	v_mfma_f32_16x16x32_bf16 v[46:49], v[150:153], v[190:193], v[46:49]
	v_mfma_f32_16x16x32_bf16 v[42:45], v[158:161], v[190:193], v[42:45]
	v_mfma_f32_16x16x32_bf16 v[30:33], v[150:153], v[198:201], v[30:33]
	v_mfma_f32_16x16x32_bf16 v[26:29], v[158:161], v[198:201], v[26:29]
	v_mfma_f32_16x16x32_bf16 v[14:17], v[150:153], v[222:225], v[14:17]
	v_mfma_f32_16x16x32_bf16 v[10:13], v[158:161], v[222:225], v[10:13]
	s_setprio 0
	s_setprio 1
	v_mfma_f32_16x16x32_bf16 v[54:57], v[162:165], v[178:181], v[54:57]
	v_mfma_f32_16x16x32_bf16 v[50:53], v[170:173], v[178:181], v[50:53]
	v_mfma_f32_16x16x32_bf16 v[38:41], v[162:165], v[186:189], v[38:41]
	v_mfma_f32_16x16x32_bf16 v[34:37], v[170:173], v[186:189], v[34:37]
	v_mfma_f32_16x16x32_bf16 v[22:25], v[162:165], v[194:197], v[22:25]
	v_mfma_f32_16x16x32_bf16 v[18:21], v[170:173], v[194:197], v[18:21]
	v_mfma_f32_16x16x32_bf16 v[6:9], v[162:165], v[210:213], v[6:9]
	v_mfma_f32_16x16x32_bf16 v[2:5], v[170:173], v[210:213], v[2:5]
	v_mfma_f32_16x16x32_bf16 v[54:57], v[166:169], v[182:185], v[54:57]
	v_mfma_f32_16x16x32_bf16 v[50:53], v[174:177], v[182:185], v[50:53]
	v_mfma_f32_16x16x32_bf16 v[38:41], v[166:169], v[190:193], v[38:41]
	v_mfma_f32_16x16x32_bf16 v[34:37], v[174:177], v[190:193], v[34:37]
	v_mfma_f32_16x16x32_bf16 v[22:25], v[166:169], v[198:201], v[22:25]
	v_mfma_f32_16x16x32_bf16 v[18:21], v[174:177], v[198:201], v[18:21]
	v_mfma_f32_16x16x32_bf16 v[6:9], v[166:169], v[222:225], v[6:9]
	v_mfma_f32_16x16x32_bf16 v[2:5], v[174:177], v[222:225], v[2:5]
	s_setprio 0
	s_barrier
	s_add_u32 s64, s64, 0x100
	s_addc_u32 s65, s65, 0
	s_add_u32 s40, s40, 0x100
	s_addc_u32 s41, s41, 0
	s_cmp_ge_i32 s30, s75
	s_mov_b32 s3, s30
	s_cbranch_scc0 .LBB0_275

; #define PG8_STAGE(bufoff, gbase, voff) do { _Pragma("unroll") for (int _i = 0; _i < 2; ++_i) \
;         __builtin_amdgcn_global_load_lds((const unsigned*)((const char*)(gbase) + (voff)[_i]), (PG8_LAS unsigned*)(lds + (bufoff) + ldsw + _i * 8192), 16, 0, 0); } while (0)
; #define PG8_LDA(dst, b, h) do { _Pragma("unroll") for (int m = 0; m < 4; ++m) _Pragma("unroll") for (int k = 0; k < 2; ++k) dst[m][k] = *(const PG8_LAS bf16x8*)(lds + PG8_SA(b, h) + aoff + m * 2048 + k * 1024); } while (0)
; #define PG8_LDB(dst, b, h) do { _Pragma("unroll") for (int n = 0; n < 2; ++n) _Pragma("unroll") for (int k = 0; k < 2; ++k) dst[n][k] = *(const PG8_LAS bf16x8*)(lds + PG8_SB(b, h) + boff + n * 2048 + k * 1024); } while (0)
; #define PG8_MMA(ai, bj, At, Bt) do { __builtin_amdgcn_s_setprio(1); _Pragma("unroll") for (int m = 0; m < 4; ++m) _Pragma("unroll") for (int n = 0; n < 2; ++n) _Pragma("unroll") for (int k = 0; k < 2; ++k) \
;         acc[ai][bj][m][n] = __builtin_amdgcn_mfma_f32_16x16x32_bf16(Bt[n][k], At[m][k], acc[ai][bj][m][n], 0, 0, 0); __builtin_amdgcn_s_setprio(0); } while (0)
; #define PG8_WAIT_V(n) asm volatile("s_waitcnt vmcnt(" #n ")" ::: "memory")
; #define PG8_WAIT_L(n) asm volatile("s_waitcnt lgkmcnt(" #n ")" ::: "memory")
; template <class Epi, class Sched, bool ALIGN_EPI = false, bool SP2 = false, bool GRP = false>
; __device__ __forceinline__ void gemm_phase(PG8_LAS unsigned char* lds, const Gemm g, const Sched& S, const Epi& E) {
;     ...
;             const bool last = (t == nt - 2);
;             const char* a1 = cA + (size_t)(t + 1) * kstep;
;             const char* a2 = last ? nA : cA + (size_t)(t + 2) * kstep; const char* b2 = last ? nB : cB + (size_t)(t + 2) * kstep;
;             const char* a3 = a2 + kstep; const char* b3 = b2 + kstep;
;             if (last && has_next) S.a_ready(nxt);
;             if constexpr (SP2) {
;             PG8_LDB(B0, 0, 0); PG8_LDB(B1, 0, 1); PG8_SCHED; PG8_LDA(At, 0, 0); PG8_STAGE(PG8_SA(1, 1), a1 + hstep, voffA);
;             PG8_WAIT_V(8); PG8_WAIT_L(0); PG8_BAR; PG8_MMA(0, 0, At, B0); PG8_MMA(0, 1, At, B1); PG8_BAR; PG8_SCHED;
;             PG8_LDA(At, 0, 1); PG8_STAGE(PG8_SB(0, 0), b2, voffB); PG8_STAGE(PG8_SB(0, 1), b2 + hstep, voffB); PG8_STAGE(PG8_SA(0, 0), a2, voffA);
;             PG8_WAIT_V(8); PG8_WAIT_L(0); PG8_BAR; PG8_MMA(1, 0, At, B0); PG8_MMA(1, 1, At, B1); PG8_BAR; PG8_SCHED;
.LBB0_298:
	s_add_i32 s30, s3, 2
	s_add_u32 s28, s26, 0x80
	s_addc_u32 s29, s27, 0
	s_add_i32 s48, 0, 0x10000
	s_cmp_eq_u32 s70, s3
	s_cselect_b32 s29, s7, s29
	s_cselect_b32 s28, s6, s28
	s_cselect_b32 s43, s23, s41
	s_cselect_b32 s42, s22, s40
	s_add_i32 s3, 0, 0x14000
	v_add_u32_e32 v156, s48, v141
	v_add_u32_e32 v172, s3, v141
	ds_read_b128 v[144:147], v156
	ds_read_b128 v[148:151], v156 offset:1024
	ds_read_b128 v[152:155], v156 offset:2048
	ds_read_b128 v[156:159], v156 offset:3072
	ds_read_b128 v[160:163], v172
	ds_read_b128 v[164:167], v172 offset:1024
	ds_read_b128 v[168:171], v172 offset:2048
	ds_read_b128 v[172:175], v172 offset:3072
	v_lshl_add_u64 v[200:201], s[26:27], 0, v[136:137]
	s_add_i32 m0, s60, 0xc000
	ds_read_b128 v[176:179], v143
	ds_read_b128 v[180:183], v143 offset:1024
	ds_read_b128 v[184:187], v143 offset:2048
	ds_read_b128 v[188:191], v143 offset:3072
	ds_read_b128 v[192:195], v143 offset:4096
	ds_read_b128 v[196:199], v143 offset:5120
	ds_read_b128 v[210:213], v143 offset:6144
	ds_read_b128 v[222:225], v143 offset:7168
	global_load_lds_dwordx4 v[200:201], off
	v_lshl_add_u64 v[200:201], s[26:27], 0, v[138:139]
	s_add_i32 m0, s60, 0xe000
	s_nop 0
	global_load_lds_dwordx4 v[200:201], off
	s_waitcnt vmcnt(8)
	s_waitcnt lgkmcnt(0)
	s_setprio 1
	s_barrier
	s_waitcnt lgkmcnt(0)
	v_mfma_f32_16x16x32_bf16 v[122:125], v[144:147], v[176:179], v[122:125]
	v_mfma_f32_16x16x32_bf16 v[126:129], v[152:155], v[176:179], v[126:129]
	v_mfma_f32_16x16x32_bf16 v[110:113], v[144:147], v[184:187], v[110:113]
	v_mfma_f32_16x16x32_bf16 v[106:109], v[152:155], v[184:187], v[106:109]
	v_mfma_f32_16x16x32_bf16 v[94:97], v[144:147], v[192:195], v[94:97]
	v_mfma_f32_16x16x32_bf16 v[90:93], v[152:155], v[192:195], v[90:93]
	v_mfma_f32_16x16x32_bf16 v[78:81], v[144:147], v[210:213], v[78:81]
	v_mfma_f32_16x16x32_bf16 v[74:77], v[152:155], v[210:213], v[74:77]
	v_mfma_f32_16x16x32_bf16 v[122:125], v[148:151], v[180:183], v[122:125]
	v_mfma_f32_16x16x32_bf16 v[126:129], v[156:159], v[180:183], v[126:129]
	v_mfma_f32_16x16x32_bf16 v[110:113], v[148:151], v[188:191], v[110:113]
	v_mfma_f32_16x16x32_bf16 v[106:109], v[156:159], v[188:191], v[106:109]
	v_mfma_f32_16x16x32_bf16 v[94:97], v[148:151], v[196:199], v[94:97]
	v_mfma_f32_16x16x32_bf16 v[90:93], v[156:159], v[196:199], v[90:93]
	v_mfma_f32_16x16x32_bf16 v[78:81], v[148:151], v[222:225], v[78:81]
	v_mfma_f32_16x16x32_bf16 v[74:77], v[156:159], v[222:225], v[74:77]
	s_setprio 0
	s_setprio 1
	v_mfma_f32_16x16x32_bf16 v[118:121], v[160:163], v[176:179], v[118:121]
	v_mfma_f32_16x16x32_bf16 v[114:117], v[168:171], v[176:179], v[114:117]
	v_mfma_f32_16x16x32_bf16 v[102:105], v[160:163], v[184:187], v[102:105]
	v_mfma_f32_16x16x32_bf16 v[98:101], v[168:171], v[184:187], v[98:101]
	v_mfma_f32_16x16x32_bf16 v[86:89], v[160:163], v[192:195], v[86:89]
	v_mfma_f32_16x16x32_bf16 v[82:85], v[168:171], v[192:195], v[82:85]
	v_mfma_f32_16x16x32_bf16 v[70:73], v[160:163], v[210:213], v[70:73]
	v_mfma_f32_16x16x32_bf16 v[66:69], v[168:171], v[210:213], v[66:69]
	v_mfma_f32_16x16x32_bf16 v[118:121], v[164:167], v[180:183], v[118:121]
	v_mfma_f32_16x16x32_bf16 v[114:117], v[172:175], v[180:183], v[114:117]
	v_mfma_f32_16x16x32_bf16 v[102:105], v[164:167], v[188:191], v[102:105]
	v_mfma_f32_16x16x32_bf16 v[98:101], v[172:175], v[188:191], v[98:101]
	v_mfma_f32_16x16x32_bf16 v[86:89], v[164:167], v[196:199], v[86:89]
	v_mfma_f32_16x16x32_bf16 v[82:85], v[172:175], v[196:199], v[82:85]
	v_mfma_f32_16x16x32_bf16 v[70:73], v[164:167], v[222:225], v[70:73]
	v_mfma_f32_16x16x32_bf16 v[66:69], v[172:175], v[222:225], v[66:69]
	s_setprio 0
	s_barrier
	s_add_i32 s48, s48, s39
	v_lshl_add_u64 v[200:201], s[42:43], 0, v[0:1]
	s_mov_b32 m0, s48
	ds_read_b128 v[176:179], v143 offset:16384
	ds_read_b128 v[180:183], v143 offset:17408
	ds_read_b128 v[184:187], v143 offset:18432
	ds_read_b128 v[188:191], v143 offset:19456
	ds_read_b128 v[192:195], v143 offset:20480
	ds_read_b128 v[196:199], v143 offset:21504
	ds_read_b128 v[210:213], v143 offset:22528
	ds_read_b128 v[222:225], v143 offset:23552
	global_load_lds_dwordx4 v[200:201], off
	s_add_i32 m0, s48, 0x2000
	v_lshl_add_u64 v[202:203], s[42:43], 0, v[130:131]
	s_add_u32 s42, s42, s12
	s_addc_u32 s43, s43, s13
	s_add_i32 s3, s3, s39
	global_load_lds_dwordx4 v[202:203], off
	v_lshl_add_u64 v[214:215], s[42:43], 0, v[0:1]
	s_mov_b32 m0, s3
	v_lshl_add_u64 v[218:219], s[42:43], 0, v[130:131]
	global_load_lds_dwordx4 v[214:215], off
	s_add_i32 m0, s3, 0x2000
	v_lshl_add_u64 v[220:221], s[28:29], 0, v[134:135]
	global_load_lds_dwordx4 v[218:219], off
	s_mov_b32 m0, s60
	v_lshl_add_u64 v[226:227], s[28:29], 0, v[132:133]
	global_load_lds_dwordx4 v[220:221], off
	s_mov_b32 m0, s61
	s_nop 0
	global_load_lds_dwordx4 v[226:227], off
	s_waitcnt vmcnt(8)
	s_waitcnt lgkmcnt(0)
	s_setprio 1
	s_barrier
; #define PG8_STAGE(bufoff, gbase, voff) do { _Pragma("unroll") for (int _i = 0; _i < 2; ++_i) \
;         __builtin_amdgcn_global_load_lds((const unsigned*)((const char*)(gbase) + (voff)[_i]), (PG8_LAS unsigned*)(lds + (bufoff) + ldsw + _i * 8192), 16, 0, 0); } while (0)
; #define PG8_LDA(dst, b, h) do { _Pragma("unroll") for (int m = 0; m < 4; ++m) _Pragma("unroll") for (int k = 0; k < 2; ++k) dst[m][k] = *(const PG8_LAS bf16x8*)(lds + PG8_SA(b, h) + aoff + m * 2048 + k * 1024); } while (0)
; #define PG8_LDB(dst, b, h) do { _Pragma("unroll") for (int n = 0; n < 2; ++n) _Pragma("unroll") for (int k = 0; k < 2; ++k) dst[n][k] = *(const PG8_LAS bf16x8*)(lds + PG8_SB(b, h) + boff + n * 2048 + k * 1024); } while (0)
; #define PG8_MMA(ai, bj, At, Bt) do { __builtin_amdgcn_s_setprio(1); _Pragma("unroll") for (int m = 0; m < 4; ++m) _Pragma("unroll") for (int n = 0; n < 2; ++n) _Pragma("unroll") for (int k = 0; k < 2; ++k) \
;         acc[ai][bj][m][n] = __builtin_amdgcn_mfma_f32_16x16x32_bf16(Bt[n][k], At[m][k], acc[ai][bj][m][n], 0, 0, 0); __builtin_amdgcn_s_setprio(0); } while (0)
; #define PG8_WAIT_V(n) asm volatile("s_waitcnt vmcnt(" #n ")" ::: "memory")
; #define PG8_WAIT_L(n) asm volatile("s_waitcnt lgkmcnt(" #n ")" ::: "memory")
; #define PG8_BAR __builtin_amdgcn_s_barrier()
; #define PG8_SCHED __builtin_amdgcn_sched_barrier(0)
; template <class Epi, class Sched, bool ALIGN_EPI = false, bool SP2 = false, bool GRP = false>
; __device__ __forceinline__ void gemm_phase(PG8_LAS unsigned char* lds, const Gemm g, const Sched& S, const Epi& E) {
;     ...
;             PG8_WAIT_V(8); PG8_WAIT_L(0); PG8_BAR; PG8_MMA(1, 0, At, B0); PG8_MMA(1, 1, At, B1); PG8_BAR; PG8_SCHED;
;             PG8_LDB(B0, 1, 0); PG8_LDB(B1, 1, 1); PG8_SCHED; PG8_LDA(At, 1, 0); PG8_STAGE(PG8_SA(0, 1), a2 + hstep, voffA);
;             PG8_WAIT_V(8); PG8_WAIT_L(0); PG8_BAR; PG8_MMA(0, 0, At, B0); PG8_MMA(0, 1, At, B1); PG8_BAR; PG8_SCHED;
	s_waitcnt lgkmcnt(0)
	v_mfma_f32_16x16x32_bf16 v[62:65], v[144:147], v[176:179], v[62:65]
	v_mfma_f32_16x16x32_bf16 v[58:61], v[152:155], v[176:179], v[58:61]
	v_mfma_f32_16x16x32_bf16 v[46:49], v[144:147], v[184:187], v[46:49]
	v_mfma_f32_16x16x32_bf16 v[42:45], v[152:155], v[184:187], v[42:45]
	v_mfma_f32_16x16x32_bf16 v[30:33], v[144:147], v[192:195], v[30:33]
	v_mfma_f32_16x16x32_bf16 v[26:29], v[152:155], v[192:195], v[26:29]
	v_mfma_f32_16x16x32_bf16 v[14:17], v[144:147], v[210:213], v[14:17]
	v_mfma_f32_16x16x32_bf16 v[10:13], v[152:155], v[210:213], v[10:13]
	v_mfma_f32_16x16x32_bf16 v[62:65], v[148:151], v[180:183], v[62:65]
	v_mfma_f32_16x16x32_bf16 v[58:61], v[156:159], v[180:183], v[58:61]
	v_mfma_f32_16x16x32_bf16 v[46:49], v[148:151], v[188:191], v[46:49]
	v_mfma_f32_16x16x32_bf16 v[42:45], v[156:159], v[188:191], v[42:45]
	v_mfma_f32_16x16x32_bf16 v[30:33], v[148:151], v[196:199], v[30:33]
	v_mfma_f32_16x16x32_bf16 v[26:29], v[156:159], v[196:199], v[26:29]
	v_mfma_f32_16x16x32_bf16 v[14:17], v[148:151], v[222:225], v[14:17]
	v_mfma_f32_16x16x32_bf16 v[10:13], v[156:159], v[222:225], v[10:13]
	s_setprio 0
	s_setprio 1
	v_mfma_f32_16x16x32_bf16 v[54:57], v[160:163], v[176:179], v[54:57]
	v_mfma_f32_16x16x32_bf16 v[50:53], v[168:171], v[176:179], v[50:53]
	v_mfma_f32_16x16x32_bf16 v[38:41], v[160:163], v[184:187], v[38:41]
	v_mfma_f32_16x16x32_bf16 v[34:37], v[168:171], v[184:187], v[34:37]
	v_mfma_f32_16x16x32_bf16 v[22:25], v[160:163], v[192:195], v[22:25]
	v_mfma_f32_16x16x32_bf16 v[18:21], v[168:171], v[192:195], v[18:21]
	v_mfma_f32_16x16x32_bf16 v[6:9], v[160:163], v[210:213], v[6:9]
	v_mfma_f32_16x16x32_bf16 v[2:5], v[168:171], v[210:213], v[2:5]
	v_mfma_f32_16x16x32_bf16 v[54:57], v[164:167], v[180:183], v[54:57]
	v_mfma_f32_16x16x32_bf16 v[50:53], v[172:175], v[180:183], v[50:53]
	v_mfma_f32_16x16x32_bf16 v[38:41], v[164:167], v[188:191], v[38:41]
	v_mfma_f32_16x16x32_bf16 v[34:37], v[172:175], v[188:191], v[34:37]
	v_mfma_f32_16x16x32_bf16 v[22:25], v[164:167], v[196:199], v[22:25]
	v_mfma_f32_16x16x32_bf16 v[18:21], v[172:175], v[196:199], v[18:21]
	v_mfma_f32_16x16x32_bf16 v[6:9], v[164:167], v[222:225], v[6:9]
	v_mfma_f32_16x16x32_bf16 v[2:5], v[172:175], v[222:225], v[2:5]
	s_setprio 0
	s_barrier
	s_add_i32 s3, 0, 0x18000
	s_add_i32 s42, 0, 0x1c000
	v_add_u32_e32 v156, s3, v141
	v_add_u32_e32 v172, s42, v141
	ds_read_b128 v[144:147], v156
	ds_read_b128 v[148:151], v156 offset:1024
	ds_read_b128 v[152:155], v156 offset:2048
	ds_read_b128 v[156:159], v156 offset:3072
	ds_read_b128 v[160:163], v172
	ds_read_b128 v[164:167], v172 offset:1024
	ds_read_b128 v[168:171], v172 offset:2048
	ds_read_b128 v[172:175], v172 offset:3072
	s_add_u32 s28, s28, s12
	s_addc_u32 s29, s29, s13
	s_mov_b32 m0, s62
	v_lshl_add_u64 v[228:229], s[28:29], 0, v[134:135]
	ds_read_b128 v[176:179], v143 offset:32768
	ds_read_b128 v[180:183], v143 offset:33792
	ds_read_b128 v[184:187], v143 offset:34816
	ds_read_b128 v[188:191], v143 offset:35840
	ds_read_b128 v[192:195], v143 offset:36864
	ds_read_b128 v[196:199], v143 offset:37888
	ds_read_b128 v[210:213], v143 offset:38912
	ds_read_b128 v[222:225], v143 offset:39936
	global_load_lds_dwordx4 v[228:229], off
	v_lshl_add_u64 v[228:229], s[28:29], 0, v[132:133]
	s_mov_b32 m0, s63
	s_nop 0
	global_load_lds_dwordx4 v[228:229], off
	s_waitcnt vmcnt(8)
	s_waitcnt lgkmcnt(0)
	s_setprio 1
	s_barrier
	s_waitcnt lgkmcnt(0)
	v_mfma_f32_16x16x32_bf16 v[122:125], v[144:147], v[176:179], v[122:125]
	v_mfma_f32_16x16x32_bf16 v[126:129], v[152:155], v[176:179], v[126:129]
	v_mfma_f32_16x16x32_bf16 v[110:113], v[144:147], v[184:187], v[110:113]
	v_mfma_f32_16x16x32_bf16 v[106:109], v[152:155], v[184:187], v[106:109]
	v_mfma_f32_16x16x32_bf16 v[94:97], v[144:147], v[192:195], v[94:97]
	v_mfma_f32_16x16x32_bf16 v[90:93], v[152:155], v[192:195], v[90:93]
	v_mfma_f32_16x16x32_bf16 v[78:81], v[144:147], v[210:213], v[78:81]
	v_mfma_f32_16x16x32_bf16 v[74:77], v[152:155], v[210:213], v[74:77]
	v_mfma_f32_16x16x32_bf16 v[122:125], v[148:151], v[180:183], v[122:125]
	v_mfma_f32_16x16x32_bf16 v[126:129], v[156:159], v[180:183], v[126:129]
	v_mfma_f32_16x16x32_bf16 v[110:113], v[148:151], v[188:191], v[110:113]
	v_mfma_f32_16x16x32_bf16 v[106:109], v[156:159], v[188:191], v[106:109]
	v_mfma_f32_16x16x32_bf16 v[94:97], v[148:151], v[196:199], v[94:97]
	v_mfma_f32_16x16x32_bf16 v[90:93], v[156:159], v[196:199], v[90:93]
	v_mfma_f32_16x16x32_bf16 v[78:81], v[148:151], v[222:225], v[78:81]
	v_mfma_f32_16x16x32_bf16 v[74:77], v[156:159], v[222:225], v[74:77]
	s_setprio 0
	s_setprio 1
	v_mfma_f32_16x16x32_bf16 v[118:121], v[160:163], v[176:179], v[118:121]
	v_mfma_f32_16x16x32_bf16 v[114:117], v[168:171], v[176:179], v[114:117]
	v_mfma_f32_16x16x32_bf16 v[102:105], v[160:163], v[184:187], v[102:105]
	v_mfma_f32_16x16x32_bf16 v[98:101], v[168:171], v[184:187], v[98:101]
	v_mfma_f32_16x16x32_bf16 v[86:89], v[160:163], v[192:195], v[86:89]
	v_mfma_f32_16x16x32_bf16 v[82:85], v[168:171], v[192:195], v[82:85]
	v_mfma_f32_16x16x32_bf16 v[70:73], v[160:163], v[210:213], v[70:73]
	v_mfma_f32_16x16x32_bf16 v[66:69], v[168:171], v[210:213], v[66:69]
	v_mfma_f32_16x16x32_bf16 v[118:121], v[164:167], v[180:183], v[118:121]
	v_mfma_f32_16x16x32_bf16 v[114:117], v[172:175], v[180:183], v[114:117]
	v_mfma_f32_16x16x32_bf16 v[102:105], v[164:167], v[188:191], v[102:105]
	v_mfma_f32_16x16x32_bf16 v[98:101], v[172:175], v[188:191], v[98:101]
	v_mfma_f32_16x16x32_bf16 v[86:89], v[164:167], v[196:199], v[86:89]
	v_mfma_f32_16x16x32_bf16 v[82:85], v[172:175], v[196:199], v[82:85]
	v_mfma_f32_16x16x32_bf16 v[70:73], v[164:167], v[222:225], v[70:73]
	v_mfma_f32_16x16x32_bf16 v[66:69], v[172:175], v[222:225], v[66:69]
	s_setprio 0
	s_barrier
; #define PG8_STAGE(bufoff, gbase, voff) do { _Pragma("unroll") for (int _i = 0; _i < 2; ++_i) \
;         __builtin_amdgcn_global_load_lds((const unsigned*)((const char*)(gbase) + (voff)[_i]), (PG8_LAS unsigned*)(lds + (bufoff) + ldsw + _i * 8192), 16, 0, 0); } while (0)
; #define PG8_LDA(dst, b, h) do { _Pragma("unroll") for (int m = 0; m < 4; ++m) _Pragma("unroll") for (int k = 0; k < 2; ++k) dst[m][k] = *(const PG8_LAS bf16x8*)(lds + PG8_SA(b, h) + aoff + m * 2048 + k * 1024); } while (0)
; #define PG8_MMA(ai, bj, At, Bt) do { __builtin_amdgcn_s_setprio(1); _Pragma("unroll") for (int m = 0; m < 4; ++m) _Pragma("unroll") for (int n = 0; n < 2; ++n) _Pragma("unroll") for (int k = 0; k < 2; ++k) \
;         acc[ai][bj][m][n] = __builtin_amdgcn_mfma_f32_16x16x32_bf16(Bt[n][k], At[m][k], acc[ai][bj][m][n], 0, 0, 0); __builtin_amdgcn_s_setprio(0); } while (0)
; #define PG8_WAIT_V(n) asm volatile("s_waitcnt vmcnt(" #n ")" ::: "memory")
; #define PG8_WAIT_L(n) asm volatile("s_waitcnt lgkmcnt(" #n ")" ::: "memory")
; #define PG8_BAR __builtin_amdgcn_s_barrier()
; #define PG8_SCHED __builtin_amdgcn_sched_barrier(0)
; template <class Epi, class Sched, bool ALIGN_EPI = false, bool SP2 = false, bool GRP = false>
; __device__ __forceinline__ void gemm_phase(PG8_LAS unsigned char* lds, const Gemm g, const Sched& S, const Epi& E) {
;     ...
;             PG8_LDA(At, 1, 1); PG8_STAGE(PG8_SB(1, 0), b3, voffB); PG8_STAGE(PG8_SB(1, 1), b3 + hstep, voffB); PG8_STAGE(PG8_SA(1, 0), a3, voffA);
;             PG8_WAIT_V(8); PG8_WAIT_L(0); PG8_BAR; PG8_MMA(1, 0, At, B0); PG8_MMA(1, 1, At, B1); PG8_BAR; PG8_SCHED;
	s_add_i32 s3, s3, s39
	v_lshl_add_u64 v[200:201], v[200:201], 0, s[36:37]
	s_mov_b32 m0, s3
	ds_read_b128 v[176:179], v143 offset:49152
	ds_read_b128 v[180:183], v143 offset:50176
	ds_read_b128 v[184:187], v143 offset:51200
	ds_read_b128 v[188:191], v143 offset:52224
	ds_read_b128 v[192:195], v143 offset:53248
	ds_read_b128 v[196:199], v143 offset:54272
	ds_read_b128 v[210:213], v143 offset:55296
	ds_read_b128 v[222:225], v143 offset:56320
	global_load_lds_dwordx4 v[200:201], off
	v_lshl_add_u64 v[200:201], v[202:203], 0, s[36:37]
	s_add_i32 m0, s3, 0x2000
	s_add_i32 s3, s42, s39
	global_load_lds_dwordx4 v[200:201], off
	v_lshl_add_u64 v[200:201], v[214:215], 0, s[36:37]
	s_mov_b32 m0, s3
	s_nop 0
	global_load_lds_dwordx4 v[200:201], off
	v_lshl_add_u64 v[200:201], v[218:219], 0, s[36:37]
	s_add_i32 m0, s3, 0x2000
	s_nop 0
	global_load_lds_dwordx4 v[200:201], off
	v_lshl_add_u64 v[200:201], v[220:221], 0, s[36:37]
	s_mov_b32 m0, s64
	s_nop 0
	global_load_lds_dwordx4 v[200:201], off
	v_lshl_add_u64 v[200:201], v[226:227], 0, s[36:37]
	s_mov_b32 m0, s65
	s_nop 0
	global_load_lds_dwordx4 v[200:201], off
	s_waitcnt vmcnt(8)
	s_waitcnt lgkmcnt(0)
	s_setprio 1
	s_barrier
	s_waitcnt lgkmcnt(0)
	v_mfma_f32_16x16x32_bf16 v[62:65], v[144:147], v[176:179], v[62:65]
	v_mfma_f32_16x16x32_bf16 v[58:61], v[152:155], v[176:179], v[58:61]
	v_mfma_f32_16x16x32_bf16 v[46:49], v[144:147], v[184:187], v[46:49]
	v_mfma_f32_16x16x32_bf16 v[42:45], v[152:155], v[184:187], v[42:45]
	v_mfma_f32_16x16x32_bf16 v[30:33], v[144:147], v[192:195], v[30:33]
	v_mfma_f32_16x16x32_bf16 v[26:29], v[152:155], v[192:195], v[26:29]
	v_mfma_f32_16x16x32_bf16 v[14:17], v[144:147], v[210:213], v[14:17]
	v_mfma_f32_16x16x32_bf16 v[10:13], v[152:155], v[210:213], v[10:13]
	v_mfma_f32_16x16x32_bf16 v[62:65], v[148:151], v[180:183], v[62:65]
	v_mfma_f32_16x16x32_bf16 v[58:61], v[156:159], v[180:183], v[58:61]
	v_mfma_f32_16x16x32_bf16 v[46:49], v[148:151], v[188:191], v[46:49]
	v_mfma_f32_16x16x32_bf16 v[42:45], v[156:159], v[188:191], v[42:45]
	v_mfma_f32_16x16x32_bf16 v[30:33], v[148:151], v[196:199], v[30:33]
	v_mfma_f32_16x16x32_bf16 v[26:29], v[156:159], v[196:199], v[26:29]
	v_mfma_f32_16x16x32_bf16 v[14:17], v[148:151], v[222:225], v[14:17]
	v_mfma_f32_16x16x32_bf16 v[10:13], v[156:159], v[222:225], v[10:13]
	s_setprio 0
	s_setprio 1
	v_mfma_f32_16x16x32_bf16 v[54:57], v[160:163], v[176:179], v[54:57]
	v_mfma_f32_16x16x32_bf16 v[50:53], v[168:171], v[176:179], v[50:53]
	v_mfma_f32_16x16x32_bf16 v[38:41], v[160:163], v[184:187], v[38:41]
	v_mfma_f32_16x16x32_bf16 v[34:37], v[168:171], v[184:187], v[34:37]
	v_mfma_f32_16x16x32_bf16 v[22:25], v[160:163], v[192:195], v[22:25]
	v_mfma_f32_16x16x32_bf16 v[18:21], v[168:171], v[192:195], v[18:21]
	v_mfma_f32_16x16x32_bf16 v[6:9], v[160:163], v[210:213], v[6:9]
	v_mfma_f32_16x16x32_bf16 v[2:5], v[168:171], v[210:213], v[2:5]
	v_mfma_f32_16x16x32_bf16 v[54:57], v[164:167], v[180:183], v[54:57]
	v_mfma_f32_16x16x32_bf16 v[50:53], v[172:175], v[180:183], v[50:53]
	v_mfma_f32_16x16x32_bf16 v[38:41], v[164:167], v[188:191], v[38:41]
	v_mfma_f32_16x16x32_bf16 v[34:37], v[172:175], v[188:191], v[34:37]
	v_mfma_f32_16x16x32_bf16 v[22:25], v[164:167], v[196:199], v[22:25]
	v_mfma_f32_16x16x32_bf16 v[18:21], v[172:175], v[196:199], v[18:21]
	v_mfma_f32_16x16x32_bf16 v[6:9], v[164:167], v[222:225], v[6:9]
	v_mfma_f32_16x16x32_bf16 v[2:5], v[172:175], v[222:225], v[2:5]
	s_setprio 0
	s_barrier
	s_add_u32 s26, s26, 0x100
	s_addc_u32 s27, s27, 0
	s_add_u32 s40, s40, 0x100
	s_addc_u32 s41, s41, 0
	s_cmp_ge_i32 s30, s67
	s_mov_b32 s3, s30
	s_cbranch_scc0 .LBB0_298

; #define PG8_STAGE(bufoff, gbase, voff) do { _Pragma("unroll") for (int _i = 0; _i < 2; ++_i) \
;         __builtin_amdgcn_global_load_lds((const unsigned*)((const char*)(gbase) + (voff)[_i]), (PG8_LAS unsigned*)(lds + (bufoff) + ldsw + _i * 8192), 16, 0, 0); } while (0)
; #define PG8_LDA(dst, b, h) do { _Pragma("unroll") for (int m = 0; m < 4; ++m) _Pragma("unroll") for (int k = 0; k < 2; ++k) dst[m][k] = *(const PG8_LAS bf16x8*)(lds + PG8_SA(b, h) + aoff + m * 2048 + k * 1024); } while (0)
; #define PG8_LDB(dst, b, h) do { _Pragma("unroll") for (int n = 0; n < 2; ++n) _Pragma("unroll") for (int k = 0; k < 2; ++k) dst[n][k] = *(const PG8_LAS bf16x8*)(lds + PG8_SB(b, h) + boff + n * 2048 + k * 1024); } while (0)
; #define PG8_MMA(ai, bj, At, Bt) do { __builtin_amdgcn_s_setprio(1); _Pragma("unroll") for (int m = 0; m < 4; ++m) _Pragma("unroll") for (int n = 0; n < 2; ++n) _Pragma("unroll") for (int k = 0; k < 2; ++k) \
;         acc[ai][bj][m][n] = __builtin_amdgcn_mfma_f32_16x16x32_bf16(Bt[n][k], At[m][k], acc[ai][bj][m][n], 0, 0, 0); __builtin_amdgcn_s_setprio(0); } while (0)
; #define PG8_WAIT_V(n) asm volatile("s_waitcnt vmcnt(" #n ")" ::: "memory")
; #define PG8_WAIT_L(n) asm volatile("s_waitcnt lgkmcnt(" #n ")" ::: "memory")
; template <class Epi, class Sched, bool ALIGN_EPI = false, bool SP2 = false, bool GRP = false>
; __device__ __forceinline__ void gemm_phase(PG8_LAS unsigned char* lds, const Gemm g, const Sched& S, const Epi& E) {
;     ...
;             const bool last = (t == nt - 2);
;             const char* a1 = cA + (size_t)(t + 1) * kstep;
;             const char* a2 = last ? nA : cA + (size_t)(t + 2) * kstep; const char* b2 = last ? nB : cB + (size_t)(t + 2) * kstep;
;             const char* a3 = a2 + kstep; const char* b3 = b2 + kstep;
;             if (last && has_next) S.a_ready(nxt);
;             if constexpr (SP2) {
;             PG8_LDB(B0, 0, 0); PG8_LDB(B1, 0, 1); PG8_SCHED; PG8_LDA(At, 0, 0); PG8_STAGE(PG8_SA(1, 1), a1 + hstep, voffA);
;             PG8_WAIT_V(8); PG8_WAIT_L(0); PG8_BAR; PG8_MMA(0, 0, At, B0); PG8_MMA(0, 1, At, B1); PG8_BAR; PG8_SCHED;
;             PG8_LDA(At, 0, 1); PG8_STAGE(PG8_SB(0, 0), b2, voffB); PG8_STAGE(PG8_SB(0, 1), b2 + hstep, voffB); PG8_STAGE(PG8_SA(0, 0), a2, voffA);
;             PG8_WAIT_V(8); PG8_WAIT_L(0); PG8_BAR; PG8_MMA(1, 0, At, B0); PG8_MMA(1, 1, At, B1); PG8_BAR; PG8_SCHED;
.LBB0_410:
	s_add_i32 s30, s3, 2
	s_add_u32 s26, s22, 0x80
	s_addc_u32 s27, s23, 0
	s_add_i32 s48, 0, 0x10000
	s_cmp_eq_u32 s71, s3
	s_cselect_b32 s27, s7, s27
	s_cselect_b32 s26, s6, s26
	s_cselect_b32 s43, s21, s41
	s_cselect_b32 s42, s20, s40
	s_add_i32 s3, 0, 0x14000
	v_add_u32_e32 v156, s48, v141
	v_add_u32_e32 v172, s3, v141
	ds_read_b128 v[144:147], v156
	ds_read_b128 v[148:151], v156 offset:1024
	ds_read_b128 v[152:155], v156 offset:2048
	ds_read_b128 v[156:159], v156 offset:3072
	ds_read_b128 v[160:163], v172
	ds_read_b128 v[164:167], v172 offset:1024
	ds_read_b128 v[168:171], v172 offset:2048
	ds_read_b128 v[172:175], v172 offset:3072
	v_lshl_add_u64 v[200:201], s[22:23], 0, v[136:137]
	s_add_i32 m0, s39, 0xc000
	ds_read_b128 v[176:179], v143
	ds_read_b128 v[180:183], v143 offset:1024
	ds_read_b128 v[184:187], v143 offset:2048
	ds_read_b128 v[188:191], v143 offset:3072
	ds_read_b128 v[192:195], v143 offset:4096
	ds_read_b128 v[196:199], v143 offset:5120
	ds_read_b128 v[210:213], v143 offset:6144
	ds_read_b128 v[222:225], v143 offset:7168
	global_load_lds_dwordx4 v[200:201], off
	v_lshl_add_u64 v[200:201], s[22:23], 0, v[138:139]
	s_add_i32 m0, s39, 0xe000
	s_nop 0
	global_load_lds_dwordx4 v[200:201], off
	s_waitcnt vmcnt(8)
	s_waitcnt lgkmcnt(0)
	s_setprio 1
	s_barrier
	s_waitcnt lgkmcnt(0)
	v_mfma_f32_16x16x32_bf16 v[122:125], v[144:147], v[176:179], v[122:125]
	v_mfma_f32_16x16x32_bf16 v[126:129], v[152:155], v[176:179], v[126:129]
	v_mfma_f32_16x16x32_bf16 v[110:113], v[144:147], v[184:187], v[110:113]
	v_mfma_f32_16x16x32_bf16 v[106:109], v[152:155], v[184:187], v[106:109]
	v_mfma_f32_16x16x32_bf16 v[94:97], v[144:147], v[192:195], v[94:97]
	v_mfma_f32_16x16x32_bf16 v[90:93], v[152:155], v[192:195], v[90:93]
	v_mfma_f32_16x16x32_bf16 v[78:81], v[144:147], v[210:213], v[78:81]
	v_mfma_f32_16x16x32_bf16 v[74:77], v[152:155], v[210:213], v[74:77]
	v_mfma_f32_16x16x32_bf16 v[122:125], v[148:151], v[180:183], v[122:125]
	v_mfma_f32_16x16x32_bf16 v[126:129], v[156:159], v[180:183], v[126:129]
	v_mfma_f32_16x16x32_bf16 v[110:113], v[148:151], v[188:191], v[110:113]
	v_mfma_f32_16x16x32_bf16 v[106:109], v[156:159], v[188:191], v[106:109]
	v_mfma_f32_16x16x32_bf16 v[94:97], v[148:151], v[196:199], v[94:97]
	v_mfma_f32_16x16x32_bf16 v[90:93], v[156:159], v[196:199], v[90:93]
	v_mfma_f32_16x16x32_bf16 v[78:81], v[148:151], v[222:225], v[78:81]
	v_mfma_f32_16x16x32_bf16 v[74:77], v[156:159], v[222:225], v[74:77]
	s_setprio 0
	s_setprio 1
	v_mfma_f32_16x16x32_bf16 v[118:121], v[160:163], v[176:179], v[118:121]
	v_mfma_f32_16x16x32_bf16 v[114:117], v[168:171], v[176:179], v[114:117]
	v_mfma_f32_16x16x32_bf16 v[102:105], v[160:163], v[184:187], v[102:105]
	v_mfma_f32_16x16x32_bf16 v[98:101], v[168:171], v[184:187], v[98:101]
	v_mfma_f32_16x16x32_bf16 v[86:89], v[160:163], v[192:195], v[86:89]
	v_mfma_f32_16x16x32_bf16 v[82:85], v[168:171], v[192:195], v[82:85]
	v_mfma_f32_16x16x32_bf16 v[70:73], v[160:163], v[210:213], v[70:73]
	v_mfma_f32_16x16x32_bf16 v[66:69], v[168:171], v[210:213], v[66:69]
	v_mfma_f32_16x16x32_bf16 v[118:121], v[164:167], v[180:183], v[118:121]
	v_mfma_f32_16x16x32_bf16 v[114:117], v[172:175], v[180:183], v[114:117]
	v_mfma_f32_16x16x32_bf16 v[102:105], v[164:167], v[188:191], v[102:105]
	v_mfma_f32_16x16x32_bf16 v[98:101], v[172:175], v[188:191], v[98:101]
	v_mfma_f32_16x16x32_bf16 v[86:89], v[164:167], v[196:199], v[86:89]
	v_mfma_f32_16x16x32_bf16 v[82:85], v[172:175], v[196:199], v[82:85]
	v_mfma_f32_16x16x32_bf16 v[70:73], v[164:167], v[222:225], v[70:73]
	v_mfma_f32_16x16x32_bf16 v[66:69], v[172:175], v[222:225], v[66:69]
	s_setprio 0
	s_barrier
	s_add_i32 s48, s48, s38
	v_lshl_add_u64 v[200:201], s[42:43], 0, v[0:1]
	s_mov_b32 m0, s48
	ds_read_b128 v[176:179], v143 offset:16384
	ds_read_b128 v[180:183], v143 offset:17408
	ds_read_b128 v[184:187], v143 offset:18432
	ds_read_b128 v[188:191], v143 offset:19456
	ds_read_b128 v[192:195], v143 offset:20480
	ds_read_b128 v[196:199], v143 offset:21504
	ds_read_b128 v[210:213], v143 offset:22528
	ds_read_b128 v[222:225], v143 offset:23552
	global_load_lds_dwordx4 v[200:201], off
	s_add_i32 m0, s48, 0x2000
	v_lshl_add_u64 v[202:203], s[42:43], 0, v[134:135]
	s_add_u32 s42, s42, s8
	s_addc_u32 s43, s43, s9
	s_add_i32 s3, s3, s38
	global_load_lds_dwordx4 v[202:203], off
	v_lshl_add_u64 v[214:215], s[42:43], 0, v[0:1]
	s_mov_b32 m0, s3
	v_lshl_add_u64 v[218:219], s[42:43], 0, v[134:135]
	global_load_lds_dwordx4 v[214:215], off
	s_add_i32 m0, s3, 0x2000
	v_lshl_add_u64 v[220:221], s[26:27], 0, v[130:131]
	global_load_lds_dwordx4 v[218:219], off
	s_mov_b32 m0, s39
	v_lshl_add_u64 v[226:227], s[26:27], 0, v[132:133]
	global_load_lds_dwordx4 v[220:221], off
	s_mov_b32 m0, s59
	s_nop 0
	global_load_lds_dwordx4 v[226:227], off
	s_waitcnt vmcnt(8)
	s_waitcnt lgkmcnt(0)
	s_setprio 1
	s_barrier
; #define PG8_STAGE(bufoff, gbase, voff) do { _Pragma("unroll") for (int _i = 0; _i < 2; ++_i) \
;         __builtin_amdgcn_global_load_lds((const unsigned*)((const char*)(gbase) + (voff)[_i]), (PG8_LAS unsigned*)(lds + (bufoff) + ldsw + _i * 8192), 16, 0, 0); } while (0)
; #define PG8_LDA(dst, b, h) do { _Pragma("unroll") for (int m = 0; m < 4; ++m) _Pragma("unroll") for (int k = 0; k < 2; ++k) dst[m][k] = *(const PG8_LAS bf16x8*)(lds + PG8_SA(b, h) + aoff + m * 2048 + k * 1024); } while (0)
; #define PG8_LDB(dst, b, h) do { _Pragma("unroll") for (int n = 0; n < 2; ++n) _Pragma("unroll") for (int k = 0; k < 2; ++k) dst[n][k] = *(const PG8_LAS bf16x8*)(lds + PG8_SB(b, h) + boff + n * 2048 + k * 1024); } while (0)
; #define PG8_MMA(ai, bj, At, Bt) do { __builtin_amdgcn_s_setprio(1); _Pragma("unroll") for (int m = 0; m < 4; ++m) _Pragma("unroll") for (int n = 0; n < 2; ++n) _Pragma("unroll") for (int k = 0; k < 2; ++k) \
;         acc[ai][bj][m][n] = __builtin_amdgcn_mfma_f32_16x16x32_bf16(Bt[n][k], At[m][k], acc[ai][bj][m][n], 0, 0, 0); __builtin_amdgcn_s_setprio(0); } while (0)
; #define PG8_WAIT_V(n) asm volatile("s_waitcnt vmcnt(" #n ")" ::: "memory")
; #define PG8_WAIT_L(n) asm volatile("s_waitcnt lgkmcnt(" #n ")" ::: "memory")
; #define PG8_BAR __builtin_amdgcn_s_barrier()
; #define PG8_SCHED __builtin_amdgcn_sched_barrier(0)
; template <class Epi, class Sched, bool ALIGN_EPI = false, bool SP2 = false, bool GRP = false>
; __device__ __forceinline__ void gemm_phase(PG8_LAS unsigned char* lds, const Gemm g, const Sched& S, const Epi& E) {
;     ...
;             PG8_WAIT_V(8); PG8_WAIT_L(0); PG8_BAR; PG8_MMA(1, 0, At, B0); PG8_MMA(1, 1, At, B1); PG8_BAR; PG8_SCHED;
;             PG8_LDB(B0, 1, 0); PG8_LDB(B1, 1, 1); PG8_SCHED; PG8_LDA(At, 1, 0); PG8_STAGE(PG8_SA(0, 1), a2 + hstep, voffA);
;             PG8_WAIT_V(8); PG8_WAIT_L(0); PG8_BAR; PG8_MMA(0, 0, At, B0); PG8_MMA(0, 1, At, B1); PG8_BAR; PG8_SCHED;
	s_waitcnt lgkmcnt(0)
	v_mfma_f32_16x16x32_bf16 v[62:65], v[144:147], v[176:179], v[62:65]
	v_mfma_f32_16x16x32_bf16 v[58:61], v[152:155], v[176:179], v[58:61]
	v_mfma_f32_16x16x32_bf16 v[46:49], v[144:147], v[184:187], v[46:49]
	v_mfma_f32_16x16x32_bf16 v[42:45], v[152:155], v[184:187], v[42:45]
	v_mfma_f32_16x16x32_bf16 v[30:33], v[144:147], v[192:195], v[30:33]
	v_mfma_f32_16x16x32_bf16 v[26:29], v[152:155], v[192:195], v[26:29]
	v_mfma_f32_16x16x32_bf16 v[14:17], v[144:147], v[210:213], v[14:17]
	v_mfma_f32_16x16x32_bf16 v[10:13], v[152:155], v[210:213], v[10:13]
	v_mfma_f32_16x16x32_bf16 v[62:65], v[148:151], v[180:183], v[62:65]
	v_mfma_f32_16x16x32_bf16 v[58:61], v[156:159], v[180:183], v[58:61]
	v_mfma_f32_16x16x32_bf16 v[46:49], v[148:151], v[188:191], v[46:49]
	v_mfma_f32_16x16x32_bf16 v[42:45], v[156:159], v[188:191], v[42:45]
	v_mfma_f32_16x16x32_bf16 v[30:33], v[148:151], v[196:199], v[30:33]
	v_mfma_f32_16x16x32_bf16 v[26:29], v[156:159], v[196:199], v[26:29]
	v_mfma_f32_16x16x32_bf16 v[14:17], v[148:151], v[222:225], v[14:17]
	v_mfma_f32_16x16x32_bf16 v[10:13], v[156:159], v[222:225], v[10:13]
	s_setprio 0
	s_setprio 1
	v_mfma_f32_16x16x32_bf16 v[54:57], v[160:163], v[176:179], v[54:57]
	v_mfma_f32_16x16x32_bf16 v[50:53], v[168:171], v[176:179], v[50:53]
	v_mfma_f32_16x16x32_bf16 v[38:41], v[160:163], v[184:187], v[38:41]
	v_mfma_f32_16x16x32_bf16 v[34:37], v[168:171], v[184:187], v[34:37]
	v_mfma_f32_16x16x32_bf16 v[22:25], v[160:163], v[192:195], v[22:25]
	v_mfma_f32_16x16x32_bf16 v[18:21], v[168:171], v[192:195], v[18:21]
	v_mfma_f32_16x16x32_bf16 v[6:9], v[160:163], v[210:213], v[6:9]
	v_mfma_f32_16x16x32_bf16 v[2:5], v[168:171], v[210:213], v[2:5]
	v_mfma_f32_16x16x32_bf16 v[54:57], v[164:167], v[180:183], v[54:57]
	v_mfma_f32_16x16x32_bf16 v[50:53], v[172:175], v[180:183], v[50:53]
	v_mfma_f32_16x16x32_bf16 v[38:41], v[164:167], v[188:191], v[38:41]
	v_mfma_f32_16x16x32_bf16 v[34:37], v[172:175], v[188:191], v[34:37]
	v_mfma_f32_16x16x32_bf16 v[22:25], v[164:167], v[196:199], v[22:25]
	v_mfma_f32_16x16x32_bf16 v[18:21], v[172:175], v[196:199], v[18:21]
	v_mfma_f32_16x16x32_bf16 v[6:9], v[164:167], v[222:225], v[6:9]
	v_mfma_f32_16x16x32_bf16 v[2:5], v[172:175], v[222:225], v[2:5]
	s_setprio 0
	s_barrier
	s_add_i32 s3, 0, 0x18000
	s_add_i32 s42, 0, 0x1c000
	v_add_u32_e32 v156, s3, v141
	v_add_u32_e32 v172, s42, v141
	ds_read_b128 v[144:147], v156
	ds_read_b128 v[148:151], v156 offset:1024
	ds_read_b128 v[152:155], v156 offset:2048
	ds_read_b128 v[156:159], v156 offset:3072
	ds_read_b128 v[160:163], v172
	ds_read_b128 v[164:167], v172 offset:1024
	ds_read_b128 v[168:171], v172 offset:2048
	ds_read_b128 v[172:175], v172 offset:3072
	s_add_u32 s26, s26, s8
	s_addc_u32 s27, s27, s9
	s_mov_b32 m0, s60
	v_lshl_add_u64 v[228:229], s[26:27], 0, v[130:131]
	ds_read_b128 v[176:179], v143 offset:32768
	ds_read_b128 v[180:183], v143 offset:33792
	ds_read_b128 v[184:187], v143 offset:34816
	ds_read_b128 v[188:191], v143 offset:35840
	ds_read_b128 v[192:195], v143 offset:36864
	ds_read_b128 v[196:199], v143 offset:37888
	ds_read_b128 v[210:213], v143 offset:38912
	ds_read_b128 v[222:225], v143 offset:39936
	global_load_lds_dwordx4 v[228:229], off
	v_lshl_add_u64 v[228:229], s[26:27], 0, v[132:133]
	s_mov_b32 m0, s61
	s_nop 0
	global_load_lds_dwordx4 v[228:229], off
	s_waitcnt vmcnt(8)
	s_waitcnt lgkmcnt(0)
	s_setprio 1
	s_barrier
	s_waitcnt lgkmcnt(0)
	v_mfma_f32_16x16x32_bf16 v[122:125], v[144:147], v[176:179], v[122:125]
	v_mfma_f32_16x16x32_bf16 v[126:129], v[152:155], v[176:179], v[126:129]
	v_mfma_f32_16x16x32_bf16 v[110:113], v[144:147], v[184:187], v[110:113]
	v_mfma_f32_16x16x32_bf16 v[106:109], v[152:155], v[184:187], v[106:109]
	v_mfma_f32_16x16x32_bf16 v[94:97], v[144:147], v[192:195], v[94:97]
	v_mfma_f32_16x16x32_bf16 v[90:93], v[152:155], v[192:195], v[90:93]
	v_mfma_f32_16x16x32_bf16 v[78:81], v[144:147], v[210:213], v[78:81]
	v_mfma_f32_16x16x32_bf16 v[74:77], v[152:155], v[210:213], v[74:77]
	v_mfma_f32_16x16x32_bf16 v[122:125], v[148:151], v[180:183], v[122:125]
	v_mfma_f32_16x16x32_bf16 v[126:129], v[156:159], v[180:183], v[126:129]
	v_mfma_f32_16x16x32_bf16 v[110:113], v[148:151], v[188:191], v[110:113]
	v_mfma_f32_16x16x32_bf16 v[106:109], v[156:159], v[188:191], v[106:109]
	v_mfma_f32_16x16x32_bf16 v[94:97], v[148:151], v[196:199], v[94:97]
	v_mfma_f32_16x16x32_bf16 v[90:93], v[156:159], v[196:199], v[90:93]
	v_mfma_f32_16x16x32_bf16 v[78:81], v[148:151], v[222:225], v[78:81]
	v_mfma_f32_16x16x32_bf16 v[74:77], v[156:159], v[222:225], v[74:77]
	s_setprio 0
	s_setprio 1
	v_mfma_f32_16x16x32_bf16 v[118:121], v[160:163], v[176:179], v[118:121]
	v_mfma_f32_16x16x32_bf16 v[114:117], v[168:171], v[176:179], v[114:117]
	v_mfma_f32_16x16x32_bf16 v[102:105], v[160:163], v[184:187], v[102:105]
	v_mfma_f32_16x16x32_bf16 v[98:101], v[168:171], v[184:187], v[98:101]
	v_mfma_f32_16x16x32_bf16 v[86:89], v[160:163], v[192:195], v[86:89]
	v_mfma_f32_16x16x32_bf16 v[82:85], v[168:171], v[192:195], v[82:85]
	v_mfma_f32_16x16x32_bf16 v[70:73], v[160:163], v[210:213], v[70:73]
	v_mfma_f32_16x16x32_bf16 v[66:69], v[168:171], v[210:213], v[66:69]
	v_mfma_f32_16x16x32_bf16 v[118:121], v[164:167], v[180:183], v[118:121]
	v_mfma_f32_16x16x32_bf16 v[114:117], v[172:175], v[180:183], v[114:117]
	v_mfma_f32_16x16x32_bf16 v[102:105], v[164:167], v[188:191], v[102:105]
	v_mfma_f32_16x16x32_bf16 v[98:101], v[172:175], v[188:191], v[98:101]
	v_mfma_f32_16x16x32_bf16 v[86:89], v[164:167], v[196:199], v[86:89]
	v_mfma_f32_16x16x32_bf16 v[82:85], v[172:175], v[196:199], v[82:85]
	v_mfma_f32_16x16x32_bf16 v[70:73], v[164:167], v[222:225], v[70:73]
	v_mfma_f32_16x16x32_bf16 v[66:69], v[172:175], v[222:225], v[66:69]
	s_setprio 0
	s_barrier
; #define PG8_STAGE(bufoff, gbase, voff) do { _Pragma("unroll") for (int _i = 0; _i < 2; ++_i) \
;         __builtin_amdgcn_global_load_lds((const unsigned*)((const char*)(gbase) + (voff)[_i]), (PG8_LAS unsigned*)(lds + (bufoff) + ldsw + _i * 8192), 16, 0, 0); } while (0)
; #define PG8_LDA(dst, b, h) do { _Pragma("unroll") for (int m = 0; m < 4; ++m) _Pragma("unroll") for (int k = 0; k < 2; ++k) dst[m][k] = *(const PG8_LAS bf16x8*)(lds + PG8_SA(b, h) + aoff + m * 2048 + k * 1024); } while (0)
; #define PG8_MMA(ai, bj, At, Bt) do { __builtin_amdgcn_s_setprio(1); _Pragma("unroll") for (int m = 0; m < 4; ++m) _Pragma("unroll") for (int n = 0; n < 2; ++n) _Pragma("unroll") for (int k = 0; k < 2; ++k) \
;         acc[ai][bj][m][n] = __builtin_amdgcn_mfma_f32_16x16x32_bf16(Bt[n][k], At[m][k], acc[ai][bj][m][n], 0, 0, 0); __builtin_amdgcn_s_setprio(0); } while (0)
; #define PG8_WAIT_V(n) asm volatile("s_waitcnt vmcnt(" #n ")" ::: "memory")
; #define PG8_WAIT_L(n) asm volatile("s_waitcnt lgkmcnt(" #n ")" ::: "memory")
; #define PG8_BAR __builtin_amdgcn_s_barrier()
; #define PG8_SCHED __builtin_amdgcn_sched_barrier(0)
; template <class Epi, class Sched, bool ALIGN_EPI = false, bool SP2 = false, bool GRP = false>
; __device__ __forceinline__ void gemm_phase(PG8_LAS unsigned char* lds, const Gemm g, const Sched& S, const Epi& E) {
;     ...
;             PG8_LDA(At, 1, 1); PG8_STAGE(PG8_SB(1, 0), b3, voffB); PG8_STAGE(PG8_SB(1, 1), b3 + hstep, voffB); PG8_STAGE(PG8_SA(1, 0), a3, voffA);
;             PG8_WAIT_V(8); PG8_WAIT_L(0); PG8_BAR; PG8_MMA(1, 0, At, B0); PG8_MMA(1, 1, At, B1); PG8_BAR; PG8_SCHED;
	s_add_i32 s3, s3, s38
	v_lshl_add_u64 v[200:201], v[200:201], 0, s[36:37]
	s_mov_b32 m0, s3
	ds_read_b128 v[176:179], v143 offset:49152
	ds_read_b128 v[180:183], v143 offset:50176
	ds_read_b128 v[184:187], v143 offset:51200
	ds_read_b128 v[188:191], v143 offset:52224
	ds_read_b128 v[192:195], v143 offset:53248
	ds_read_b128 v[196:199], v143 offset:54272
	ds_read_b128 v[210:213], v143 offset:55296
	ds_read_b128 v[222:225], v143 offset:56320
	global_load_lds_dwordx4 v[200:201], off
	v_lshl_add_u64 v[200:201], v[202:203], 0, s[36:37]
	s_add_i32 m0, s3, 0x2000
	s_add_i32 s3, s42, s38
	global_load_lds_dwordx4 v[200:201], off
	v_lshl_add_u64 v[200:201], v[214:215], 0, s[36:37]
	s_mov_b32 m0, s3
	s_nop 0
	global_load_lds_dwordx4 v[200:201], off
	v_lshl_add_u64 v[200:201], v[218:219], 0, s[36:37]
	s_add_i32 m0, s3, 0x2000
	s_nop 0
	global_load_lds_dwordx4 v[200:201], off
	v_lshl_add_u64 v[200:201], v[220:221], 0, s[36:37]
	s_mov_b32 m0, s62
	s_nop 0
	global_load_lds_dwordx4 v[200:201], off
	v_lshl_add_u64 v[200:201], v[226:227], 0, s[36:37]
	s_mov_b32 m0, s63
	s_nop 0
	global_load_lds_dwordx4 v[200:201], off
	s_waitcnt vmcnt(8)
	s_waitcnt lgkmcnt(0)
	s_setprio 1
	s_barrier
	s_waitcnt lgkmcnt(0)
	v_mfma_f32_16x16x32_bf16 v[62:65], v[144:147], v[176:179], v[62:65]
	v_mfma_f32_16x16x32_bf16 v[58:61], v[152:155], v[176:179], v[58:61]
	v_mfma_f32_16x16x32_bf16 v[46:49], v[144:147], v[184:187], v[46:49]
	v_mfma_f32_16x16x32_bf16 v[42:45], v[152:155], v[184:187], v[42:45]
	v_mfma_f32_16x16x32_bf16 v[30:33], v[144:147], v[192:195], v[30:33]
	v_mfma_f32_16x16x32_bf16 v[26:29], v[152:155], v[192:195], v[26:29]
	v_mfma_f32_16x16x32_bf16 v[14:17], v[144:147], v[210:213], v[14:17]
	v_mfma_f32_16x16x32_bf16 v[10:13], v[152:155], v[210:213], v[10:13]
	v_mfma_f32_16x16x32_bf16 v[62:65], v[148:151], v[180:183], v[62:65]
	v_mfma_f32_16x16x32_bf16 v[58:61], v[156:159], v[180:183], v[58:61]
	v_mfma_f32_16x16x32_bf16 v[46:49], v[148:151], v[188:191], v[46:49]
	v_mfma_f32_16x16x32_bf16 v[42:45], v[156:159], v[188:191], v[42:45]
	v_mfma_f32_16x16x32_bf16 v[30:33], v[148:151], v[196:199], v[30:33]
	v_mfma_f32_16x16x32_bf16 v[26:29], v[156:159], v[196:199], v[26:29]
	v_mfma_f32_16x16x32_bf16 v[14:17], v[148:151], v[222:225], v[14:17]
	v_mfma_f32_16x16x32_bf16 v[10:13], v[156:159], v[222:225], v[10:13]
	s_setprio 0
	s_setprio 1
	v_mfma_f32_16x16x32_bf16 v[54:57], v[160:163], v[176:179], v[54:57]
	v_mfma_f32_16x16x32_bf16 v[50:53], v[168:171], v[176:179], v[50:53]
	v_mfma_f32_16x16x32_bf16 v[38:41], v[160:163], v[184:187], v[38:41]
	v_mfma_f32_16x16x32_bf16 v[34:37], v[168:171], v[184:187], v[34:37]
	v_mfma_f32_16x16x32_bf16 v[22:25], v[160:163], v[192:195], v[22:25]
	v_mfma_f32_16x16x32_bf16 v[18:21], v[168:171], v[192:195], v[18:21]
	v_mfma_f32_16x16x32_bf16 v[6:9], v[160:163], v[210:213], v[6:9]
	v_mfma_f32_16x16x32_bf16 v[2:5], v[168:171], v[210:213], v[2:5]
	v_mfma_f32_16x16x32_bf16 v[54:57], v[164:167], v[180:183], v[54:57]
	v_mfma_f32_16x16x32_bf16 v[50:53], v[172:175], v[180:183], v[50:53]
	v_mfma_f32_16x16x32_bf16 v[38:41], v[164:167], v[188:191], v[38:41]
	v_mfma_f32_16x16x32_bf16 v[34:37], v[172:175], v[188:191], v[34:37]
	v_mfma_f32_16x16x32_bf16 v[22:25], v[164:167], v[196:199], v[22:25]
	v_mfma_f32_16x16x32_bf16 v[18:21], v[172:175], v[196:199], v[18:21]
	v_mfma_f32_16x16x32_bf16 v[6:9], v[164:167], v[222:225], v[6:9]
	v_mfma_f32_16x16x32_bf16 v[2:5], v[172:175], v[222:225], v[2:5]
	s_setprio 0
	s_barrier
	s_add_u32 s22, s22, 0x100
	s_addc_u32 s23, s23, 0
	s_add_u32 s40, s40, 0x100
	s_addc_u32 s41, s41, 0
	s_cmp_ge_i32 s30, s70
	s_mov_b32 s3, s30
	s_cbranch_scc0 .LBB0_410

; #define PG8_STAGE(bufoff, gbase, voff) do { _Pragma("unroll") for (int _i = 0; _i < 2; ++_i) \
;         __builtin_amdgcn_global_load_lds((const unsigned*)((const char*)(gbase) + (voff)[_i]), (PG8_LAS unsigned*)(lds + (bufoff) + ldsw + _i * 8192), 16, 0, 0); } while (0)
; #define PG8_LDA(dst, b, h) do { _Pragma("unroll") for (int m = 0; m < 4; ++m) _Pragma("unroll") for (int k = 0; k < 2; ++k) dst[m][k] = *(const PG8_LAS bf16x8*)(lds + PG8_SA(b, h) + aoff + m * 2048 + k * 1024); } while (0)
; #define PG8_LDB(dst, b, h) do { _Pragma("unroll") for (int n = 0; n < 2; ++n) _Pragma("unroll") for (int k = 0; k < 2; ++k) dst[n][k] = *(const PG8_LAS bf16x8*)(lds + PG8_SB(b, h) + boff + n * 2048 + k * 1024); } while (0)
; #define PG8_MMA(ai, bj, At, Bt) do { __builtin_amdgcn_s_setprio(1); _Pragma("unroll") for (int m = 0; m < 4; ++m) _Pragma("unroll") for (int n = 0; n < 2; ++n) _Pragma("unroll") for (int k = 0; k < 2; ++k) \
;         acc[ai][bj][m][n] = __builtin_amdgcn_mfma_f32_16x16x32_bf16(Bt[n][k], At[m][k], acc[ai][bj][m][n], 0, 0, 0); __builtin_amdgcn_s_setprio(0); } while (0)
; #define PG8_WAIT_V(n) asm volatile("s_waitcnt vmcnt(" #n ")" ::: "memory")
; #define PG8_WAIT_L(n) asm volatile("s_waitcnt lgkmcnt(" #n ")" ::: "memory")
; template <class Epi, class Sched, bool ALIGN_EPI = false, bool SP2 = false, bool GRP = false>
; __device__ __forceinline__ void gemm_phase(PG8_LAS unsigned char* lds, const Gemm g, const Sched& S, const Epi& E) {
;     ...
;             const bool last = (t == nt - 2);
;             const char* a1 = cA + (size_t)(t + 1) * kstep;
;             const char* a2 = last ? nA : cA + (size_t)(t + 2) * kstep; const char* b2 = last ? nB : cB + (size_t)(t + 2) * kstep;
;             const char* a3 = a2 + kstep; const char* b3 = b2 + kstep;
;             if (last && has_next) S.a_ready(nxt);
;             if constexpr (SP2) {
;             PG8_LDB(B0, 0, 0); PG8_LDB(B1, 0, 1); PG8_SCHED; PG8_LDA(At, 0, 0); PG8_STAGE(PG8_SA(1, 1), a1 + hstep, voffA);
;             PG8_WAIT_V(8); PG8_WAIT_L(0); PG8_BAR; PG8_MMA(0, 0, At, B0); PG8_MMA(0, 1, At, B1); PG8_BAR; PG8_SCHED;
;             PG8_LDA(At, 0, 1); PG8_STAGE(PG8_SB(0, 0), b2, voffB); PG8_STAGE(PG8_SB(0, 1), b2 + hstep, voffB); PG8_STAGE(PG8_SA(0, 0), a2, voffA);
;             PG8_WAIT_V(8); PG8_WAIT_L(0); PG8_BAR; PG8_MMA(1, 0, At, B0); PG8_MMA(1, 1, At, B1); PG8_BAR; PG8_SCHED;
.LBB0_524:
	s_add_i32 s30, s3, 2
	s_add_u32 s26, s22, 0x80
	s_addc_u32 s27, s23, 0
	s_add_i32 s41, 0, 0x10000
	s_cmp_eq_u32 s74, s3
	s_cselect_b32 s27, s7, s27
	s_cselect_b32 s26, s6, s26
	v_add_u32_e32 v0, s41, v145
	s_cselect_b32 s43, s21, s40
	s_cselect_b32 s42, s20, s39
	s_add_i32 s3, 0, 0x14000
	ds_read_b128 v[150:153], v0
	ds_read_b128 v[154:157], v0 offset:1024
	ds_read_b128 v[158:161], v0 offset:2048
	ds_read_b128 v[162:165], v0 offset:3072
	v_add_u32_e32 v0, s3, v145
	ds_read_b128 v[166:169], v0
	ds_read_b128 v[170:173], v0 offset:1024
	ds_read_b128 v[174:177], v0 offset:2048
	ds_read_b128 v[178:181], v0 offset:3072
	v_lshl_add_u64 v[202:203], s[22:23], 0, v[138:139]
	s_add_i32 m0, s60, 0xc000
	ds_read_b128 v[182:185], v148
	ds_read_b128 v[186:189], v148 offset:1024
	ds_read_b128 v[190:193], v148 offset:2048
	ds_read_b128 v[194:197], v148 offset:3072
	ds_read_b128 v[198:201], v148 offset:4096
	ds_read_b128 v[210:213], v148 offset:5120
	ds_read_b128 v[222:225], v148 offset:6144
	ds_read_b128 v[226:229], v148 offset:7168
	global_load_lds_dwordx4 v[202:203], off
	v_lshl_add_u64 v[202:203], s[22:23], 0, v[140:141]
	s_add_i32 m0, s60, 0xe000
	s_nop 0
	global_load_lds_dwordx4 v[202:203], off
	s_waitcnt vmcnt(8)
	s_waitcnt lgkmcnt(0)
	s_setprio 1
	s_barrier
	s_waitcnt lgkmcnt(0)
	v_mfma_f32_16x16x32_bf16 v[126:129], v[150:153], v[182:185], v[126:129]
	v_mfma_f32_16x16x32_bf16 v[122:125], v[158:161], v[182:185], v[122:125]
	v_mfma_f32_16x16x32_bf16 v[110:113], v[150:153], v[190:193], v[110:113]
	v_mfma_f32_16x16x32_bf16 v[106:109], v[158:161], v[190:193], v[106:109]
	v_mfma_f32_16x16x32_bf16 v[94:97], v[150:153], v[198:201], v[94:97]
	v_mfma_f32_16x16x32_bf16 v[90:93], v[158:161], v[198:201], v[90:93]
	v_mfma_f32_16x16x32_bf16 v[78:81], v[150:153], v[222:225], v[78:81]
	v_mfma_f32_16x16x32_bf16 v[74:77], v[158:161], v[222:225], v[74:77]
	v_mfma_f32_16x16x32_bf16 v[126:129], v[154:157], v[186:189], v[126:129]
	v_mfma_f32_16x16x32_bf16 v[122:125], v[162:165], v[186:189], v[122:125]
	v_mfma_f32_16x16x32_bf16 v[110:113], v[154:157], v[194:197], v[110:113]
	v_mfma_f32_16x16x32_bf16 v[106:109], v[162:165], v[194:197], v[106:109]
	v_mfma_f32_16x16x32_bf16 v[94:97], v[154:157], v[210:213], v[94:97]
	v_mfma_f32_16x16x32_bf16 v[90:93], v[162:165], v[210:213], v[90:93]
	v_mfma_f32_16x16x32_bf16 v[78:81], v[154:157], v[226:229], v[78:81]
	v_mfma_f32_16x16x32_bf16 v[74:77], v[162:165], v[226:229], v[74:77]
	s_setprio 0
	s_setprio 1
	v_mfma_f32_16x16x32_bf16 v[118:121], v[166:169], v[182:185], v[118:121]
	v_mfma_f32_16x16x32_bf16 v[114:117], v[174:177], v[182:185], v[114:117]
	v_mfma_f32_16x16x32_bf16 v[102:105], v[166:169], v[190:193], v[102:105]
	v_mfma_f32_16x16x32_bf16 v[98:101], v[174:177], v[190:193], v[98:101]
	v_mfma_f32_16x16x32_bf16 v[86:89], v[166:169], v[198:201], v[86:89]
	v_mfma_f32_16x16x32_bf16 v[82:85], v[174:177], v[198:201], v[82:85]
	v_mfma_f32_16x16x32_bf16 v[70:73], v[166:169], v[222:225], v[70:73]
	v_mfma_f32_16x16x32_bf16 v[66:69], v[174:177], v[222:225], v[66:69]
	v_mfma_f32_16x16x32_bf16 v[118:121], v[170:173], v[186:189], v[118:121]
	v_mfma_f32_16x16x32_bf16 v[114:117], v[178:181], v[186:189], v[114:117]
	v_mfma_f32_16x16x32_bf16 v[102:105], v[170:173], v[194:197], v[102:105]
	v_mfma_f32_16x16x32_bf16 v[98:101], v[178:181], v[194:197], v[98:101]
	v_mfma_f32_16x16x32_bf16 v[86:89], v[170:173], v[210:213], v[86:89]
	v_mfma_f32_16x16x32_bf16 v[82:85], v[178:181], v[210:213], v[82:85]
	v_mfma_f32_16x16x32_bf16 v[70:73], v[170:173], v[226:229], v[70:73]
	v_mfma_f32_16x16x32_bf16 v[66:69], v[178:181], v[226:229], v[66:69]
	s_setprio 0
	s_barrier
	s_add_i32 s41, s41, s59
	v_lshl_add_u64 v[202:203], s[42:43], 0, v[132:133]
	s_mov_b32 m0, s41
	ds_read_b128 v[182:185], v148 offset:16384
	ds_read_b128 v[186:189], v148 offset:17408
	ds_read_b128 v[190:193], v148 offset:18432
	ds_read_b128 v[194:197], v148 offset:19456
	ds_read_b128 v[198:201], v148 offset:20480
	ds_read_b128 v[210:213], v148 offset:21504
	ds_read_b128 v[222:225], v148 offset:22528
	ds_read_b128 v[226:229], v148 offset:23552
	global_load_lds_dwordx4 v[202:203], off
	s_add_i32 m0, s41, 0x2000
	v_lshl_add_u64 v[214:215], s[42:43], 0, v[136:137]
	s_add_u32 s42, s42, s8
	s_addc_u32 s43, s43, s9
	s_add_i32 s3, s3, s59
	global_load_lds_dwordx4 v[214:215], off
	v_lshl_add_u64 v[218:219], s[42:43], 0, v[132:133]
	s_mov_b32 m0, s3
	v_lshl_add_u64 v[220:221], s[42:43], 0, v[136:137]
	global_load_lds_dwordx4 v[218:219], off
	s_add_i32 m0, s3, 0x2000
	v_lshl_add_u64 v[230:231], s[26:27], 0, v[130:131]
	global_load_lds_dwordx4 v[220:221], off
	s_mov_b32 m0, s60
	v_lshl_add_u64 v[234:235], s[26:27], 0, v[134:135]
	global_load_lds_dwordx4 v[230:231], off
	s_mov_b32 m0, s61
	s_nop 0
	global_load_lds_dwordx4 v[234:235], off
	s_waitcnt vmcnt(8)
	s_waitcnt lgkmcnt(0)
	s_setprio 1
	s_barrier
; #define PG8_STAGE(bufoff, gbase, voff) do { _Pragma("unroll") for (int _i = 0; _i < 2; ++_i) \
;         __builtin_amdgcn_global_load_lds((const unsigned*)((const char*)(gbase) + (voff)[_i]), (PG8_LAS unsigned*)(lds + (bufoff) + ldsw + _i * 8192), 16, 0, 0); } while (0)
; #define PG8_LDA(dst, b, h) do { _Pragma("unroll") for (int m = 0; m < 4; ++m) _Pragma("unroll") for (int k = 0; k < 2; ++k) dst[m][k] = *(const PG8_LAS bf16x8*)(lds + PG8_SA(b, h) + aoff + m * 2048 + k * 1024); } while (0)
; #define PG8_LDB(dst, b, h) do { _Pragma("unroll") for (int n = 0; n < 2; ++n) _Pragma("unroll") for (int k = 0; k < 2; ++k) dst[n][k] = *(const PG8_LAS bf16x8*)(lds + PG8_SB(b, h) + boff + n * 2048 + k * 1024); } while (0)
; #define PG8_MMA(ai, bj, At, Bt) do { __builtin_amdgcn_s_setprio(1); _Pragma("unroll") for (int m = 0; m < 4; ++m) _Pragma("unroll") for (int n = 0; n < 2; ++n) _Pragma("unroll") for (int k = 0; k < 2; ++k) \
;         acc[ai][bj][m][n] = __builtin_amdgcn_mfma_f32_16x16x32_bf16(Bt[n][k], At[m][k], acc[ai][bj][m][n], 0, 0, 0); __builtin_amdgcn_s_setprio(0); } while (0)
; #define PG8_WAIT_V(n) asm volatile("s_waitcnt vmcnt(" #n ")" ::: "memory")
; #define PG8_WAIT_L(n) asm volatile("s_waitcnt lgkmcnt(" #n ")" ::: "memory")
; #define PG8_BAR __builtin_amdgcn_s_barrier()
; #define PG8_SCHED __builtin_amdgcn_sched_barrier(0)
; template <class Epi, class Sched, bool ALIGN_EPI = false, bool SP2 = false, bool GRP = false>
; __device__ __forceinline__ void gemm_phase(PG8_LAS unsigned char* lds, const Gemm g, const Sched& S, const Epi& E) {
;     ...
;             PG8_WAIT_V(8); PG8_WAIT_L(0); PG8_BAR; PG8_MMA(1, 0, At, B0); PG8_MMA(1, 1, At, B1); PG8_BAR; PG8_SCHED;
;             PG8_LDB(B0, 1, 0); PG8_LDB(B1, 1, 1); PG8_SCHED; PG8_LDA(At, 1, 0); PG8_STAGE(PG8_SA(0, 1), a2 + hstep, voffA);
;             PG8_WAIT_V(8); PG8_WAIT_L(0); PG8_BAR; PG8_MMA(0, 0, At, B0); PG8_MMA(0, 1, At, B1); PG8_BAR; PG8_SCHED;
	s_waitcnt lgkmcnt(0)
	v_mfma_f32_16x16x32_bf16 v[62:65], v[150:153], v[182:185], v[62:65]
	v_mfma_f32_16x16x32_bf16 v[58:61], v[158:161], v[182:185], v[58:61]
	v_mfma_f32_16x16x32_bf16 v[46:49], v[150:153], v[190:193], v[46:49]
	v_mfma_f32_16x16x32_bf16 v[42:45], v[158:161], v[190:193], v[42:45]
	v_mfma_f32_16x16x32_bf16 v[30:33], v[150:153], v[198:201], v[30:33]
	v_mfma_f32_16x16x32_bf16 v[26:29], v[158:161], v[198:201], v[26:29]
	v_mfma_f32_16x16x32_bf16 v[14:17], v[150:153], v[222:225], v[14:17]
	v_mfma_f32_16x16x32_bf16 v[10:13], v[158:161], v[222:225], v[10:13]
	v_mfma_f32_16x16x32_bf16 v[62:65], v[154:157], v[186:189], v[62:65]
	v_mfma_f32_16x16x32_bf16 v[58:61], v[162:165], v[186:189], v[58:61]
	v_mfma_f32_16x16x32_bf16 v[46:49], v[154:157], v[194:197], v[46:49]
	v_mfma_f32_16x16x32_bf16 v[42:45], v[162:165], v[194:197], v[42:45]
	v_mfma_f32_16x16x32_bf16 v[30:33], v[154:157], v[210:213], v[30:33]
	v_mfma_f32_16x16x32_bf16 v[26:29], v[162:165], v[210:213], v[26:29]
	v_mfma_f32_16x16x32_bf16 v[14:17], v[154:157], v[226:229], v[14:17]
	v_mfma_f32_16x16x32_bf16 v[10:13], v[162:165], v[226:229], v[10:13]
	s_setprio 0
	s_setprio 1
	v_mfma_f32_16x16x32_bf16 v[54:57], v[166:169], v[182:185], v[54:57]
	v_mfma_f32_16x16x32_bf16 v[50:53], v[174:177], v[182:185], v[50:53]
	v_mfma_f32_16x16x32_bf16 v[38:41], v[166:169], v[190:193], v[38:41]
	v_mfma_f32_16x16x32_bf16 v[34:37], v[174:177], v[190:193], v[34:37]
	v_mfma_f32_16x16x32_bf16 v[22:25], v[166:169], v[198:201], v[22:25]
	v_mfma_f32_16x16x32_bf16 v[18:21], v[174:177], v[198:201], v[18:21]
	v_mfma_f32_16x16x32_bf16 v[6:9], v[166:169], v[222:225], v[6:9]
	v_mfma_f32_16x16x32_bf16 v[2:5], v[174:177], v[222:225], v[2:5]
	v_mfma_f32_16x16x32_bf16 v[54:57], v[170:173], v[186:189], v[54:57]
	v_mfma_f32_16x16x32_bf16 v[50:53], v[178:181], v[186:189], v[50:53]
	v_mfma_f32_16x16x32_bf16 v[38:41], v[170:173], v[194:197], v[38:41]
	v_mfma_f32_16x16x32_bf16 v[34:37], v[178:181], v[194:197], v[34:37]
	v_mfma_f32_16x16x32_bf16 v[22:25], v[170:173], v[210:213], v[22:25]
	v_mfma_f32_16x16x32_bf16 v[18:21], v[178:181], v[210:213], v[18:21]
	v_mfma_f32_16x16x32_bf16 v[6:9], v[170:173], v[226:229], v[6:9]
	v_mfma_f32_16x16x32_bf16 v[2:5], v[178:181], v[226:229], v[2:5]
	s_setprio 0
	s_barrier
	s_add_i32 s3, 0, 0x18000
	v_add_u32_e32 v0, s3, v145
	s_add_i32 s41, 0, 0x1c000
	ds_read_b128 v[150:153], v0
	ds_read_b128 v[154:157], v0 offset:1024
	ds_read_b128 v[158:161], v0 offset:2048
	ds_read_b128 v[162:165], v0 offset:3072
	v_add_u32_e32 v0, s41, v145
	ds_read_b128 v[166:169], v0
	ds_read_b128 v[170:173], v0 offset:1024
	ds_read_b128 v[174:177], v0 offset:2048
	ds_read_b128 v[178:181], v0 offset:3072
	s_add_u32 s26, s26, s8
	s_addc_u32 s27, s27, s9
	s_mov_b32 m0, s62
	v_lshl_add_u64 v[236:237], s[26:27], 0, v[130:131]
	ds_read_b128 v[182:185], v148 offset:32768
	ds_read_b128 v[186:189], v148 offset:33792
	ds_read_b128 v[190:193], v148 offset:34816
	ds_read_b128 v[194:197], v148 offset:35840
	ds_read_b128 v[198:201], v148 offset:36864
	ds_read_b128 v[210:213], v148 offset:37888
	ds_read_b128 v[222:225], v148 offset:38912
	ds_read_b128 v[226:229], v148 offset:39936
	global_load_lds_dwordx4 v[236:237], off
	v_lshl_add_u64 v[236:237], s[26:27], 0, v[134:135]
	s_mov_b32 m0, s63
	s_nop 0
	global_load_lds_dwordx4 v[236:237], off
	s_waitcnt vmcnt(8)
	s_waitcnt lgkmcnt(0)
	s_setprio 1
	s_barrier
	s_waitcnt lgkmcnt(0)
	v_mfma_f32_16x16x32_bf16 v[126:129], v[150:153], v[182:185], v[126:129]
	v_mfma_f32_16x16x32_bf16 v[122:125], v[158:161], v[182:185], v[122:125]
	v_mfma_f32_16x16x32_bf16 v[110:113], v[150:153], v[190:193], v[110:113]
	v_mfma_f32_16x16x32_bf16 v[106:109], v[158:161], v[190:193], v[106:109]
	v_mfma_f32_16x16x32_bf16 v[94:97], v[150:153], v[198:201], v[94:97]
	v_mfma_f32_16x16x32_bf16 v[90:93], v[158:161], v[198:201], v[90:93]
	v_mfma_f32_16x16x32_bf16 v[78:81], v[150:153], v[222:225], v[78:81]
	v_mfma_f32_16x16x32_bf16 v[74:77], v[158:161], v[222:225], v[74:77]
	v_mfma_f32_16x16x32_bf16 v[126:129], v[154:157], v[186:189], v[126:129]
	v_mfma_f32_16x16x32_bf16 v[122:125], v[162:165], v[186:189], v[122:125]
	v_mfma_f32_16x16x32_bf16 v[110:113], v[154:157], v[194:197], v[110:113]
	v_mfma_f32_16x16x32_bf16 v[106:109], v[162:165], v[194:197], v[106:109]
	v_mfma_f32_16x16x32_bf16 v[94:97], v[154:157], v[210:213], v[94:97]
	v_mfma_f32_16x16x32_bf16 v[90:93], v[162:165], v[210:213], v[90:93]
	v_mfma_f32_16x16x32_bf16 v[78:81], v[154:157], v[226:229], v[78:81]
	v_mfma_f32_16x16x32_bf16 v[74:77], v[162:165], v[226:229], v[74:77]
	s_setprio 0
	s_setprio 1
	v_mfma_f32_16x16x32_bf16 v[118:121], v[166:169], v[182:185], v[118:121]
	v_mfma_f32_16x16x32_bf16 v[114:117], v[174:177], v[182:185], v[114:117]
	v_mfma_f32_16x16x32_bf16 v[102:105], v[166:169], v[190:193], v[102:105]
	v_mfma_f32_16x16x32_bf16 v[98:101], v[174:177], v[190:193], v[98:101]
	v_mfma_f32_16x16x32_bf16 v[86:89], v[166:169], v[198:201], v[86:89]
	v_mfma_f32_16x16x32_bf16 v[82:85], v[174:177], v[198:201], v[82:85]
	v_mfma_f32_16x16x32_bf16 v[70:73], v[166:169], v[222:225], v[70:73]
	v_mfma_f32_16x16x32_bf16 v[66:69], v[174:177], v[222:225], v[66:69]
	v_mfma_f32_16x16x32_bf16 v[118:121], v[170:173], v[186:189], v[118:121]
	v_mfma_f32_16x16x32_bf16 v[114:117], v[178:181], v[186:189], v[114:117]
	v_mfma_f32_16x16x32_bf16 v[102:105], v[170:173], v[194:197], v[102:105]
	v_mfma_f32_16x16x32_bf16 v[98:101], v[178:181], v[194:197], v[98:101]
	v_mfma_f32_16x16x32_bf16 v[86:89], v[170:173], v[210:213], v[86:89]
	v_mfma_f32_16x16x32_bf16 v[82:85], v[178:181], v[210:213], v[82:85]
	v_mfma_f32_16x16x32_bf16 v[70:73], v[170:173], v[226:229], v[70:73]
	v_mfma_f32_16x16x32_bf16 v[66:69], v[178:181], v[226:229], v[66:69]
	s_setprio 0
	s_barrier
; #define PG8_STAGE(bufoff, gbase, voff) do { _Pragma("unroll") for (int _i = 0; _i < 2; ++_i) \
;         __builtin_amdgcn_global_load_lds((const unsigned*)((const char*)(gbase) + (voff)[_i]), (PG8_LAS unsigned*)(lds + (bufoff) + ldsw + _i * 8192), 16, 0, 0); } while (0)
; #define PG8_LDA(dst, b, h) do { _Pragma("unroll") for (int m = 0; m < 4; ++m) _Pragma("unroll") for (int k = 0; k < 2; ++k) dst[m][k] = *(const PG8_LAS bf16x8*)(lds + PG8_SA(b, h) + aoff + m * 2048 + k * 1024); } while (0)
; #define PG8_MMA(ai, bj, At, Bt) do { __builtin_amdgcn_s_setprio(1); _Pragma("unroll") for (int m = 0; m < 4; ++m) _Pragma("unroll") for (int n = 0; n < 2; ++n) _Pragma("unroll") for (int k = 0; k < 2; ++k) \
;         acc[ai][bj][m][n] = __builtin_amdgcn_mfma_f32_16x16x32_bf16(Bt[n][k], At[m][k], acc[ai][bj][m][n], 0, 0, 0); __builtin_amdgcn_s_setprio(0); } while (0)
; #define PG8_WAIT_V(n) asm volatile("s_waitcnt vmcnt(" #n ")" ::: "memory")
; #define PG8_WAIT_L(n) asm volatile("s_waitcnt lgkmcnt(" #n ")" ::: "memory")
; #define PG8_BAR __builtin_amdgcn_s_barrier()
; #define PG8_SCHED __builtin_amdgcn_sched_barrier(0)
; template <class Epi, class Sched, bool ALIGN_EPI = false, bool SP2 = false, bool GRP = false>
; __device__ __forceinline__ void gemm_phase(PG8_LAS unsigned char* lds, const Gemm g, const Sched& S, const Epi& E) {
;     ...
;             PG8_LDA(At, 1, 1); PG8_STAGE(PG8_SB(1, 0), b3, voffB); PG8_STAGE(PG8_SB(1, 1), b3 + hstep, voffB); PG8_STAGE(PG8_SA(1, 0), a3, voffA);
;             PG8_WAIT_V(8); PG8_WAIT_L(0); PG8_BAR; PG8_MMA(1, 0, At, B0); PG8_MMA(1, 1, At, B1); PG8_BAR; PG8_SCHED;
	s_add_i32 s3, s3, s59
	v_lshl_add_u64 v[202:203], v[202:203], 0, s[36:37]
	s_mov_b32 m0, s3
	ds_read_b128 v[182:185], v148 offset:49152
	ds_read_b128 v[186:189], v148 offset:50176
	ds_read_b128 v[190:193], v148 offset:51200
	ds_read_b128 v[194:197], v148 offset:52224
	ds_read_b128 v[198:201], v148 offset:53248
	ds_read_b128 v[210:213], v148 offset:54272
	ds_read_b128 v[222:225], v148 offset:55296
	ds_read_b128 v[226:229], v148 offset:56320
	global_load_lds_dwordx4 v[202:203], off
	v_lshl_add_u64 v[202:203], v[214:215], 0, s[36:37]
	s_add_i32 m0, s3, 0x2000
	s_add_i32 s3, s41, s59
	global_load_lds_dwordx4 v[202:203], off
	v_lshl_add_u64 v[202:203], v[218:219], 0, s[36:37]
	s_mov_b32 m0, s3
	s_nop 0
	global_load_lds_dwordx4 v[202:203], off
	v_lshl_add_u64 v[202:203], v[220:221], 0, s[36:37]
	s_add_i32 m0, s3, 0x2000
	s_nop 0
	global_load_lds_dwordx4 v[202:203], off
	v_lshl_add_u64 v[202:203], v[230:231], 0, s[36:37]
	s_mov_b32 m0, s70
	s_nop 0
	global_load_lds_dwordx4 v[202:203], off
	v_lshl_add_u64 v[202:203], v[234:235], 0, s[36:37]
	s_mov_b32 m0, s71
	s_nop 0
	global_load_lds_dwordx4 v[202:203], off
	s_waitcnt vmcnt(8)
	s_waitcnt lgkmcnt(0)
	s_setprio 1
	s_barrier
	s_waitcnt lgkmcnt(0)
	v_mfma_f32_16x16x32_bf16 v[62:65], v[150:153], v[182:185], v[62:65]
	v_mfma_f32_16x16x32_bf16 v[58:61], v[158:161], v[182:185], v[58:61]
	v_mfma_f32_16x16x32_bf16 v[46:49], v[150:153], v[190:193], v[46:49]
	v_mfma_f32_16x16x32_bf16 v[42:45], v[158:161], v[190:193], v[42:45]
	v_mfma_f32_16x16x32_bf16 v[30:33], v[150:153], v[198:201], v[30:33]
	v_mfma_f32_16x16x32_bf16 v[26:29], v[158:161], v[198:201], v[26:29]
	v_mfma_f32_16x16x32_bf16 v[14:17], v[150:153], v[222:225], v[14:17]
	v_mfma_f32_16x16x32_bf16 v[10:13], v[158:161], v[222:225], v[10:13]
	v_mfma_f32_16x16x32_bf16 v[62:65], v[154:157], v[186:189], v[62:65]
	v_mfma_f32_16x16x32_bf16 v[58:61], v[162:165], v[186:189], v[58:61]
	v_mfma_f32_16x16x32_bf16 v[46:49], v[154:157], v[194:197], v[46:49]
	v_mfma_f32_16x16x32_bf16 v[42:45], v[162:165], v[194:197], v[42:45]
	v_mfma_f32_16x16x32_bf16 v[30:33], v[154:157], v[210:213], v[30:33]
	v_mfma_f32_16x16x32_bf16 v[26:29], v[162:165], v[210:213], v[26:29]
	v_mfma_f32_16x16x32_bf16 v[14:17], v[154:157], v[226:229], v[14:17]
	v_mfma_f32_16x16x32_bf16 v[10:13], v[162:165], v[226:229], v[10:13]
	s_setprio 0
	s_setprio 1
	v_mfma_f32_16x16x32_bf16 v[54:57], v[166:169], v[182:185], v[54:57]
	v_mfma_f32_16x16x32_bf16 v[50:53], v[174:177], v[182:185], v[50:53]
	v_mfma_f32_16x16x32_bf16 v[38:41], v[166:169], v[190:193], v[38:41]
	v_mfma_f32_16x16x32_bf16 v[34:37], v[174:177], v[190:193], v[34:37]
	v_mfma_f32_16x16x32_bf16 v[22:25], v[166:169], v[198:201], v[22:25]
	v_mfma_f32_16x16x32_bf16 v[18:21], v[174:177], v[198:201], v[18:21]
	v_mfma_f32_16x16x32_bf16 v[6:9], v[166:169], v[222:225], v[6:9]
	v_mfma_f32_16x16x32_bf16 v[2:5], v[174:177], v[222:225], v[2:5]
	v_mfma_f32_16x16x32_bf16 v[54:57], v[170:173], v[186:189], v[54:57]
	v_mfma_f32_16x16x32_bf16 v[50:53], v[178:181], v[186:189], v[50:53]
	v_mfma_f32_16x16x32_bf16 v[38:41], v[170:173], v[194:197], v[38:41]
	v_mfma_f32_16x16x32_bf16 v[34:37], v[178:181], v[194:197], v[34:37]
	v_mfma_f32_16x16x32_bf16 v[22:25], v[170:173], v[210:213], v[22:25]
	v_mfma_f32_16x16x32_bf16 v[18:21], v[178:181], v[210:213], v[18:21]
	v_mfma_f32_16x16x32_bf16 v[6:9], v[170:173], v[226:229], v[6:9]
	v_mfma_f32_16x16x32_bf16 v[2:5], v[178:181], v[226:229], v[2:5]
	s_setprio 0
	s_barrier
	s_add_u32 s22, s22, 0x100
	s_addc_u32 s23, s23, 0
	s_add_u32 s39, s39, 0x100
	s_addc_u32 s40, s40, 0
	s_cmp_ge_i32 s30, s72
	s_mov_b32 s3, s30
	s_cbranch_scc0 .LBB0_524
	s_mov_b64 s[40:41], 0x50000

; #define PG8_STAGE(bufoff, gbase, voff) do { _Pragma("unroll") for (int _i = 0; _i < 2; ++_i) \
;         __builtin_amdgcn_global_load_lds((const unsigned*)((const char*)(gbase) + (voff)[_i]), (PG8_LAS unsigned*)(lds + (bufoff) + ldsw + _i * 8192), 16, 0, 0); } while (0)
; #define PG8_LDA(dst, b, h) do { _Pragma("unroll") for (int m = 0; m < 4; ++m) _Pragma("unroll") for (int k = 0; k < 2; ++k) dst[m][k] = *(const PG8_LAS bf16x8*)(lds + PG8_SA(b, h) + aoff + m * 2048 + k * 1024); } while (0)
; #define PG8_LDB(dst, b, h) do { _Pragma("unroll") for (int n = 0; n < 2; ++n) _Pragma("unroll") for (int k = 0; k < 2; ++k) dst[n][k] = *(const PG8_LAS bf16x8*)(lds + PG8_SB(b, h) + boff + n * 2048 + k * 1024); } while (0)
; #define PG8_MMA(ai, bj, At, Bt) do { __builtin_amdgcn_s_setprio(1); _Pragma("unroll") for (int m = 0; m < 4; ++m) _Pragma("unroll") for (int n = 0; n < 2; ++n) _Pragma("unroll") for (int k = 0; k < 2; ++k) \
;         acc[ai][bj][m][n] = __builtin_amdgcn_mfma_f32_16x16x32_bf16(Bt[n][k], At[m][k], acc[ai][bj][m][n], 0, 0, 0); __builtin_amdgcn_s_setprio(0); } while (0)
; #define PG8_WAIT_V(n) asm volatile("s_waitcnt vmcnt(" #n ")" ::: "memory")
; #define PG8_WAIT_L(n) asm volatile("s_waitcnt lgkmcnt(" #n ")" ::: "memory")
; template <class Epi, class Sched, bool ALIGN_EPI = false, bool SP2 = false, bool GRP = false>
; __device__ __forceinline__ void gemm_phase(PG8_LAS unsigned char* lds, const Gemm g, const Sched& S, const Epi& E) {
;     ...
;             const bool last = (t == nt - 2);
;             const char* a1 = cA + (size_t)(t + 1) * kstep;
;             const char* a2 = last ? nA : cA + (size_t)(t + 2) * kstep; const char* b2 = last ? nB : cB + (size_t)(t + 2) * kstep;
;             const char* a3 = a2 + kstep; const char* b3 = b2 + kstep;
;             if (last && has_next) S.a_ready(nxt);
;             if constexpr (SP2) {
;             PG8_LDB(B0, 0, 0); PG8_LDB(B1, 0, 1); PG8_SCHED; PG8_LDA(At, 0, 0); PG8_STAGE(PG8_SA(1, 1), a1 + hstep, voffA);
;             PG8_WAIT_V(8); PG8_WAIT_L(0); PG8_BAR; PG8_MMA(0, 0, At, B0); PG8_MMA(0, 1, At, B1); PG8_BAR; PG8_SCHED;
;             PG8_LDA(At, 0, 1); PG8_STAGE(PG8_SB(0, 0), b2, voffB); PG8_STAGE(PG8_SB(0, 1), b2 + hstep, voffB); PG8_STAGE(PG8_SA(0, 0), a2, voffA);
;             PG8_WAIT_V(8); PG8_WAIT_L(0); PG8_BAR; PG8_MMA(1, 0, At, B0); PG8_MMA(1, 1, At, B1); PG8_BAR; PG8_SCHED;
.LBB0_707:
	s_add_i32 s30, s3, 2
	s_add_u32 s38, s70, 0x80
	s_addc_u32 s39, s71, 0
	s_add_i32 s40, 0, 0x10000
	s_cmp_eq_u32 s82, s3
	s_cselect_b32 s73, s7, s39
	s_cselect_b32 s72, s6, s38
	s_cselect_b32 s39, s29, s33
	s_cselect_b32 s38, s28, s25
	s_add_i32 s3, 0, 0x14000
	v_add_u32_e32 v156, s40, v149
	v_add_u32_e32 v172, s3, v149
	ds_read_b128 v[140:143], v156
	ds_read_b128 v[144:147], v156 offset:1024
	ds_read_b128 v[152:155], v156 offset:2048
	ds_read_b128 v[156:159], v156 offset:3072
	ds_read_b128 v[160:163], v172
	ds_read_b128 v[164:167], v172 offset:1024
	ds_read_b128 v[168:171], v172 offset:2048
	ds_read_b128 v[172:175], v172 offset:3072
	v_lshl_add_u64 v[200:201], s[70:71], 0, v[136:137]
	s_add_i32 m0, s76, 0xc000
	ds_read_b128 v[176:179], v151
	ds_read_b128 v[180:183], v151 offset:1024
	ds_read_b128 v[184:187], v151 offset:2048
	ds_read_b128 v[188:191], v151 offset:3072
	ds_read_b128 v[192:195], v151 offset:4096
	ds_read_b128 v[196:199], v151 offset:5120
	ds_read_b128 v[210:213], v151 offset:6144
	ds_read_b128 v[222:225], v151 offset:7168
	global_load_lds_dwordx4 v[200:201], off
	v_lshl_add_u64 v[200:201], s[70:71], 0, v[138:139]
	s_add_i32 m0, s76, 0xe000
	s_nop 0
	global_load_lds_dwordx4 v[200:201], off
	s_waitcnt vmcnt(8)
	s_waitcnt lgkmcnt(0)
	s_setprio 1
	s_barrier
	s_waitcnt lgkmcnt(0)
	v_mfma_f32_16x16x32_bf16 v[126:129], v[140:143], v[176:179], v[126:129]
	v_mfma_f32_16x16x32_bf16 v[122:125], v[152:155], v[176:179], v[122:125]
	v_mfma_f32_16x16x32_bf16 v[110:113], v[140:143], v[184:187], v[110:113]
	v_mfma_f32_16x16x32_bf16 v[106:109], v[152:155], v[184:187], v[106:109]
	v_mfma_f32_16x16x32_bf16 v[94:97], v[140:143], v[192:195], v[94:97]
	v_mfma_f32_16x16x32_bf16 v[90:93], v[152:155], v[192:195], v[90:93]
	v_mfma_f32_16x16x32_bf16 v[78:81], v[140:143], v[210:213], v[78:81]
	v_mfma_f32_16x16x32_bf16 v[74:77], v[152:155], v[210:213], v[74:77]
	v_mfma_f32_16x16x32_bf16 v[126:129], v[144:147], v[180:183], v[126:129]
	v_mfma_f32_16x16x32_bf16 v[122:125], v[156:159], v[180:183], v[122:125]
	v_mfma_f32_16x16x32_bf16 v[110:113], v[144:147], v[188:191], v[110:113]
	v_mfma_f32_16x16x32_bf16 v[106:109], v[156:159], v[188:191], v[106:109]
	v_mfma_f32_16x16x32_bf16 v[94:97], v[144:147], v[196:199], v[94:97]
	v_mfma_f32_16x16x32_bf16 v[90:93], v[156:159], v[196:199], v[90:93]
	v_mfma_f32_16x16x32_bf16 v[78:81], v[144:147], v[222:225], v[78:81]
	v_mfma_f32_16x16x32_bf16 v[74:77], v[156:159], v[222:225], v[74:77]
	s_setprio 0
	s_setprio 1
	v_mfma_f32_16x16x32_bf16 v[118:121], v[160:163], v[176:179], v[118:121]
	v_mfma_f32_16x16x32_bf16 v[114:117], v[168:171], v[176:179], v[114:117]
	v_mfma_f32_16x16x32_bf16 v[102:105], v[160:163], v[184:187], v[102:105]
	v_mfma_f32_16x16x32_bf16 v[98:101], v[168:171], v[184:187], v[98:101]
	v_mfma_f32_16x16x32_bf16 v[86:89], v[160:163], v[192:195], v[86:89]
	v_mfma_f32_16x16x32_bf16 v[82:85], v[168:171], v[192:195], v[82:85]
	v_mfma_f32_16x16x32_bf16 v[70:73], v[160:163], v[210:213], v[70:73]
	v_mfma_f32_16x16x32_bf16 v[66:69], v[168:171], v[210:213], v[66:69]
	v_mfma_f32_16x16x32_bf16 v[118:121], v[164:167], v[180:183], v[118:121]
	v_mfma_f32_16x16x32_bf16 v[114:117], v[172:175], v[180:183], v[114:117]
	v_mfma_f32_16x16x32_bf16 v[102:105], v[164:167], v[188:191], v[102:105]
	v_mfma_f32_16x16x32_bf16 v[98:101], v[172:175], v[188:191], v[98:101]
	v_mfma_f32_16x16x32_bf16 v[86:89], v[164:167], v[196:199], v[86:89]
	v_mfma_f32_16x16x32_bf16 v[82:85], v[172:175], v[196:199], v[82:85]
	v_mfma_f32_16x16x32_bf16 v[70:73], v[164:167], v[222:225], v[70:73]
	v_mfma_f32_16x16x32_bf16 v[66:69], v[172:175], v[222:225], v[66:69]
	s_setprio 0
	s_barrier
	s_add_i32 s40, s40, s75
	v_lshl_add_u64 v[200:201], s[38:39], 0, v[0:1]
	s_mov_b32 m0, s40
	ds_read_b128 v[176:179], v151 offset:16384
	ds_read_b128 v[180:183], v151 offset:17408
	ds_read_b128 v[184:187], v151 offset:18432
	ds_read_b128 v[188:191], v151 offset:19456
	ds_read_b128 v[192:195], v151 offset:20480
	ds_read_b128 v[196:199], v151 offset:21504
	ds_read_b128 v[210:213], v151 offset:22528
	ds_read_b128 v[222:225], v151 offset:23552
	global_load_lds_dwordx4 v[200:201], off
	s_add_i32 m0, s40, 0x2000
	v_lshl_add_u64 v[202:203], s[38:39], 0, v[134:135]
	s_add_u32 s38, s38, s12
	s_addc_u32 s39, s39, s13
	s_add_i32 s3, s3, s75
	global_load_lds_dwordx4 v[202:203], off
	v_lshl_add_u64 v[214:215], s[38:39], 0, v[0:1]
	s_mov_b32 m0, s3
	v_lshl_add_u64 v[218:219], s[38:39], 0, v[134:135]
	global_load_lds_dwordx4 v[214:215], off
	s_add_i32 m0, s3, 0x2000
	v_lshl_add_u64 v[220:221], s[72:73], 0, v[130:131]
	global_load_lds_dwordx4 v[218:219], off
	s_mov_b32 m0, s76
	v_lshl_add_u64 v[226:227], s[72:73], 0, v[132:133]
	global_load_lds_dwordx4 v[220:221], off
	s_mov_b32 m0, s77
	s_nop 0
	global_load_lds_dwordx4 v[226:227], off
	s_waitcnt vmcnt(8)
	s_waitcnt lgkmcnt(0)
	s_setprio 1
	s_barrier
; #define PG8_STAGE(bufoff, gbase, voff) do { _Pragma("unroll") for (int _i = 0; _i < 2; ++_i) \
;         __builtin_amdgcn_global_load_lds((const unsigned*)((const char*)(gbase) + (voff)[_i]), (PG8_LAS unsigned*)(lds + (bufoff) + ldsw + _i * 8192), 16, 0, 0); } while (0)
; #define PG8_LDA(dst, b, h) do { _Pragma("unroll") for (int m = 0; m < 4; ++m) _Pragma("unroll") for (int k = 0; k < 2; ++k) dst[m][k] = *(const PG8_LAS bf16x8*)(lds + PG8_SA(b, h) + aoff + m * 2048 + k * 1024); } while (0)
; #define PG8_LDB(dst, b, h) do { _Pragma("unroll") for (int n = 0; n < 2; ++n) _Pragma("unroll") for (int k = 0; k < 2; ++k) dst[n][k] = *(const PG8_LAS bf16x8*)(lds + PG8_SB(b, h) + boff + n * 2048 + k * 1024); } while (0)
; #define PG8_MMA(ai, bj, At, Bt) do { __builtin_amdgcn_s_setprio(1); _Pragma("unroll") for (int m = 0; m < 4; ++m) _Pragma("unroll") for (int n = 0; n < 2; ++n) _Pragma("unroll") for (int k = 0; k < 2; ++k) \
;         acc[ai][bj][m][n] = __builtin_amdgcn_mfma_f32_16x16x32_bf16(Bt[n][k], At[m][k], acc[ai][bj][m][n], 0, 0, 0); __builtin_amdgcn_s_setprio(0); } while (0)
; #define PG8_WAIT_V(n) asm volatile("s_waitcnt vmcnt(" #n ")" ::: "memory")
; #define PG8_WAIT_L(n) asm volatile("s_waitcnt lgkmcnt(" #n ")" ::: "memory")
; #define PG8_BAR __builtin_amdgcn_s_barrier()
; #define PG8_SCHED __builtin_amdgcn_sched_barrier(0)
; template <class Epi, class Sched, bool ALIGN_EPI = false, bool SP2 = false, bool GRP = false>
; __device__ __forceinline__ void gemm_phase(PG8_LAS unsigned char* lds, const Gemm g, const Sched& S, const Epi& E) {
;     ...
;             PG8_WAIT_V(8); PG8_WAIT_L(0); PG8_BAR; PG8_MMA(1, 0, At, B0); PG8_MMA(1, 1, At, B1); PG8_BAR; PG8_SCHED;
;             PG8_LDB(B0, 1, 0); PG8_LDB(B1, 1, 1); PG8_SCHED; PG8_LDA(At, 1, 0); PG8_STAGE(PG8_SA(0, 1), a2 + hstep, voffA);
;             PG8_WAIT_V(8); PG8_WAIT_L(0); PG8_BAR; PG8_MMA(0, 0, At, B0); PG8_MMA(0, 1, At, B1); PG8_BAR; PG8_SCHED;
	s_waitcnt lgkmcnt(0)
	v_mfma_f32_16x16x32_bf16 v[62:65], v[140:143], v[176:179], v[62:65]
	v_mfma_f32_16x16x32_bf16 v[58:61], v[152:155], v[176:179], v[58:61]
	v_mfma_f32_16x16x32_bf16 v[46:49], v[140:143], v[184:187], v[46:49]
	v_mfma_f32_16x16x32_bf16 v[42:45], v[152:155], v[184:187], v[42:45]
	v_mfma_f32_16x16x32_bf16 v[30:33], v[140:143], v[192:195], v[30:33]
	v_mfma_f32_16x16x32_bf16 v[26:29], v[152:155], v[192:195], v[26:29]
	v_mfma_f32_16x16x32_bf16 v[14:17], v[140:143], v[210:213], v[14:17]
	v_mfma_f32_16x16x32_bf16 v[10:13], v[152:155], v[210:213], v[10:13]
	v_mfma_f32_16x16x32_bf16 v[62:65], v[144:147], v[180:183], v[62:65]
	v_mfma_f32_16x16x32_bf16 v[58:61], v[156:159], v[180:183], v[58:61]
	v_mfma_f32_16x16x32_bf16 v[46:49], v[144:147], v[188:191], v[46:49]
	v_mfma_f32_16x16x32_bf16 v[42:45], v[156:159], v[188:191], v[42:45]
	v_mfma_f32_16x16x32_bf16 v[30:33], v[144:147], v[196:199], v[30:33]
	v_mfma_f32_16x16x32_bf16 v[26:29], v[156:159], v[196:199], v[26:29]
	v_mfma_f32_16x16x32_bf16 v[14:17], v[144:147], v[222:225], v[14:17]
	v_mfma_f32_16x16x32_bf16 v[10:13], v[156:159], v[222:225], v[10:13]
	s_setprio 0
	s_setprio 1
	v_mfma_f32_16x16x32_bf16 v[54:57], v[160:163], v[176:179], v[54:57]
	v_mfma_f32_16x16x32_bf16 v[50:53], v[168:171], v[176:179], v[50:53]
	v_mfma_f32_16x16x32_bf16 v[38:41], v[160:163], v[184:187], v[38:41]
	v_mfma_f32_16x16x32_bf16 v[34:37], v[168:171], v[184:187], v[34:37]
	v_mfma_f32_16x16x32_bf16 v[22:25], v[160:163], v[192:195], v[22:25]
	v_mfma_f32_16x16x32_bf16 v[18:21], v[168:171], v[192:195], v[18:21]
	v_mfma_f32_16x16x32_bf16 v[6:9], v[160:163], v[210:213], v[6:9]
	v_mfma_f32_16x16x32_bf16 v[2:5], v[168:171], v[210:213], v[2:5]
	v_mfma_f32_16x16x32_bf16 v[54:57], v[164:167], v[180:183], v[54:57]
	v_mfma_f32_16x16x32_bf16 v[50:53], v[172:175], v[180:183], v[50:53]
	v_mfma_f32_16x16x32_bf16 v[38:41], v[164:167], v[188:191], v[38:41]
	v_mfma_f32_16x16x32_bf16 v[34:37], v[172:175], v[188:191], v[34:37]
	v_mfma_f32_16x16x32_bf16 v[22:25], v[164:167], v[196:199], v[22:25]
	v_mfma_f32_16x16x32_bf16 v[18:21], v[172:175], v[196:199], v[18:21]
	v_mfma_f32_16x16x32_bf16 v[6:9], v[164:167], v[222:225], v[6:9]
	v_mfma_f32_16x16x32_bf16 v[2:5], v[172:175], v[222:225], v[2:5]
	s_setprio 0
	s_barrier
	s_add_i32 s3, 0, 0x18000
	s_add_i32 s40, 0, 0x1c000
	v_add_u32_e32 v156, s3, v149
	v_add_u32_e32 v172, s40, v149
	ds_read_b128 v[140:143], v156
	ds_read_b128 v[144:147], v156 offset:1024
	ds_read_b128 v[152:155], v156 offset:2048
	ds_read_b128 v[156:159], v156 offset:3072
	ds_read_b128 v[160:163], v172
	ds_read_b128 v[164:167], v172 offset:1024
	ds_read_b128 v[168:171], v172 offset:2048
	ds_read_b128 v[172:175], v172 offset:3072
	s_add_u32 s38, s72, s12
	s_addc_u32 s39, s73, s13
	s_mov_b32 m0, s78
	v_lshl_add_u64 v[228:229], s[38:39], 0, v[130:131]
	ds_read_b128 v[176:179], v151 offset:32768
	ds_read_b128 v[180:183], v151 offset:33792
	ds_read_b128 v[184:187], v151 offset:34816
	ds_read_b128 v[188:191], v151 offset:35840
	ds_read_b128 v[192:195], v151 offset:36864
	ds_read_b128 v[196:199], v151 offset:37888
	ds_read_b128 v[210:213], v151 offset:38912
	ds_read_b128 v[222:225], v151 offset:39936
	global_load_lds_dwordx4 v[228:229], off
	v_lshl_add_u64 v[228:229], s[38:39], 0, v[132:133]
	s_mov_b32 m0, s79
	s_nop 0
	global_load_lds_dwordx4 v[228:229], off
	s_waitcnt vmcnt(8)
	s_waitcnt lgkmcnt(0)
	s_setprio 1
	s_barrier
	s_waitcnt lgkmcnt(0)
	v_mfma_f32_16x16x32_bf16 v[126:129], v[140:143], v[176:179], v[126:129]
	v_mfma_f32_16x16x32_bf16 v[122:125], v[152:155], v[176:179], v[122:125]
	v_mfma_f32_16x16x32_bf16 v[110:113], v[140:143], v[184:187], v[110:113]
	v_mfma_f32_16x16x32_bf16 v[106:109], v[152:155], v[184:187], v[106:109]
	v_mfma_f32_16x16x32_bf16 v[94:97], v[140:143], v[192:195], v[94:97]
	v_mfma_f32_16x16x32_bf16 v[90:93], v[152:155], v[192:195], v[90:93]
	v_mfma_f32_16x16x32_bf16 v[78:81], v[140:143], v[210:213], v[78:81]
	v_mfma_f32_16x16x32_bf16 v[74:77], v[152:155], v[210:213], v[74:77]
	v_mfma_f32_16x16x32_bf16 v[126:129], v[144:147], v[180:183], v[126:129]
	v_mfma_f32_16x16x32_bf16 v[122:125], v[156:159], v[180:183], v[122:125]
	v_mfma_f32_16x16x32_bf16 v[110:113], v[144:147], v[188:191], v[110:113]
	v_mfma_f32_16x16x32_bf16 v[106:109], v[156:159], v[188:191], v[106:109]
	v_mfma_f32_16x16x32_bf16 v[94:97], v[144:147], v[196:199], v[94:97]
	v_mfma_f32_16x16x32_bf16 v[90:93], v[156:159], v[196:199], v[90:93]
	v_mfma_f32_16x16x32_bf16 v[78:81], v[144:147], v[222:225], v[78:81]
	v_mfma_f32_16x16x32_bf16 v[74:77], v[156:159], v[222:225], v[74:77]
	s_setprio 0
	s_setprio 1
	v_mfma_f32_16x16x32_bf16 v[118:121], v[160:163], v[176:179], v[118:121]
	v_mfma_f32_16x16x32_bf16 v[114:117], v[168:171], v[176:179], v[114:117]
	v_mfma_f32_16x16x32_bf16 v[102:105], v[160:163], v[184:187], v[102:105]
	v_mfma_f32_16x16x32_bf16 v[98:101], v[168:171], v[184:187], v[98:101]
	v_mfma_f32_16x16x32_bf16 v[86:89], v[160:163], v[192:195], v[86:89]
	v_mfma_f32_16x16x32_bf16 v[82:85], v[168:171], v[192:195], v[82:85]
	v_mfma_f32_16x16x32_bf16 v[70:73], v[160:163], v[210:213], v[70:73]
	v_mfma_f32_16x16x32_bf16 v[66:69], v[168:171], v[210:213], v[66:69]
	v_mfma_f32_16x16x32_bf16 v[118:121], v[164:167], v[180:183], v[118:121]
	v_mfma_f32_16x16x32_bf16 v[114:117], v[172:175], v[180:183], v[114:117]
	v_mfma_f32_16x16x32_bf16 v[102:105], v[164:167], v[188:191], v[102:105]
	v_mfma_f32_16x16x32_bf16 v[98:101], v[172:175], v[188:191], v[98:101]
	v_mfma_f32_16x16x32_bf16 v[86:89], v[164:167], v[196:199], v[86:89]
	v_mfma_f32_16x16x32_bf16 v[82:85], v[172:175], v[196:199], v[82:85]
	v_mfma_f32_16x16x32_bf16 v[70:73], v[164:167], v[222:225], v[70:73]
	v_mfma_f32_16x16x32_bf16 v[66:69], v[172:175], v[222:225], v[66:69]
	s_setprio 0
	s_barrier
; #define PG8_STAGE(bufoff, gbase, voff) do { _Pragma("unroll") for (int _i = 0; _i < 2; ++_i) \
;         __builtin_amdgcn_global_load_lds((const unsigned*)((const char*)(gbase) + (voff)[_i]), (PG8_LAS unsigned*)(lds + (bufoff) + ldsw + _i * 8192), 16, 0, 0); } while (0)
; #define PG8_LDA(dst, b, h) do { _Pragma("unroll") for (int m = 0; m < 4; ++m) _Pragma("unroll") for (int k = 0; k < 2; ++k) dst[m][k] = *(const PG8_LAS bf16x8*)(lds + PG8_SA(b, h) + aoff + m * 2048 + k * 1024); } while (0)
; #define PG8_MMA(ai, bj, At, Bt) do { __builtin_amdgcn_s_setprio(1); _Pragma("unroll") for (int m = 0; m < 4; ++m) _Pragma("unroll") for (int n = 0; n < 2; ++n) _Pragma("unroll") for (int k = 0; k < 2; ++k) \
;         acc[ai][bj][m][n] = __builtin_amdgcn_mfma_f32_16x16x32_bf16(Bt[n][k], At[m][k], acc[ai][bj][m][n], 0, 0, 0); __builtin_amdgcn_s_setprio(0); } while (0)
; #define PG8_WAIT_V(n) asm volatile("s_waitcnt vmcnt(" #n ")" ::: "memory")
; #define PG8_WAIT_L(n) asm volatile("s_waitcnt lgkmcnt(" #n ")" ::: "memory")
; #define PG8_BAR __builtin_amdgcn_s_barrier()
; #define PG8_SCHED __builtin_amdgcn_sched_barrier(0)
; template <class Epi, class Sched, bool ALIGN_EPI = false, bool SP2 = false, bool GRP = false>
; __device__ __forceinline__ void gemm_phase(PG8_LAS unsigned char* lds, const Gemm g, const Sched& S, const Epi& E) {
;     ...
;             PG8_LDA(At, 1, 1); PG8_STAGE(PG8_SB(1, 0), b3, voffB); PG8_STAGE(PG8_SB(1, 1), b3 + hstep, voffB); PG8_STAGE(PG8_SA(1, 0), a3, voffA);
;             PG8_WAIT_V(8); PG8_WAIT_L(0); PG8_BAR; PG8_MMA(1, 0, At, B0); PG8_MMA(1, 1, At, B1); PG8_BAR; PG8_SCHED;
	s_add_i32 s3, s3, s75
	v_lshl_add_u64 v[200:201], v[200:201], 0, s[36:37]
	s_mov_b32 m0, s3
	ds_read_b128 v[176:179], v151 offset:49152
	ds_read_b128 v[180:183], v151 offset:50176
	ds_read_b128 v[184:187], v151 offset:51200
	ds_read_b128 v[188:191], v151 offset:52224
	ds_read_b128 v[192:195], v151 offset:53248
	ds_read_b128 v[196:199], v151 offset:54272
	ds_read_b128 v[210:213], v151 offset:55296
	ds_read_b128 v[222:225], v151 offset:56320
	global_load_lds_dwordx4 v[200:201], off
	v_lshl_add_u64 v[200:201], v[202:203], 0, s[36:37]
	s_add_i32 m0, s3, 0x2000
	s_add_i32 s3, s40, s75
	global_load_lds_dwordx4 v[200:201], off
	v_lshl_add_u64 v[200:201], v[214:215], 0, s[36:37]
	s_mov_b32 m0, s3
	s_nop 0
	global_load_lds_dwordx4 v[200:201], off
	v_lshl_add_u64 v[200:201], v[218:219], 0, s[36:37]
	s_add_i32 m0, s3, 0x2000
	s_nop 0
	global_load_lds_dwordx4 v[200:201], off
	v_lshl_add_u64 v[200:201], v[220:221], 0, s[36:37]
	s_mov_b32 m0, s34
	s_nop 0
	global_load_lds_dwordx4 v[200:201], off
	v_lshl_add_u64 v[200:201], v[226:227], 0, s[36:37]
	s_mov_b32 m0, s80
	s_nop 0
	global_load_lds_dwordx4 v[200:201], off
	s_waitcnt vmcnt(8)
	s_waitcnt lgkmcnt(0)
	s_setprio 1
	s_barrier
	s_waitcnt lgkmcnt(0)
	v_mfma_f32_16x16x32_bf16 v[62:65], v[140:143], v[176:179], v[62:65]
	v_mfma_f32_16x16x32_bf16 v[58:61], v[152:155], v[176:179], v[58:61]
	v_mfma_f32_16x16x32_bf16 v[46:49], v[140:143], v[184:187], v[46:49]
	v_mfma_f32_16x16x32_bf16 v[42:45], v[152:155], v[184:187], v[42:45]
	v_mfma_f32_16x16x32_bf16 v[30:33], v[140:143], v[192:195], v[30:33]
	v_mfma_f32_16x16x32_bf16 v[26:29], v[152:155], v[192:195], v[26:29]
	v_mfma_f32_16x16x32_bf16 v[14:17], v[140:143], v[210:213], v[14:17]
	v_mfma_f32_16x16x32_bf16 v[10:13], v[152:155], v[210:213], v[10:13]
	v_mfma_f32_16x16x32_bf16 v[62:65], v[144:147], v[180:183], v[62:65]
	v_mfma_f32_16x16x32_bf16 v[58:61], v[156:159], v[180:183], v[58:61]
	v_mfma_f32_16x16x32_bf16 v[46:49], v[144:147], v[188:191], v[46:49]
	v_mfma_f32_16x16x32_bf16 v[42:45], v[156:159], v[188:191], v[42:45]
	v_mfma_f32_16x16x32_bf16 v[30:33], v[144:147], v[196:199], v[30:33]
	v_mfma_f32_16x16x32_bf16 v[26:29], v[156:159], v[196:199], v[26:29]
	v_mfma_f32_16x16x32_bf16 v[14:17], v[144:147], v[222:225], v[14:17]
	v_mfma_f32_16x16x32_bf16 v[10:13], v[156:159], v[222:225], v[10:13]
	s_setprio 0
	s_setprio 1
	v_mfma_f32_16x16x32_bf16 v[54:57], v[160:163], v[176:179], v[54:57]
	v_mfma_f32_16x16x32_bf16 v[50:53], v[168:171], v[176:179], v[50:53]
	v_mfma_f32_16x16x32_bf16 v[38:41], v[160:163], v[184:187], v[38:41]
	v_mfma_f32_16x16x32_bf16 v[34:37], v[168:171], v[184:187], v[34:37]
	v_mfma_f32_16x16x32_bf16 v[22:25], v[160:163], v[192:195], v[22:25]
	v_mfma_f32_16x16x32_bf16 v[18:21], v[168:171], v[192:195], v[18:21]
	v_mfma_f32_16x16x32_bf16 v[6:9], v[160:163], v[210:213], v[6:9]
	v_mfma_f32_16x16x32_bf16 v[2:5], v[168:171], v[210:213], v[2:5]
	v_mfma_f32_16x16x32_bf16 v[54:57], v[164:167], v[180:183], v[54:57]
	v_mfma_f32_16x16x32_bf16 v[50:53], v[172:175], v[180:183], v[50:53]
	v_mfma_f32_16x16x32_bf16 v[38:41], v[164:167], v[188:191], v[38:41]
	v_mfma_f32_16x16x32_bf16 v[34:37], v[172:175], v[188:191], v[34:37]
	v_mfma_f32_16x16x32_bf16 v[22:25], v[164:167], v[196:199], v[22:25]
	v_mfma_f32_16x16x32_bf16 v[18:21], v[172:175], v[196:199], v[18:21]
	v_mfma_f32_16x16x32_bf16 v[6:9], v[164:167], v[222:225], v[6:9]
	v_mfma_f32_16x16x32_bf16 v[2:5], v[172:175], v[222:225], v[2:5]
	s_setprio 0
	s_barrier
	s_add_u32 s70, s70, 0x100
	s_addc_u32 s71, s71, 0
	s_add_u32 s25, s25, 0x100
	s_addc_u32 s33, s33, 0
	s_cmp_ge_i32 s30, s81
	s_mov_b32 s3, s30
	s_cbranch_scc0 .LBB0_707

; #define PG8_STAGE(bufoff, gbase, voff) do { _Pragma("unroll") for (int _i = 0; _i < 2; ++_i) \
;         __builtin_amdgcn_global_load_lds((const unsigned*)((const char*)(gbase) + (voff)[_i]), (PG8_LAS unsigned*)(lds + (bufoff) + ldsw + _i * 8192), 16, 0, 0); } while (0)
; #define PG8_LDA(dst, b, h) do { _Pragma("unroll") for (int m = 0; m < 4; ++m) _Pragma("unroll") for (int k = 0; k < 2; ++k) dst[m][k] = *(const PG8_LAS bf16x8*)(lds + PG8_SA(b, h) + aoff + m * 2048 + k * 1024); } while (0)
; #define PG8_LDB(dst, b, h) do { _Pragma("unroll") for (int n = 0; n < 2; ++n) _Pragma("unroll") for (int k = 0; k < 2; ++k) dst[n][k] = *(const PG8_LAS bf16x8*)(lds + PG8_SB(b, h) + boff + n * 2048 + k * 1024); } while (0)
; #define PG8_MMA(ai, bj, At, Bt) do { __builtin_amdgcn_s_setprio(1); _Pragma("unroll") for (int m = 0; m < 4; ++m) _Pragma("unroll") for (int n = 0; n < 2; ++n) _Pragma("unroll") for (int k = 0; k < 2; ++k) \
;         acc[ai][bj][m][n] = __builtin_amdgcn_mfma_f32_16x16x32_bf16(Bt[n][k], At[m][k], acc[ai][bj][m][n], 0, 0, 0); __builtin_amdgcn_s_setprio(0); } while (0)
; #define PG8_WAIT_V(n) asm volatile("s_waitcnt vmcnt(" #n ")" ::: "memory")
; #define PG8_WAIT_L(n) asm volatile("s_waitcnt lgkmcnt(" #n ")" ::: "memory")
; template <class Epi, class Sched, bool ALIGN_EPI = false, bool SP2 = false, bool GRP = false>
; __device__ __forceinline__ void gemm_phase(PG8_LAS unsigned char* lds, const Gemm g, const Sched& S, const Epi& E) {
;     ...
;             const bool last = (t == nt - 2);
;             const char* a1 = cA + (size_t)(t + 1) * kstep;
;             const char* a2 = last ? nA : cA + (size_t)(t + 2) * kstep; const char* b2 = last ? nB : cB + (size_t)(t + 2) * kstep;
;             const char* a3 = a2 + kstep; const char* b3 = b2 + kstep;
;             if (last && has_next) S.a_ready(nxt);
;             if constexpr (SP2) {
;             PG8_LDB(B0, 0, 0); PG8_LDB(B1, 0, 1); PG8_SCHED; PG8_LDA(At, 0, 0); PG8_STAGE(PG8_SA(1, 1), a1 + hstep, voffA);
;             PG8_WAIT_V(8); PG8_WAIT_L(0); PG8_BAR; PG8_MMA(0, 0, At, B0); PG8_MMA(0, 1, At, B1); PG8_BAR; PG8_SCHED;
;             PG8_LDA(At, 0, 1); PG8_STAGE(PG8_SB(0, 0), b2, voffB); PG8_STAGE(PG8_SB(0, 1), b2 + hstep, voffB); PG8_STAGE(PG8_SA(0, 0), a2, voffA);
;             PG8_WAIT_V(8); PG8_WAIT_L(0); PG8_BAR; PG8_MMA(1, 0, At, B0); PG8_MMA(1, 1, At, B1); PG8_BAR; PG8_SCHED;
.LBB0_801:
	s_add_i32 s93, s82, 2
	s_add_u32 s48, s80, 0x80
	s_addc_u32 s49, s81, 0
	s_add_i32 s94, 0, 0x10000
	s_cmp_eq_u32 s3, s82
	s_cselect_b32 s83, s9, s49
	s_cselect_b32 s82, s8, s48
	v_add_u32_e32 v0, s94, v140
	s_cselect_b32 s69, s79, s92
	s_cselect_b32 s68, s78, s55
	s_add_i32 s48, 0, 0x14000
	ds_read_b128 v[142:145], v0
	ds_read_b128 v[146:149], v0 offset:1024
	ds_read_b128 v[150:153], v0 offset:2048
	ds_read_b128 v[158:161], v0 offset:3072
	v_add_u32_e32 v0, s48, v140
	ds_read_b128 v[162:165], v0
	ds_read_b128 v[166:169], v0 offset:1024
	ds_read_b128 v[170:173], v0 offset:2048
	ds_read_b128 v[174:177], v0 offset:3072
	v_lshl_add_u64 v[2:3], s[80:81], 0, v[136:137]
	s_add_i32 m0, s57, 0xc000
	ds_read_b128 v[178:181], v141
	ds_read_b128 v[182:185], v141 offset:1024
	ds_read_b128 v[186:189], v141 offset:2048
	ds_read_b128 v[190:193], v141 offset:3072
	ds_read_b128 v[194:197], v141 offset:4096
	ds_read_b128 v[198:201], v141 offset:5120
	ds_read_b128 v[210:213], v141 offset:6144
	ds_read_b128 v[222:225], v141 offset:7168
	global_load_lds_dwordx4 v[2:3], off
	v_lshl_add_u64 v[2:3], s[80:81], 0, v[138:139]
	s_add_i32 m0, s57, 0xe000
	s_nop 0
	global_load_lds_dwordx4 v[2:3], off
	s_waitcnt vmcnt(8)
	s_waitcnt lgkmcnt(0)
	s_setprio 1
	s_barrier
	s_waitcnt lgkmcnt(0)
	v_mfma_f32_16x16x32_bf16 v[128:131], v[142:145], v[178:181], v[128:131]
	v_mfma_f32_16x16x32_bf16 v[124:127], v[150:153], v[178:181], v[124:127]
	v_mfma_f32_16x16x32_bf16 v[112:115], v[142:145], v[186:189], v[112:115]
	v_mfma_f32_16x16x32_bf16 v[108:111], v[150:153], v[186:189], v[108:111]
	v_mfma_f32_16x16x32_bf16 v[96:99], v[142:145], v[194:197], v[96:99]
	v_mfma_f32_16x16x32_bf16 v[92:95], v[150:153], v[194:197], v[92:95]
	v_mfma_f32_16x16x32_bf16 v[80:83], v[142:145], v[210:213], v[80:83]
	v_mfma_f32_16x16x32_bf16 v[76:79], v[150:153], v[210:213], v[76:79]
	v_mfma_f32_16x16x32_bf16 v[128:131], v[146:149], v[182:185], v[128:131]
	v_mfma_f32_16x16x32_bf16 v[124:127], v[158:161], v[182:185], v[124:127]
	v_mfma_f32_16x16x32_bf16 v[112:115], v[146:149], v[190:193], v[112:115]
	v_mfma_f32_16x16x32_bf16 v[108:111], v[158:161], v[190:193], v[108:111]
	v_mfma_f32_16x16x32_bf16 v[96:99], v[146:149], v[198:201], v[96:99]
	v_mfma_f32_16x16x32_bf16 v[92:95], v[158:161], v[198:201], v[92:95]
	v_mfma_f32_16x16x32_bf16 v[80:83], v[146:149], v[222:225], v[80:83]
	v_mfma_f32_16x16x32_bf16 v[76:79], v[158:161], v[222:225], v[76:79]
	s_setprio 0
	s_setprio 1
	v_mfma_f32_16x16x32_bf16 v[120:123], v[162:165], v[178:181], v[120:123]
	v_mfma_f32_16x16x32_bf16 v[116:119], v[170:173], v[178:181], v[116:119]
	v_mfma_f32_16x16x32_bf16 v[104:107], v[162:165], v[186:189], v[104:107]
	v_mfma_f32_16x16x32_bf16 v[100:103], v[170:173], v[186:189], v[100:103]
	v_mfma_f32_16x16x32_bf16 v[88:91], v[162:165], v[194:197], v[88:91]
	v_mfma_f32_16x16x32_bf16 v[84:87], v[170:173], v[194:197], v[84:87]
	v_mfma_f32_16x16x32_bf16 v[72:75], v[162:165], v[210:213], v[72:75]
	v_mfma_f32_16x16x32_bf16 v[68:71], v[170:173], v[210:213], v[68:71]
	v_mfma_f32_16x16x32_bf16 v[120:123], v[166:169], v[182:185], v[120:123]
	v_mfma_f32_16x16x32_bf16 v[116:119], v[174:177], v[182:185], v[116:119]
	v_mfma_f32_16x16x32_bf16 v[104:107], v[166:169], v[190:193], v[104:107]
	v_mfma_f32_16x16x32_bf16 v[100:103], v[174:177], v[190:193], v[100:103]
	v_mfma_f32_16x16x32_bf16 v[88:91], v[166:169], v[198:201], v[88:91]
	v_mfma_f32_16x16x32_bf16 v[84:87], v[174:177], v[198:201], v[84:87]
	v_mfma_f32_16x16x32_bf16 v[72:75], v[166:169], v[222:225], v[72:75]
	v_mfma_f32_16x16x32_bf16 v[68:71], v[174:177], v[222:225], v[68:71]
	s_setprio 0
	s_barrier
	s_add_i32 s49, s94, s91
	v_lshl_add_u64 v[154:155], s[68:69], 0, v[132:133]
	s_mov_b32 m0, s49
	ds_read_b128 v[178:181], v141 offset:16384
	ds_read_b128 v[182:185], v141 offset:17408
	ds_read_b128 v[186:189], v141 offset:18432
	ds_read_b128 v[190:193], v141 offset:19456
	ds_read_b128 v[194:197], v141 offset:20480
	ds_read_b128 v[198:201], v141 offset:21504
	ds_read_b128 v[210:213], v141 offset:22528
	ds_read_b128 v[222:225], v141 offset:23552
	global_load_lds_dwordx4 v[154:155], off
	s_add_i32 m0, s49, 0x2000
	v_lshl_add_u64 v[202:203], s[68:69], 0, v[134:135]
	s_add_u32 s68, s68, s10
	s_addc_u32 s69, s69, s11
	s_add_i32 s48, s48, s91
	global_load_lds_dwordx4 v[202:203], off
	v_lshl_add_u64 v[214:215], s[68:69], 0, v[132:133]
	s_mov_b32 m0, s48
	v_lshl_add_u64 v[218:219], s[68:69], 0, v[134:135]
	global_load_lds_dwordx4 v[214:215], off
	s_add_i32 m0, s48, 0x2000
	v_lshl_add_u64 v[226:227], s[82:83], 0, v[132:133]
	global_load_lds_dwordx4 v[218:219], off
	s_mov_b32 m0, s57
	v_lshl_add_u64 v[228:229], s[82:83], 0, v[134:135]
	global_load_lds_dwordx4 v[226:227], off
	s_mov_b32 m0, s86
	s_nop 0
	global_load_lds_dwordx4 v[228:229], off
	s_waitcnt vmcnt(8)
	s_waitcnt lgkmcnt(0)
	s_setprio 1
	s_barrier
; #define PG8_STAGE(bufoff, gbase, voff) do { _Pragma("unroll") for (int _i = 0; _i < 2; ++_i) \
;         __builtin_amdgcn_global_load_lds((const unsigned*)((const char*)(gbase) + (voff)[_i]), (PG8_LAS unsigned*)(lds + (bufoff) + ldsw + _i * 8192), 16, 0, 0); } while (0)
; #define PG8_LDA(dst, b, h) do { _Pragma("unroll") for (int m = 0; m < 4; ++m) _Pragma("unroll") for (int k = 0; k < 2; ++k) dst[m][k] = *(const PG8_LAS bf16x8*)(lds + PG8_SA(b, h) + aoff + m * 2048 + k * 1024); } while (0)
; #define PG8_LDB(dst, b, h) do { _Pragma("unroll") for (int n = 0; n < 2; ++n) _Pragma("unroll") for (int k = 0; k < 2; ++k) dst[n][k] = *(const PG8_LAS bf16x8*)(lds + PG8_SB(b, h) + boff + n * 2048 + k * 1024); } while (0)
; #define PG8_MMA(ai, bj, At, Bt) do { __builtin_amdgcn_s_setprio(1); _Pragma("unroll") for (int m = 0; m < 4; ++m) _Pragma("unroll") for (int n = 0; n < 2; ++n) _Pragma("unroll") for (int k = 0; k < 2; ++k) \
;         acc[ai][bj][m][n] = __builtin_amdgcn_mfma_f32_16x16x32_bf16(Bt[n][k], At[m][k], acc[ai][bj][m][n], 0, 0, 0); __builtin_amdgcn_s_setprio(0); } while (0)
; #define PG8_WAIT_V(n) asm volatile("s_waitcnt vmcnt(" #n ")" ::: "memory")
; #define PG8_WAIT_L(n) asm volatile("s_waitcnt lgkmcnt(" #n ")" ::: "memory")
; #define PG8_BAR __builtin_amdgcn_s_barrier()
; #define PG8_SCHED __builtin_amdgcn_sched_barrier(0)
; template <class Epi, class Sched, bool ALIGN_EPI = false, bool SP2 = false, bool GRP = false>
; __device__ __forceinline__ void gemm_phase(PG8_LAS unsigned char* lds, const Gemm g, const Sched& S, const Epi& E) {
;     ...
;             PG8_WAIT_V(8); PG8_WAIT_L(0); PG8_BAR; PG8_MMA(1, 0, At, B0); PG8_MMA(1, 1, At, B1); PG8_BAR; PG8_SCHED;
;             PG8_LDB(B0, 1, 0); PG8_LDB(B1, 1, 1); PG8_SCHED; PG8_LDA(At, 1, 0); PG8_STAGE(PG8_SA(0, 1), a2 + hstep, voffA);
;             PG8_WAIT_V(8); PG8_WAIT_L(0); PG8_BAR; PG8_MMA(0, 0, At, B0); PG8_MMA(0, 1, At, B1); PG8_BAR; PG8_SCHED;
	s_waitcnt lgkmcnt(0)
	v_mfma_f32_16x16x32_bf16 v[64:67], v[142:145], v[178:181], v[64:67]
	v_mfma_f32_16x16x32_bf16 v[60:63], v[150:153], v[178:181], v[60:63]
	v_mfma_f32_16x16x32_bf16 v[48:51], v[142:145], v[186:189], v[48:51]
	v_mfma_f32_16x16x32_bf16 v[44:47], v[150:153], v[186:189], v[44:47]
	v_mfma_f32_16x16x32_bf16 v[32:35], v[142:145], v[194:197], v[32:35]
	v_mfma_f32_16x16x32_bf16 v[28:31], v[150:153], v[194:197], v[28:31]
	v_mfma_f32_16x16x32_bf16 v[16:19], v[142:145], v[210:213], v[16:19]
	v_mfma_f32_16x16x32_bf16 v[12:15], v[150:153], v[210:213], v[12:15]
	v_mfma_f32_16x16x32_bf16 v[64:67], v[146:149], v[182:185], v[64:67]
	v_mfma_f32_16x16x32_bf16 v[60:63], v[158:161], v[182:185], v[60:63]
	v_mfma_f32_16x16x32_bf16 v[48:51], v[146:149], v[190:193], v[48:51]
	v_mfma_f32_16x16x32_bf16 v[44:47], v[158:161], v[190:193], v[44:47]
	v_mfma_f32_16x16x32_bf16 v[32:35], v[146:149], v[198:201], v[32:35]
	v_mfma_f32_16x16x32_bf16 v[28:31], v[158:161], v[198:201], v[28:31]
	v_mfma_f32_16x16x32_bf16 v[16:19], v[146:149], v[222:225], v[16:19]
	v_mfma_f32_16x16x32_bf16 v[12:15], v[158:161], v[222:225], v[12:15]
	s_setprio 0
	s_setprio 1
	v_mfma_f32_16x16x32_bf16 v[56:59], v[162:165], v[178:181], v[56:59]
	v_mfma_f32_16x16x32_bf16 v[52:55], v[170:173], v[178:181], v[52:55]
	v_mfma_f32_16x16x32_bf16 v[40:43], v[162:165], v[186:189], v[40:43]
	v_mfma_f32_16x16x32_bf16 v[36:39], v[170:173], v[186:189], v[36:39]
	v_mfma_f32_16x16x32_bf16 v[24:27], v[162:165], v[194:197], v[24:27]
	v_mfma_f32_16x16x32_bf16 v[20:23], v[170:173], v[194:197], v[20:23]
	v_mfma_f32_16x16x32_bf16 v[8:11], v[162:165], v[210:213], v[8:11]
	v_mfma_f32_16x16x32_bf16 v[2:5], v[170:173], v[210:213], v[4:7]
	v_mfma_f32_16x16x32_bf16 v[56:59], v[166:169], v[182:185], v[56:59]
	v_mfma_f32_16x16x32_bf16 v[52:55], v[174:177], v[182:185], v[52:55]
	v_mfma_f32_16x16x32_bf16 v[40:43], v[166:169], v[190:193], v[40:43]
	v_mfma_f32_16x16x32_bf16 v[36:39], v[174:177], v[190:193], v[36:39]
	v_mfma_f32_16x16x32_bf16 v[24:27], v[166:169], v[198:201], v[24:27]
	v_mfma_f32_16x16x32_bf16 v[20:23], v[174:177], v[198:201], v[20:23]
	v_mfma_f32_16x16x32_bf16 v[8:11], v[166:169], v[222:225], v[8:11]
	v_mfma_f32_16x16x32_bf16 v[2:5], v[174:177], v[222:225], v[2:5]
	s_setprio 0
	s_barrier
	s_add_i32 s48, 0, 0x18000
	v_add_u32_e32 v0, s48, v140
	s_add_i32 s49, 0, 0x1c000
	ds_read_b128 v[142:145], v0
	ds_read_b128 v[146:149], v0 offset:1024
	ds_read_b128 v[150:153], v0 offset:2048
	ds_read_b128 v[158:161], v0 offset:3072
	v_add_u32_e32 v0, s49, v140
	ds_read_b128 v[162:165], v0
	ds_read_b128 v[166:169], v0 offset:1024
	ds_read_b128 v[170:173], v0 offset:2048
	ds_read_b128 v[174:177], v0 offset:3072
	s_add_u32 s68, s82, s10
	s_addc_u32 s69, s83, s11
	s_mov_b32 m0, s87
	v_lshl_add_u64 v[6:7], s[68:69], 0, v[132:133]
	ds_read_b128 v[178:181], v141 offset:32768
	ds_read_b128 v[182:185], v141 offset:33792
	ds_read_b128 v[186:189], v141 offset:34816
	ds_read_b128 v[190:193], v141 offset:35840
	ds_read_b128 v[194:197], v141 offset:36864
	ds_read_b128 v[198:201], v141 offset:37888
	ds_read_b128 v[210:213], v141 offset:38912
	ds_read_b128 v[222:225], v141 offset:39936
	global_load_lds_dwordx4 v[6:7], off
	v_lshl_add_u64 v[6:7], s[68:69], 0, v[134:135]
	s_mov_b32 m0, s40
	s_nop 0
	global_load_lds_dwordx4 v[6:7], off
	s_waitcnt vmcnt(8)
	s_waitcnt lgkmcnt(0)
	s_setprio 1
	s_barrier
	s_waitcnt lgkmcnt(0)
	v_mfma_f32_16x16x32_bf16 v[128:131], v[142:145], v[178:181], v[128:131]
	v_mfma_f32_16x16x32_bf16 v[124:127], v[150:153], v[178:181], v[124:127]
	v_mfma_f32_16x16x32_bf16 v[112:115], v[142:145], v[186:189], v[112:115]
	v_mfma_f32_16x16x32_bf16 v[108:111], v[150:153], v[186:189], v[108:111]
	v_mfma_f32_16x16x32_bf16 v[96:99], v[142:145], v[194:197], v[96:99]
	v_mfma_f32_16x16x32_bf16 v[92:95], v[150:153], v[194:197], v[92:95]
	v_mfma_f32_16x16x32_bf16 v[80:83], v[142:145], v[210:213], v[80:83]
	v_mfma_f32_16x16x32_bf16 v[76:79], v[150:153], v[210:213], v[76:79]
	v_mfma_f32_16x16x32_bf16 v[128:131], v[146:149], v[182:185], v[128:131]
	v_mfma_f32_16x16x32_bf16 v[124:127], v[158:161], v[182:185], v[124:127]
	v_mfma_f32_16x16x32_bf16 v[112:115], v[146:149], v[190:193], v[112:115]
	v_mfma_f32_16x16x32_bf16 v[108:111], v[158:161], v[190:193], v[108:111]
	v_mfma_f32_16x16x32_bf16 v[96:99], v[146:149], v[198:201], v[96:99]
	v_mfma_f32_16x16x32_bf16 v[92:95], v[158:161], v[198:201], v[92:95]
	v_mfma_f32_16x16x32_bf16 v[80:83], v[146:149], v[222:225], v[80:83]
	v_mfma_f32_16x16x32_bf16 v[76:79], v[158:161], v[222:225], v[76:79]
	s_setprio 0
	s_setprio 1
	v_mfma_f32_16x16x32_bf16 v[120:123], v[162:165], v[178:181], v[120:123]
	v_mfma_f32_16x16x32_bf16 v[116:119], v[170:173], v[178:181], v[116:119]
	v_mfma_f32_16x16x32_bf16 v[104:107], v[162:165], v[186:189], v[104:107]
	v_mfma_f32_16x16x32_bf16 v[100:103], v[170:173], v[186:189], v[100:103]
	v_mfma_f32_16x16x32_bf16 v[88:91], v[162:165], v[194:197], v[88:91]
	v_mfma_f32_16x16x32_bf16 v[84:87], v[170:173], v[194:197], v[84:87]
	v_mfma_f32_16x16x32_bf16 v[72:75], v[162:165], v[210:213], v[72:75]
	v_mfma_f32_16x16x32_bf16 v[68:71], v[170:173], v[210:213], v[68:71]
	v_mfma_f32_16x16x32_bf16 v[120:123], v[166:169], v[182:185], v[120:123]
	v_mfma_f32_16x16x32_bf16 v[116:119], v[174:177], v[182:185], v[116:119]
	v_mfma_f32_16x16x32_bf16 v[104:107], v[166:169], v[190:193], v[104:107]
	v_mfma_f32_16x16x32_bf16 v[100:103], v[174:177], v[190:193], v[100:103]
	v_mfma_f32_16x16x32_bf16 v[88:91], v[166:169], v[198:201], v[88:91]
	v_mfma_f32_16x16x32_bf16 v[84:87], v[174:177], v[198:201], v[84:87]
	v_mfma_f32_16x16x32_bf16 v[72:75], v[166:169], v[222:225], v[72:75]
	v_mfma_f32_16x16x32_bf16 v[68:71], v[174:177], v[222:225], v[68:71]
	s_setprio 0
	s_barrier
; #define PG8_STAGE(bufoff, gbase, voff) do { _Pragma("unroll") for (int _i = 0; _i < 2; ++_i) \
;         __builtin_amdgcn_global_load_lds((const unsigned*)((const char*)(gbase) + (voff)[_i]), (PG8_LAS unsigned*)(lds + (bufoff) + ldsw + _i * 8192), 16, 0, 0); } while (0)
; #define PG8_LDA(dst, b, h) do { _Pragma("unroll") for (int m = 0; m < 4; ++m) _Pragma("unroll") for (int k = 0; k < 2; ++k) dst[m][k] = *(const PG8_LAS bf16x8*)(lds + PG8_SA(b, h) + aoff + m * 2048 + k * 1024); } while (0)
; #define PG8_MMA(ai, bj, At, Bt) do { __builtin_amdgcn_s_setprio(1); _Pragma("unroll") for (int m = 0; m < 4; ++m) _Pragma("unroll") for (int n = 0; n < 2; ++n) _Pragma("unroll") for (int k = 0; k < 2; ++k) \
;         acc[ai][bj][m][n] = __builtin_amdgcn_mfma_f32_16x16x32_bf16(Bt[n][k], At[m][k], acc[ai][bj][m][n], 0, 0, 0); __builtin_amdgcn_s_setprio(0); } while (0)
; #define PG8_WAIT_V(n) asm volatile("s_waitcnt vmcnt(" #n ")" ::: "memory")
; #define PG8_WAIT_L(n) asm volatile("s_waitcnt lgkmcnt(" #n ")" ::: "memory")
; #define PG8_BAR __builtin_amdgcn_s_barrier()
; #define PG8_SCHED __builtin_amdgcn_sched_barrier(0)
; template <class Epi, class Sched, bool ALIGN_EPI = false, bool SP2 = false, bool GRP = false>
; __device__ __forceinline__ void gemm_phase(PG8_LAS unsigned char* lds, const Gemm g, const Sched& S, const Epi& E) {
;     ...
;             PG8_LDA(At, 1, 1); PG8_STAGE(PG8_SB(1, 0), b3, voffB); PG8_STAGE(PG8_SB(1, 1), b3 + hstep, voffB); PG8_STAGE(PG8_SA(1, 0), a3, voffA);
;             PG8_WAIT_V(8); PG8_WAIT_L(0); PG8_BAR; PG8_MMA(1, 0, At, B0); PG8_MMA(1, 1, At, B1); PG8_BAR; PG8_SCHED;
	s_add_i32 s48, s48, s91
	v_lshl_add_u64 v[6:7], v[154:155], 0, s[36:37]
	s_mov_b32 m0, s48
	ds_read_b128 v[178:181], v141 offset:49152
	ds_read_b128 v[182:185], v141 offset:50176
	ds_read_b128 v[186:189], v141 offset:51200
	ds_read_b128 v[190:193], v141 offset:52224
	ds_read_b128 v[194:197], v141 offset:53248
	ds_read_b128 v[198:201], v141 offset:54272
	ds_read_b128 v[210:213], v141 offset:55296
	ds_read_b128 v[222:225], v141 offset:56320
	global_load_lds_dwordx4 v[6:7], off
	v_lshl_add_u64 v[6:7], v[202:203], 0, s[36:37]
	s_add_i32 m0, s48, 0x2000
	s_add_i32 s48, s49, s91
	global_load_lds_dwordx4 v[6:7], off
	v_lshl_add_u64 v[6:7], v[214:215], 0, s[36:37]
	s_mov_b32 m0, s48
	s_nop 0
	global_load_lds_dwordx4 v[6:7], off
	v_lshl_add_u64 v[6:7], v[218:219], 0, s[36:37]
	s_add_i32 m0, s48, 0x2000
	s_nop 0
	global_load_lds_dwordx4 v[6:7], off
	v_lshl_add_u64 v[6:7], v[226:227], 0, s[36:37]
	s_mov_b32 m0, s42
	s_nop 0
	global_load_lds_dwordx4 v[6:7], off
	v_lshl_add_u64 v[6:7], v[228:229], 0, s[36:37]
	s_mov_b32 m0, s43
	s_nop 0
	global_load_lds_dwordx4 v[6:7], off
	s_waitcnt vmcnt(8)
	s_waitcnt lgkmcnt(0)
	s_setprio 1
	s_barrier
	s_waitcnt lgkmcnt(0)
	v_mfma_f32_16x16x32_bf16 v[64:67], v[142:145], v[178:181], v[64:67]
	v_mfma_f32_16x16x32_bf16 v[60:63], v[150:153], v[178:181], v[60:63]
	v_mfma_f32_16x16x32_bf16 v[48:51], v[142:145], v[186:189], v[48:51]
	v_mfma_f32_16x16x32_bf16 v[44:47], v[150:153], v[186:189], v[44:47]
	v_mfma_f32_16x16x32_bf16 v[32:35], v[142:145], v[194:197], v[32:35]
	v_mfma_f32_16x16x32_bf16 v[28:31], v[150:153], v[194:197], v[28:31]
	v_mfma_f32_16x16x32_bf16 v[16:19], v[142:145], v[210:213], v[16:19]
	v_mfma_f32_16x16x32_bf16 v[12:15], v[150:153], v[210:213], v[12:15]
	v_mfma_f32_16x16x32_bf16 v[64:67], v[146:149], v[182:185], v[64:67]
	v_mfma_f32_16x16x32_bf16 v[60:63], v[158:161], v[182:185], v[60:63]
	v_mfma_f32_16x16x32_bf16 v[48:51], v[146:149], v[190:193], v[48:51]
	v_mfma_f32_16x16x32_bf16 v[44:47], v[158:161], v[190:193], v[44:47]
	v_mfma_f32_16x16x32_bf16 v[32:35], v[146:149], v[198:201], v[32:35]
	v_mfma_f32_16x16x32_bf16 v[28:31], v[158:161], v[198:201], v[28:31]
	v_mfma_f32_16x16x32_bf16 v[16:19], v[146:149], v[222:225], v[16:19]
	v_mfma_f32_16x16x32_bf16 v[12:15], v[158:161], v[222:225], v[12:15]
	s_setprio 0
	s_setprio 1
	v_mfma_f32_16x16x32_bf16 v[56:59], v[162:165], v[178:181], v[56:59]
	v_mfma_f32_16x16x32_bf16 v[52:55], v[170:173], v[178:181], v[52:55]
	v_mfma_f32_16x16x32_bf16 v[40:43], v[162:165], v[186:189], v[40:43]
	v_mfma_f32_16x16x32_bf16 v[36:39], v[170:173], v[186:189], v[36:39]
	v_mfma_f32_16x16x32_bf16 v[24:27], v[162:165], v[194:197], v[24:27]
	v_mfma_f32_16x16x32_bf16 v[20:23], v[170:173], v[194:197], v[20:23]
	v_mfma_f32_16x16x32_bf16 v[6:9], v[162:165], v[210:213], v[8:11]
	v_mfma_f32_16x16x32_bf16 v[2:5], v[170:173], v[210:213], v[2:5]
	v_mfma_f32_16x16x32_bf16 v[56:59], v[166:169], v[182:185], v[56:59]
	v_mfma_f32_16x16x32_bf16 v[52:55], v[174:177], v[182:185], v[52:55]
	v_mfma_f32_16x16x32_bf16 v[40:43], v[166:169], v[190:193], v[40:43]
	v_mfma_f32_16x16x32_bf16 v[36:39], v[174:177], v[190:193], v[36:39]
	v_mfma_f32_16x16x32_bf16 v[24:27], v[166:169], v[198:201], v[24:27]
	v_mfma_f32_16x16x32_bf16 v[20:23], v[174:177], v[198:201], v[20:23]
	v_mfma_f32_16x16x32_bf16 v[8:11], v[166:169], v[222:225], v[6:9]
	v_mfma_f32_16x16x32_bf16 v[4:7], v[174:177], v[222:225], v[2:5]
	s_setprio 0
	s_barrier
	s_add_u32 s80, s80, 0x100
	s_addc_u32 s81, s81, 0
	s_add_u32 s55, s55, 0x100
	s_addc_u32 s92, s92, 0
	s_cmp_ge_i32 s93, s66
	s_mov_b32 s82, s93
	s_cbranch_scc0 .LBB0_801

; #define PG8_STAGE(bufoff, gbase, voff) do { _Pragma("unroll") for (int _i = 0; _i < 2; ++_i) \
;         __builtin_amdgcn_global_load_lds((const unsigned*)((const char*)(gbase) + (voff)[_i]), (PG8_LAS unsigned*)(lds + (bufoff) + ldsw + _i * 8192), 16, 0, 0); } while (0)
; #define PG8_LDA(dst, b, h) do { _Pragma("unroll") for (int m = 0; m < 4; ++m) _Pragma("unroll") for (int k = 0; k < 2; ++k) dst[m][k] = *(const PG8_LAS bf16x8*)(lds + PG8_SA(b, h) + aoff + m * 2048 + k * 1024); } while (0)
; #define PG8_LDB(dst, b, h) do { _Pragma("unroll") for (int n = 0; n < 2; ++n) _Pragma("unroll") for (int k = 0; k < 2; ++k) dst[n][k] = *(const PG8_LAS bf16x8*)(lds + PG8_SB(b, h) + boff + n * 2048 + k * 1024); } while (0)
; #define PG8_MMA(ai, bj, At, Bt) do { __builtin_amdgcn_s_setprio(1); _Pragma("unroll") for (int m = 0; m < 4; ++m) _Pragma("unroll") for (int n = 0; n < 2; ++n) _Pragma("unroll") for (int k = 0; k < 2; ++k) \
;         acc[ai][bj][m][n] = __builtin_amdgcn_mfma_f32_16x16x32_bf16(Bt[n][k], At[m][k], acc[ai][bj][m][n], 0, 0, 0); __builtin_amdgcn_s_setprio(0); } while (0)
; #define PG8_WAIT_V(n) asm volatile("s_waitcnt vmcnt(" #n ")" ::: "memory")
; #define PG8_WAIT_L(n) asm volatile("s_waitcnt lgkmcnt(" #n ")" ::: "memory")
; template <class Epi, class Sched, bool ALIGN_EPI = false, bool SP2 = false, bool GRP = false>
; __device__ __forceinline__ void gemm_phase(PG8_LAS unsigned char* lds, const Gemm g, const Sched& S, const Epi& E) {
;     ...
;             const bool last = (t == nt - 2);
;             const char* a1 = cA + (size_t)(t + 1) * kstep;
;             const char* a2 = last ? nA : cA + (size_t)(t + 2) * kstep; const char* b2 = last ? nB : cB + (size_t)(t + 2) * kstep;
;             const char* a3 = a2 + kstep; const char* b3 = b2 + kstep;
;             if (last && has_next) S.a_ready(nxt);
;             if constexpr (SP2) {
;             PG8_LDB(B0, 0, 0); PG8_LDB(B1, 0, 1); PG8_SCHED; PG8_LDA(At, 0, 0); PG8_STAGE(PG8_SA(1, 1), a1 + hstep, voffA);
;             PG8_WAIT_V(8); PG8_WAIT_L(0); PG8_BAR; PG8_MMA(0, 0, At, B0); PG8_MMA(0, 1, At, B1); PG8_BAR; PG8_SCHED;
;             PG8_LDA(At, 0, 1); PG8_STAGE(PG8_SB(0, 0), b2, voffB); PG8_STAGE(PG8_SB(0, 1), b2 + hstep, voffB); PG8_STAGE(PG8_SA(0, 0), a2, voffA);
;             PG8_WAIT_V(8); PG8_WAIT_L(0); PG8_BAR; PG8_MMA(1, 0, At, B0); PG8_MMA(1, 1, At, B1); PG8_BAR; PG8_SCHED;
.LBB0_886:
	s_add_i32 vcc_lo, s84, 2
	s_add_u32 s48, s82, 0x80
	s_addc_u32 s49, s83, 0
	s_add_i32 s94, 0, 0x10000
	s_cmp_eq_u32 s3, s84
	s_cselect_b32 s85, s9, s49
	s_cselect_b32 s84, s8, s48
	v_add_u32_e32 v0, s94, v112
	s_cselect_b32 s69, s81, s96
	s_cselect_b32 s68, s80, s55
	s_add_i32 s48, 0, 0x14000
	ds_read_b128 v[120:123], v0
	ds_read_b128 v[132:135], v0 offset:1024
	ds_read_b128 v[136:139], v0 offset:2048
	ds_read_b128 v[140:143], v0 offset:3072
	v_add_u32_e32 v0, s48, v112
	ds_read_b128 v[148:151], v0
	ds_read_b128 v[160:163], v0 offset:1024
	ds_read_b128 v[168:171], v0 offset:2048
	ds_read_b128 v[172:175], v0 offset:3072
	v_lshl_add_u64 v[2:3], s[82:83], 0, v[104:105]
	s_add_i32 m0, s57, 0xc000
	ds_read_b128 v[176:179], v113
	ds_read_b128 v[180:183], v113 offset:1024
	ds_read_b128 v[184:187], v113 offset:2048
	ds_read_b128 v[188:191], v113 offset:3072
	ds_read_b128 v[192:195], v113 offset:4096
	ds_read_b128 v[198:201], v113 offset:5120
	ds_read_b128 v[210:213], v113 offset:6144
	ds_read_b128 v[222:225], v113 offset:7168
	global_load_lds_dwordx4 v[2:3], off
	v_lshl_add_u64 v[2:3], s[82:83], 0, v[106:107]
	s_add_i32 m0, s57, 0xe000
	s_nop 0
	global_load_lds_dwordx4 v[2:3], off
	s_waitcnt vmcnt(8)
	s_waitcnt lgkmcnt(0)
	s_setprio 1
	s_barrier
	s_waitcnt lgkmcnt(0)
	v_mfma_f32_16x16x32_bf16 v[164:167], v[120:123], v[176:179], v[164:167]
	v_mfma_f32_16x16x32_bf16 v[156:159], v[136:139], v[176:179], v[156:159]
	v_mfma_f32_16x16x32_bf16 v[128:131], v[120:123], v[184:187], v[128:131]
	v_mfma_f32_16x16x32_bf16 v[124:127], v[136:139], v[184:187], v[124:127]
	v_mfma_f32_16x16x32_bf16 v[96:99], v[120:123], v[192:195], v[96:99]
	v_mfma_f32_16x16x32_bf16 v[92:95], v[136:139], v[192:195], v[92:95]
	v_mfma_f32_16x16x32_bf16 v[80:83], v[120:123], v[210:213], v[80:83]
	v_mfma_f32_16x16x32_bf16 v[76:79], v[136:139], v[210:213], v[76:79]
	v_mfma_f32_16x16x32_bf16 v[164:167], v[132:135], v[180:183], v[164:167]
	v_mfma_f32_16x16x32_bf16 v[156:159], v[140:143], v[180:183], v[156:159]
	v_mfma_f32_16x16x32_bf16 v[128:131], v[132:135], v[188:191], v[128:131]
	v_mfma_f32_16x16x32_bf16 v[124:127], v[140:143], v[188:191], v[124:127]
	v_mfma_f32_16x16x32_bf16 v[96:99], v[132:135], v[198:201], v[96:99]
	v_mfma_f32_16x16x32_bf16 v[92:95], v[140:143], v[198:201], v[92:95]
	v_mfma_f32_16x16x32_bf16 v[80:83], v[132:135], v[222:225], v[80:83]
	v_mfma_f32_16x16x32_bf16 v[76:79], v[140:143], v[222:225], v[76:79]
	s_setprio 0
	s_setprio 1
	v_mfma_f32_16x16x32_bf16 v[152:155], v[148:151], v[176:179], v[152:155]
	v_mfma_f32_16x16x32_bf16 v[144:147], v[168:171], v[176:179], v[144:147]
	v_mfma_f32_16x16x32_bf16 v[114:117], v[148:151], v[184:187], v[116:119]
	v_mfma_f32_16x16x32_bf16 v[108:111], v[168:171], v[184:187], v[108:111]
	v_mfma_f32_16x16x32_bf16 v[88:91], v[148:151], v[192:195], v[88:91]
	v_mfma_f32_16x16x32_bf16 v[84:87], v[168:171], v[192:195], v[84:87]
	v_mfma_f32_16x16x32_bf16 v[72:75], v[148:151], v[210:213], v[72:75]
	v_mfma_f32_16x16x32_bf16 v[68:71], v[168:171], v[210:213], v[68:71]
	v_mfma_f32_16x16x32_bf16 v[152:155], v[160:163], v[180:183], v[152:155]
	v_mfma_f32_16x16x32_bf16 v[144:147], v[172:175], v[180:183], v[144:147]
	v_mfma_f32_16x16x32_bf16 v[114:117], v[160:163], v[188:191], v[114:117]
	v_mfma_f32_16x16x32_bf16 v[108:111], v[172:175], v[188:191], v[108:111]
	v_mfma_f32_16x16x32_bf16 v[88:91], v[160:163], v[198:201], v[88:91]
	v_mfma_f32_16x16x32_bf16 v[84:87], v[172:175], v[198:201], v[84:87]
	v_mfma_f32_16x16x32_bf16 v[72:75], v[160:163], v[222:225], v[72:75]
	v_mfma_f32_16x16x32_bf16 v[68:71], v[172:175], v[222:225], v[68:71]
	s_setprio 0
	s_barrier
	s_add_i32 s49, s94, s91
	v_lshl_add_u64 v[202:203], s[68:69], 0, v[100:101]
	s_mov_b32 m0, s49
	ds_read_b128 v[176:179], v113 offset:16384
	ds_read_b128 v[180:183], v113 offset:17408
	ds_read_b128 v[184:187], v113 offset:18432
	ds_read_b128 v[188:191], v113 offset:19456
	ds_read_b128 v[192:195], v113 offset:20480
	ds_read_b128 v[198:201], v113 offset:21504
	ds_read_b128 v[210:213], v113 offset:22528
	ds_read_b128 v[222:225], v113 offset:23552
	global_load_lds_dwordx4 v[202:203], off
	s_add_i32 m0, s49, 0x2000
	v_lshl_add_u64 v[214:215], s[68:69], 0, v[102:103]
	s_add_u32 s68, s68, s10
	s_addc_u32 s69, s69, s11
	s_add_i32 s48, s48, s91
	global_load_lds_dwordx4 v[214:215], off
	v_lshl_add_u64 v[218:219], s[68:69], 0, v[100:101]
	s_mov_b32 m0, s48
	v_lshl_add_u64 v[226:227], s[68:69], 0, v[102:103]
	global_load_lds_dwordx4 v[218:219], off
	s_add_i32 m0, s48, 0x2000
	v_lshl_add_u64 v[228:229], s[84:85], 0, v[100:101]
	global_load_lds_dwordx4 v[226:227], off
	s_mov_b32 m0, s57
	v_lshl_add_u64 v[230:231], s[84:85], 0, v[102:103]
	global_load_lds_dwordx4 v[228:229], off
	s_mov_b32 m0, s86
	s_nop 0
	global_load_lds_dwordx4 v[230:231], off
	s_waitcnt vmcnt(8)
	s_waitcnt lgkmcnt(0)
	s_setprio 1
	s_barrier
; #define PG8_STAGE(bufoff, gbase, voff) do { _Pragma("unroll") for (int _i = 0; _i < 2; ++_i) \
;         __builtin_amdgcn_global_load_lds((const unsigned*)((const char*)(gbase) + (voff)[_i]), (PG8_LAS unsigned*)(lds + (bufoff) + ldsw + _i * 8192), 16, 0, 0); } while (0)
; #define PG8_LDA(dst, b, h) do { _Pragma("unroll") for (int m = 0; m < 4; ++m) _Pragma("unroll") for (int k = 0; k < 2; ++k) dst[m][k] = *(const PG8_LAS bf16x8*)(lds + PG8_SA(b, h) + aoff + m * 2048 + k * 1024); } while (0)
; #define PG8_LDB(dst, b, h) do { _Pragma("unroll") for (int n = 0; n < 2; ++n) _Pragma("unroll") for (int k = 0; k < 2; ++k) dst[n][k] = *(const PG8_LAS bf16x8*)(lds + PG8_SB(b, h) + boff + n * 2048 + k * 1024); } while (0)
; #define PG8_MMA(ai, bj, At, Bt) do { __builtin_amdgcn_s_setprio(1); _Pragma("unroll") for (int m = 0; m < 4; ++m) _Pragma("unroll") for (int n = 0; n < 2; ++n) _Pragma("unroll") for (int k = 0; k < 2; ++k) \
;         acc[ai][bj][m][n] = __builtin_amdgcn_mfma_f32_16x16x32_bf16(Bt[n][k], At[m][k], acc[ai][bj][m][n], 0, 0, 0); __builtin_amdgcn_s_setprio(0); } while (0)
; #define PG8_WAIT_V(n) asm volatile("s_waitcnt vmcnt(" #n ")" ::: "memory")
; #define PG8_WAIT_L(n) asm volatile("s_waitcnt lgkmcnt(" #n ")" ::: "memory")
; #define PG8_BAR __builtin_amdgcn_s_barrier()
; #define PG8_SCHED __builtin_amdgcn_sched_barrier(0)
; template <class Epi, class Sched, bool ALIGN_EPI = false, bool SP2 = false, bool GRP = false>
; __device__ __forceinline__ void gemm_phase(PG8_LAS unsigned char* lds, const Gemm g, const Sched& S, const Epi& E) {
;     ...
;             PG8_WAIT_V(8); PG8_WAIT_L(0); PG8_BAR; PG8_MMA(1, 0, At, B0); PG8_MMA(1, 1, At, B1); PG8_BAR; PG8_SCHED;
;             PG8_LDB(B0, 1, 0); PG8_LDB(B1, 1, 1); PG8_SCHED; PG8_LDA(At, 1, 0); PG8_STAGE(PG8_SA(0, 1), a2 + hstep, voffA);
;             PG8_WAIT_V(8); PG8_WAIT_L(0); PG8_BAR; PG8_MMA(0, 0, At, B0); PG8_MMA(0, 1, At, B1); PG8_BAR; PG8_SCHED;
	s_waitcnt lgkmcnt(0)
	v_mfma_f32_16x16x32_bf16 v[64:67], v[120:123], v[176:179], v[64:67]
	v_mfma_f32_16x16x32_bf16 v[60:63], v[136:139], v[176:179], v[60:63]
	v_mfma_f32_16x16x32_bf16 v[48:51], v[120:123], v[184:187], v[48:51]
	v_mfma_f32_16x16x32_bf16 v[44:47], v[136:139], v[184:187], v[44:47]
	v_mfma_f32_16x16x32_bf16 v[32:35], v[120:123], v[192:195], v[32:35]
	v_mfma_f32_16x16x32_bf16 v[28:31], v[136:139], v[192:195], v[28:31]
	v_mfma_f32_16x16x32_bf16 v[16:19], v[120:123], v[210:213], v[16:19]
	v_mfma_f32_16x16x32_bf16 v[12:15], v[136:139], v[210:213], v[12:15]
	v_mfma_f32_16x16x32_bf16 v[64:67], v[132:135], v[180:183], v[64:67]
	v_mfma_f32_16x16x32_bf16 v[60:63], v[140:143], v[180:183], v[60:63]
	v_mfma_f32_16x16x32_bf16 v[48:51], v[132:135], v[188:191], v[48:51]
	v_mfma_f32_16x16x32_bf16 v[44:47], v[140:143], v[188:191], v[44:47]
	v_mfma_f32_16x16x32_bf16 v[32:35], v[132:135], v[198:201], v[32:35]
	v_mfma_f32_16x16x32_bf16 v[28:31], v[140:143], v[198:201], v[28:31]
	v_mfma_f32_16x16x32_bf16 v[16:19], v[132:135], v[222:225], v[16:19]
	v_mfma_f32_16x16x32_bf16 v[12:15], v[140:143], v[222:225], v[12:15]
	s_setprio 0
	s_setprio 1
	v_mfma_f32_16x16x32_bf16 v[56:59], v[148:151], v[176:179], v[56:59]
	v_mfma_f32_16x16x32_bf16 v[52:55], v[168:171], v[176:179], v[52:55]
	v_mfma_f32_16x16x32_bf16 v[40:43], v[148:151], v[184:187], v[40:43]
	v_mfma_f32_16x16x32_bf16 v[36:39], v[168:171], v[184:187], v[36:39]
	v_mfma_f32_16x16x32_bf16 v[24:27], v[148:151], v[192:195], v[24:27]
	v_mfma_f32_16x16x32_bf16 v[20:23], v[168:171], v[192:195], v[20:23]
	v_mfma_f32_16x16x32_bf16 v[8:11], v[148:151], v[210:213], v[8:11]
	v_mfma_f32_16x16x32_bf16 v[2:5], v[168:171], v[210:213], v[4:7]
	v_mfma_f32_16x16x32_bf16 v[56:59], v[160:163], v[180:183], v[56:59]
	v_mfma_f32_16x16x32_bf16 v[52:55], v[172:175], v[180:183], v[52:55]
	v_mfma_f32_16x16x32_bf16 v[40:43], v[160:163], v[188:191], v[40:43]
	v_mfma_f32_16x16x32_bf16 v[36:39], v[172:175], v[188:191], v[36:39]
	v_mfma_f32_16x16x32_bf16 v[24:27], v[160:163], v[198:201], v[24:27]
	v_mfma_f32_16x16x32_bf16 v[20:23], v[172:175], v[198:201], v[20:23]
	v_mfma_f32_16x16x32_bf16 v[8:11], v[160:163], v[222:225], v[8:11]
	v_mfma_f32_16x16x32_bf16 v[2:5], v[172:175], v[222:225], v[2:5]
	s_setprio 0
	s_barrier
	s_add_i32 s48, 0, 0x18000
	v_add_u32_e32 v0, s48, v112
	s_add_i32 s49, 0, 0x1c000
	ds_read_b128 v[120:123], v0
	ds_read_b128 v[132:135], v0 offset:1024
	ds_read_b128 v[136:139], v0 offset:2048
	ds_read_b128 v[140:143], v0 offset:3072
	v_add_u32_e32 v0, s49, v112
	ds_read_b128 v[148:151], v0
	ds_read_b128 v[160:163], v0 offset:1024
	ds_read_b128 v[168:171], v0 offset:2048
	ds_read_b128 v[172:175], v0 offset:3072
	s_add_u32 s68, s84, s10
	s_addc_u32 s69, s85, s11
	s_mov_b32 m0, s87
	v_lshl_add_u64 v[6:7], s[68:69], 0, v[100:101]
	ds_read_b128 v[176:179], v113 offset:32768
	ds_read_b128 v[180:183], v113 offset:33792
	ds_read_b128 v[184:187], v113 offset:34816
	ds_read_b128 v[188:191], v113 offset:35840
	ds_read_b128 v[192:195], v113 offset:36864
	ds_read_b128 v[198:201], v113 offset:37888
	ds_read_b128 v[210:213], v113 offset:38912
	ds_read_b128 v[222:225], v113 offset:39936
	global_load_lds_dwordx4 v[6:7], off
	v_lshl_add_u64 v[6:7], s[68:69], 0, v[102:103]
	s_mov_b32 m0, s40
	s_nop 0
	global_load_lds_dwordx4 v[6:7], off
	s_waitcnt vmcnt(8)
	s_waitcnt lgkmcnt(0)
	s_setprio 1
	s_barrier
	s_waitcnt lgkmcnt(0)
	v_mfma_f32_16x16x32_bf16 v[164:167], v[120:123], v[176:179], v[164:167]
	v_mfma_f32_16x16x32_bf16 v[156:159], v[136:139], v[176:179], v[156:159]
	v_mfma_f32_16x16x32_bf16 v[128:131], v[120:123], v[184:187], v[128:131]
	v_mfma_f32_16x16x32_bf16 v[124:127], v[136:139], v[184:187], v[124:127]
	v_mfma_f32_16x16x32_bf16 v[96:99], v[120:123], v[192:195], v[96:99]
	v_mfma_f32_16x16x32_bf16 v[92:95], v[136:139], v[192:195], v[92:95]
	v_mfma_f32_16x16x32_bf16 v[80:83], v[120:123], v[210:213], v[80:83]
	v_mfma_f32_16x16x32_bf16 v[76:79], v[136:139], v[210:213], v[76:79]
	v_mfma_f32_16x16x32_bf16 v[164:167], v[132:135], v[180:183], v[164:167]
	v_mfma_f32_16x16x32_bf16 v[156:159], v[140:143], v[180:183], v[156:159]
	v_mfma_f32_16x16x32_bf16 v[128:131], v[132:135], v[188:191], v[128:131]
	v_mfma_f32_16x16x32_bf16 v[124:127], v[140:143], v[188:191], v[124:127]
	v_mfma_f32_16x16x32_bf16 v[96:99], v[132:135], v[198:201], v[96:99]
	v_mfma_f32_16x16x32_bf16 v[92:95], v[140:143], v[198:201], v[92:95]
	v_mfma_f32_16x16x32_bf16 v[80:83], v[132:135], v[222:225], v[80:83]
	v_mfma_f32_16x16x32_bf16 v[76:79], v[140:143], v[222:225], v[76:79]
	s_setprio 0
	s_setprio 1
	v_mfma_f32_16x16x32_bf16 v[152:155], v[148:151], v[176:179], v[152:155]
	v_mfma_f32_16x16x32_bf16 v[144:147], v[168:171], v[176:179], v[144:147]
	v_mfma_f32_16x16x32_bf16 v[114:117], v[148:151], v[184:187], v[114:117]
	v_mfma_f32_16x16x32_bf16 v[108:111], v[168:171], v[184:187], v[108:111]
	v_mfma_f32_16x16x32_bf16 v[88:91], v[148:151], v[192:195], v[88:91]
	v_mfma_f32_16x16x32_bf16 v[84:87], v[168:171], v[192:195], v[84:87]
	v_mfma_f32_16x16x32_bf16 v[72:75], v[148:151], v[210:213], v[72:75]
	v_mfma_f32_16x16x32_bf16 v[68:71], v[168:171], v[210:213], v[68:71]
	v_mfma_f32_16x16x32_bf16 v[152:155], v[160:163], v[180:183], v[152:155]
	v_mfma_f32_16x16x32_bf16 v[144:147], v[172:175], v[180:183], v[144:147]
	v_mfma_f32_16x16x32_bf16 v[116:119], v[160:163], v[188:191], v[114:117]
	v_mfma_f32_16x16x32_bf16 v[108:111], v[172:175], v[188:191], v[108:111]
	v_mfma_f32_16x16x32_bf16 v[88:91], v[160:163], v[198:201], v[88:91]
	v_mfma_f32_16x16x32_bf16 v[84:87], v[172:175], v[198:201], v[84:87]
	v_mfma_f32_16x16x32_bf16 v[72:75], v[160:163], v[222:225], v[72:75]
	v_mfma_f32_16x16x32_bf16 v[68:71], v[172:175], v[222:225], v[68:71]
	s_setprio 0
	s_barrier
; #define PG8_STAGE(bufoff, gbase, voff) do { _Pragma("unroll") for (int _i = 0; _i < 2; ++_i) \
;         __builtin_amdgcn_global_load_lds((const unsigned*)((const char*)(gbase) + (voff)[_i]), (PG8_LAS unsigned*)(lds + (bufoff) + ldsw + _i * 8192), 16, 0, 0); } while (0)
; #define PG8_LDA(dst, b, h) do { _Pragma("unroll") for (int m = 0; m < 4; ++m) _Pragma("unroll") for (int k = 0; k < 2; ++k) dst[m][k] = *(const PG8_LAS bf16x8*)(lds + PG8_SA(b, h) + aoff + m * 2048 + k * 1024); } while (0)
; #define PG8_MMA(ai, bj, At, Bt) do { __builtin_amdgcn_s_setprio(1); _Pragma("unroll") for (int m = 0; m < 4; ++m) _Pragma("unroll") for (int n = 0; n < 2; ++n) _Pragma("unroll") for (int k = 0; k < 2; ++k) \
;         acc[ai][bj][m][n] = __builtin_amdgcn_mfma_f32_16x16x32_bf16(Bt[n][k], At[m][k], acc[ai][bj][m][n], 0, 0, 0); __builtin_amdgcn_s_setprio(0); } while (0)
; #define PG8_WAIT_V(n) asm volatile("s_waitcnt vmcnt(" #n ")" ::: "memory")
; #define PG8_WAIT_L(n) asm volatile("s_waitcnt lgkmcnt(" #n ")" ::: "memory")
; #define PG8_BAR __builtin_amdgcn_s_barrier()
; #define PG8_SCHED __builtin_amdgcn_sched_barrier(0)
; template <class Epi, class Sched, bool ALIGN_EPI = false, bool SP2 = false, bool GRP = false>
; __device__ __forceinline__ void gemm_phase(PG8_LAS unsigned char* lds, const Gemm g, const Sched& S, const Epi& E) {
;     ...
;             PG8_LDA(At, 1, 1); PG8_STAGE(PG8_SB(1, 0), b3, voffB); PG8_STAGE(PG8_SB(1, 1), b3 + hstep, voffB); PG8_STAGE(PG8_SA(1, 0), a3, voffA);
;             PG8_WAIT_V(8); PG8_WAIT_L(0); PG8_BAR; PG8_MMA(1, 0, At, B0); PG8_MMA(1, 1, At, B1); PG8_BAR; PG8_SCHED;
	s_add_i32 s48, s48, s91
	v_lshl_add_u64 v[6:7], v[202:203], 0, s[36:37]
	s_mov_b32 m0, s48
	ds_read_b128 v[176:179], v113 offset:49152
	ds_read_b128 v[180:183], v113 offset:50176
	ds_read_b128 v[184:187], v113 offset:51200
	ds_read_b128 v[188:191], v113 offset:52224
	ds_read_b128 v[192:195], v113 offset:53248
	ds_read_b128 v[198:201], v113 offset:54272
	ds_read_b128 v[210:213], v113 offset:55296
	ds_read_b128 v[222:225], v113 offset:56320
	global_load_lds_dwordx4 v[6:7], off
	v_lshl_add_u64 v[6:7], v[214:215], 0, s[36:37]
	s_add_i32 m0, s48, 0x2000
	s_add_i32 s48, s49, s91
	global_load_lds_dwordx4 v[6:7], off
	v_lshl_add_u64 v[6:7], v[218:219], 0, s[36:37]
	s_mov_b32 m0, s48
	s_nop 0
	global_load_lds_dwordx4 v[6:7], off
	v_lshl_add_u64 v[6:7], v[226:227], 0, s[36:37]
	s_add_i32 m0, s48, 0x2000
	s_nop 0
	global_load_lds_dwordx4 v[6:7], off
	v_lshl_add_u64 v[6:7], v[228:229], 0, s[36:37]
	s_mov_b32 m0, s42
	s_nop 0
	global_load_lds_dwordx4 v[6:7], off
	v_lshl_add_u64 v[6:7], v[230:231], 0, s[36:37]
	s_mov_b32 m0, s43
	s_nop 0
	global_load_lds_dwordx4 v[6:7], off
	s_waitcnt vmcnt(8)
	s_waitcnt lgkmcnt(0)
	s_setprio 1
	s_barrier
	s_waitcnt lgkmcnt(0)
	v_mfma_f32_16x16x32_bf16 v[64:67], v[120:123], v[176:179], v[64:67]
	v_mfma_f32_16x16x32_bf16 v[60:63], v[136:139], v[176:179], v[60:63]
	v_mfma_f32_16x16x32_bf16 v[48:51], v[120:123], v[184:187], v[48:51]
	v_mfma_f32_16x16x32_bf16 v[44:47], v[136:139], v[184:187], v[44:47]
	v_mfma_f32_16x16x32_bf16 v[32:35], v[120:123], v[192:195], v[32:35]
	v_mfma_f32_16x16x32_bf16 v[28:31], v[136:139], v[192:195], v[28:31]
	v_mfma_f32_16x16x32_bf16 v[16:19], v[120:123], v[210:213], v[16:19]
	v_mfma_f32_16x16x32_bf16 v[12:15], v[136:139], v[210:213], v[12:15]
	v_mfma_f32_16x16x32_bf16 v[64:67], v[132:135], v[180:183], v[64:67]
	v_mfma_f32_16x16x32_bf16 v[60:63], v[140:143], v[180:183], v[60:63]
	v_mfma_f32_16x16x32_bf16 v[48:51], v[132:135], v[188:191], v[48:51]
	v_mfma_f32_16x16x32_bf16 v[44:47], v[140:143], v[188:191], v[44:47]
	v_mfma_f32_16x16x32_bf16 v[32:35], v[132:135], v[198:201], v[32:35]
	v_mfma_f32_16x16x32_bf16 v[28:31], v[140:143], v[198:201], v[28:31]
	v_mfma_f32_16x16x32_bf16 v[16:19], v[132:135], v[222:225], v[16:19]
	v_mfma_f32_16x16x32_bf16 v[12:15], v[140:143], v[222:225], v[12:15]
	s_setprio 0
	s_setprio 1
	v_mfma_f32_16x16x32_bf16 v[56:59], v[148:151], v[176:179], v[56:59]
	v_mfma_f32_16x16x32_bf16 v[52:55], v[168:171], v[176:179], v[52:55]
	v_mfma_f32_16x16x32_bf16 v[40:43], v[148:151], v[184:187], v[40:43]
	v_mfma_f32_16x16x32_bf16 v[36:39], v[168:171], v[184:187], v[36:39]
	v_mfma_f32_16x16x32_bf16 v[24:27], v[148:151], v[192:195], v[24:27]
	v_mfma_f32_16x16x32_bf16 v[20:23], v[168:171], v[192:195], v[20:23]
	v_mfma_f32_16x16x32_bf16 v[6:9], v[148:151], v[210:213], v[8:11]
	v_mfma_f32_16x16x32_bf16 v[2:5], v[168:171], v[210:213], v[2:5]
	v_mfma_f32_16x16x32_bf16 v[56:59], v[160:163], v[180:183], v[56:59]
	v_mfma_f32_16x16x32_bf16 v[52:55], v[172:175], v[180:183], v[52:55]
	v_mfma_f32_16x16x32_bf16 v[40:43], v[160:163], v[188:191], v[40:43]
	v_mfma_f32_16x16x32_bf16 v[36:39], v[172:175], v[188:191], v[36:39]
	v_mfma_f32_16x16x32_bf16 v[24:27], v[160:163], v[198:201], v[24:27]
	v_mfma_f32_16x16x32_bf16 v[20:23], v[172:175], v[198:201], v[20:23]
	v_mfma_f32_16x16x32_bf16 v[8:11], v[160:163], v[222:225], v[6:9]
	v_mfma_f32_16x16x32_bf16 v[4:7], v[172:175], v[222:225], v[2:5]
	s_setprio 0
	s_barrier
	s_add_u32 s82, s82, 0x100
	s_addc_u32 s83, s83, 0
	s_add_u32 s55, s55, 0x100
	s_addc_u32 s96, s96, 0
	s_cmp_ge_i32 vcc_lo, s66
	s_mov_b32 s84, vcc_lo
	s_cbranch_scc0 .LBB0_886

; #define PG8_STAGE(bufoff, gbase, voff) do { _Pragma("unroll") for (int _i = 0; _i < 2; ++_i) \
;         __builtin_amdgcn_global_load_lds((const unsigned*)((const char*)(gbase) + (voff)[_i]), (PG8_LAS unsigned*)(lds + (bufoff) + ldsw + _i * 8192), 16, 0, 0); } while (0)
; #define PG8_LDA(dst, b, h) do { _Pragma("unroll") for (int m = 0; m < 4; ++m) _Pragma("unroll") for (int k = 0; k < 2; ++k) dst[m][k] = *(const PG8_LAS bf16x8*)(lds + PG8_SA(b, h) + aoff + m * 2048 + k * 1024); } while (0)
; #define PG8_LDB(dst, b, h) do { _Pragma("unroll") for (int n = 0; n < 2; ++n) _Pragma("unroll") for (int k = 0; k < 2; ++k) dst[n][k] = *(const PG8_LAS bf16x8*)(lds + PG8_SB(b, h) + boff + n * 2048 + k * 1024); } while (0)
; #define PG8_MMA(ai, bj, At, Bt) do { __builtin_amdgcn_s_setprio(1); _Pragma("unroll") for (int m = 0; m < 4; ++m) _Pragma("unroll") for (int n = 0; n < 2; ++n) _Pragma("unroll") for (int k = 0; k < 2; ++k) \
;         acc[ai][bj][m][n] = __builtin_amdgcn_mfma_f32_16x16x32_bf16(Bt[n][k], At[m][k], acc[ai][bj][m][n], 0, 0, 0); __builtin_amdgcn_s_setprio(0); } while (0)
; #define PG8_WAIT_V(n) asm volatile("s_waitcnt vmcnt(" #n ")" ::: "memory")
; #define PG8_WAIT_L(n) asm volatile("s_waitcnt lgkmcnt(" #n ")" ::: "memory")
; template <class Epi, class Sched, bool ALIGN_EPI = false, bool SP2 = false, bool GRP = false>
; __device__ __forceinline__ void gemm_phase(PG8_LAS unsigned char* lds, const Gemm g, const Sched& S, const Epi& E) {
;     ...
;             const bool last = (t == nt - 2);
;             const char* a1 = cA + (size_t)(t + 1) * kstep;
;             const char* a2 = last ? nA : cA + (size_t)(t + 2) * kstep; const char* b2 = last ? nB : cB + (size_t)(t + 2) * kstep;
;             const char* a3 = a2 + kstep; const char* b3 = b2 + kstep;
;             if (last && has_next) S.a_ready(nxt);
;             if constexpr (SP2) {
;             PG8_LDB(B0, 0, 0); PG8_LDB(B1, 0, 1); PG8_SCHED; PG8_LDA(At, 0, 0); PG8_STAGE(PG8_SA(1, 1), a1 + hstep, voffA);
;             PG8_WAIT_V(8); PG8_WAIT_L(0); PG8_BAR; PG8_MMA(0, 0, At, B0); PG8_MMA(0, 1, At, B1); PG8_BAR; PG8_SCHED;
;             PG8_LDA(At, 0, 1); PG8_STAGE(PG8_SB(0, 0), b2, voffB); PG8_STAGE(PG8_SB(0, 1), b2 + hstep, voffB); PG8_STAGE(PG8_SA(0, 0), a2, voffA);
;             PG8_WAIT_V(8); PG8_WAIT_L(0); PG8_BAR; PG8_MMA(1, 0, At, B0); PG8_MMA(1, 1, At, B1); PG8_BAR; PG8_SCHED;
.LBB0_1021:
	s_add_i32 s30, s3, 2
	s_add_u32 s28, s26, 0x80
	s_addc_u32 s29, s27, 0
	s_add_i32 s48, 0, 0x10000
	s_cmp_eq_u32 s71, s3
	s_cselect_b32 s29, s7, s29
	s_cselect_b32 s28, s6, s28
	v_add_u32_e32 v140, s48, v143
	s_cselect_b32 s43, s23, s41
	s_cselect_b32 s42, s22, s40
	s_add_i32 s3, 0, 0x14000
	ds_read_b128 v[146:149], v140
	ds_read_b128 v[150:153], v140 offset:1024
	ds_read_b128 v[154:157], v140 offset:2048
	ds_read_b128 v[158:161], v140 offset:3072
	v_add_u32_e32 v140, s3, v143
	ds_read_b128 v[162:165], v140
	ds_read_b128 v[166:169], v140 offset:1024
	ds_read_b128 v[170:173], v140 offset:2048
	ds_read_b128 v[174:177], v140 offset:3072
	v_lshl_add_u64 v[140:141], s[26:27], 0, v[136:137]
	s_add_i32 m0, s61, 0xc000
	ds_read_b128 v[178:181], v145
	ds_read_b128 v[182:185], v145 offset:1024
	ds_read_b128 v[186:189], v145 offset:2048
	ds_read_b128 v[190:193], v145 offset:3072
	ds_read_b128 v[194:197], v145 offset:4096
	ds_read_b128 v[198:201], v145 offset:5120
	ds_read_b128 v[210:213], v145 offset:6144
	ds_read_b128 v[218:221], v145 offset:7168
	global_load_lds_dwordx4 v[140:141], off
	v_lshl_add_u64 v[140:141], s[26:27], 0, v[138:139]
	s_add_i32 m0, s61, 0xe000
	s_nop 0
	global_load_lds_dwordx4 v[140:141], off
	s_waitcnt vmcnt(8)
	s_waitcnt lgkmcnt(0)
	s_setprio 1
	s_barrier
	s_waitcnt lgkmcnt(0)
	v_mfma_f32_16x16x32_bf16 v[122:125], v[146:149], v[178:181], v[122:125]
	v_mfma_f32_16x16x32_bf16 v[126:129], v[154:157], v[178:181], v[126:129]
	v_mfma_f32_16x16x32_bf16 v[110:113], v[146:149], v[186:189], v[110:113]
	v_mfma_f32_16x16x32_bf16 v[106:109], v[154:157], v[186:189], v[106:109]
	v_mfma_f32_16x16x32_bf16 v[94:97], v[146:149], v[194:197], v[94:97]
	v_mfma_f32_16x16x32_bf16 v[90:93], v[154:157], v[194:197], v[90:93]
	v_mfma_f32_16x16x32_bf16 v[78:81], v[146:149], v[210:213], v[78:81]
	v_mfma_f32_16x16x32_bf16 v[74:77], v[154:157], v[210:213], v[74:77]
	v_mfma_f32_16x16x32_bf16 v[122:125], v[150:153], v[182:185], v[122:125]
	v_mfma_f32_16x16x32_bf16 v[126:129], v[158:161], v[182:185], v[126:129]
	v_mfma_f32_16x16x32_bf16 v[110:113], v[150:153], v[190:193], v[110:113]
	v_mfma_f32_16x16x32_bf16 v[106:109], v[158:161], v[190:193], v[106:109]
	v_mfma_f32_16x16x32_bf16 v[94:97], v[150:153], v[198:201], v[94:97]
	v_mfma_f32_16x16x32_bf16 v[90:93], v[158:161], v[198:201], v[90:93]
	v_mfma_f32_16x16x32_bf16 v[78:81], v[150:153], v[218:221], v[78:81]
	v_mfma_f32_16x16x32_bf16 v[74:77], v[158:161], v[218:221], v[74:77]
	s_setprio 0
	s_setprio 1
	v_mfma_f32_16x16x32_bf16 v[118:121], v[162:165], v[178:181], v[118:121]
	v_mfma_f32_16x16x32_bf16 v[114:117], v[170:173], v[178:181], v[114:117]
	v_mfma_f32_16x16x32_bf16 v[102:105], v[162:165], v[186:189], v[102:105]
	v_mfma_f32_16x16x32_bf16 v[98:101], v[170:173], v[186:189], v[98:101]
	v_mfma_f32_16x16x32_bf16 v[86:89], v[162:165], v[194:197], v[86:89]
	v_mfma_f32_16x16x32_bf16 v[82:85], v[170:173], v[194:197], v[82:85]
	v_mfma_f32_16x16x32_bf16 v[70:73], v[162:165], v[210:213], v[70:73]
	v_mfma_f32_16x16x32_bf16 v[66:69], v[170:173], v[210:213], v[66:69]
	v_mfma_f32_16x16x32_bf16 v[118:121], v[166:169], v[182:185], v[118:121]
	v_mfma_f32_16x16x32_bf16 v[114:117], v[174:177], v[182:185], v[114:117]
	v_mfma_f32_16x16x32_bf16 v[102:105], v[166:169], v[190:193], v[102:105]
	v_mfma_f32_16x16x32_bf16 v[98:101], v[174:177], v[190:193], v[98:101]
	v_mfma_f32_16x16x32_bf16 v[86:89], v[166:169], v[198:201], v[86:89]
	v_mfma_f32_16x16x32_bf16 v[82:85], v[174:177], v[198:201], v[82:85]
	v_mfma_f32_16x16x32_bf16 v[70:73], v[166:169], v[218:221], v[70:73]
	v_mfma_f32_16x16x32_bf16 v[66:69], v[174:177], v[218:221], v[66:69]
	s_setprio 0
	s_barrier
	s_add_i32 s48, s48, s60
	v_lshl_add_u64 v[140:141], s[42:43], 0, v[0:1]
	s_mov_b32 m0, s48
	ds_read_b128 v[178:181], v145 offset:16384
	ds_read_b128 v[182:185], v145 offset:17408
	ds_read_b128 v[186:189], v145 offset:18432
	ds_read_b128 v[190:193], v145 offset:19456
	ds_read_b128 v[194:197], v145 offset:20480
	ds_read_b128 v[198:201], v145 offset:21504
	ds_read_b128 v[210:213], v145 offset:22528
	ds_read_b128 v[218:221], v145 offset:23552
	global_load_lds_dwordx4 v[140:141], off
	s_add_i32 m0, s48, 0x2000
	v_lshl_add_u64 v[202:203], s[42:43], 0, v[134:135]
	s_add_u32 s42, s42, s8
	s_addc_u32 s43, s43, s9
	s_add_i32 s3, s3, s60
	global_load_lds_dwordx4 v[202:203], off
	v_lshl_add_u64 v[214:215], s[42:43], 0, v[0:1]
	s_mov_b32 m0, s3
	v_lshl_add_u64 v[222:223], s[42:43], 0, v[134:135]
	global_load_lds_dwordx4 v[214:215], off
	s_add_i32 m0, s3, 0x2000
	v_lshl_add_u64 v[224:225], s[28:29], 0, v[130:131]
	global_load_lds_dwordx4 v[222:223], off
	s_mov_b32 m0, s61
	v_lshl_add_u64 v[226:227], s[28:29], 0, v[132:133]
	global_load_lds_dwordx4 v[224:225], off
	s_mov_b32 m0, s62
	s_nop 0
	global_load_lds_dwordx4 v[226:227], off
	s_waitcnt vmcnt(8)
	s_waitcnt lgkmcnt(0)
	s_setprio 1
	s_barrier
; #define PG8_STAGE(bufoff, gbase, voff) do { _Pragma("unroll") for (int _i = 0; _i < 2; ++_i) \
;         __builtin_amdgcn_global_load_lds((const unsigned*)((const char*)(gbase) + (voff)[_i]), (PG8_LAS unsigned*)(lds + (bufoff) + ldsw + _i * 8192), 16, 0, 0); } while (0)
; #define PG8_LDA(dst, b, h) do { _Pragma("unroll") for (int m = 0; m < 4; ++m) _Pragma("unroll") for (int k = 0; k < 2; ++k) dst[m][k] = *(const PG8_LAS bf16x8*)(lds + PG8_SA(b, h) + aoff + m * 2048 + k * 1024); } while (0)
; #define PG8_LDB(dst, b, h) do { _Pragma("unroll") for (int n = 0; n < 2; ++n) _Pragma("unroll") for (int k = 0; k < 2; ++k) dst[n][k] = *(const PG8_LAS bf16x8*)(lds + PG8_SB(b, h) + boff + n * 2048 + k * 1024); } while (0)
; #define PG8_MMA(ai, bj, At, Bt) do { __builtin_amdgcn_s_setprio(1); _Pragma("unroll") for (int m = 0; m < 4; ++m) _Pragma("unroll") for (int n = 0; n < 2; ++n) _Pragma("unroll") for (int k = 0; k < 2; ++k) \
;         acc[ai][bj][m][n] = __builtin_amdgcn_mfma_f32_16x16x32_bf16(Bt[n][k], At[m][k], acc[ai][bj][m][n], 0, 0, 0); __builtin_amdgcn_s_setprio(0); } while (0)
; #define PG8_WAIT_V(n) asm volatile("s_waitcnt vmcnt(" #n ")" ::: "memory")
; #define PG8_WAIT_L(n) asm volatile("s_waitcnt lgkmcnt(" #n ")" ::: "memory")
; #define PG8_BAR __builtin_amdgcn_s_barrier()
; #define PG8_SCHED __builtin_amdgcn_sched_barrier(0)
; template <class Epi, class Sched, bool ALIGN_EPI = false, bool SP2 = false, bool GRP = false>
; __device__ __forceinline__ void gemm_phase(PG8_LAS unsigned char* lds, const Gemm g, const Sched& S, const Epi& E) {
;     ...
;             PG8_WAIT_V(8); PG8_WAIT_L(0); PG8_BAR; PG8_MMA(1, 0, At, B0); PG8_MMA(1, 1, At, B1); PG8_BAR; PG8_SCHED;
;             PG8_LDB(B0, 1, 0); PG8_LDB(B1, 1, 1); PG8_SCHED; PG8_LDA(At, 1, 0); PG8_STAGE(PG8_SA(0, 1), a2 + hstep, voffA);
;             PG8_WAIT_V(8); PG8_WAIT_L(0); PG8_BAR; PG8_MMA(0, 0, At, B0); PG8_MMA(0, 1, At, B1); PG8_BAR; PG8_SCHED;
	s_waitcnt lgkmcnt(0)
	v_mfma_f32_16x16x32_bf16 v[62:65], v[146:149], v[178:181], v[62:65]
	v_mfma_f32_16x16x32_bf16 v[58:61], v[154:157], v[178:181], v[58:61]
	v_mfma_f32_16x16x32_bf16 v[46:49], v[146:149], v[186:189], v[46:49]
	v_mfma_f32_16x16x32_bf16 v[42:45], v[154:157], v[186:189], v[42:45]
	v_mfma_f32_16x16x32_bf16 v[30:33], v[146:149], v[194:197], v[30:33]
	v_mfma_f32_16x16x32_bf16 v[26:29], v[154:157], v[194:197], v[26:29]
	v_mfma_f32_16x16x32_bf16 v[14:17], v[146:149], v[210:213], v[14:17]
	v_mfma_f32_16x16x32_bf16 v[10:13], v[154:157], v[210:213], v[10:13]
	v_mfma_f32_16x16x32_bf16 v[62:65], v[150:153], v[182:185], v[62:65]
	v_mfma_f32_16x16x32_bf16 v[58:61], v[158:161], v[182:185], v[58:61]
	v_mfma_f32_16x16x32_bf16 v[46:49], v[150:153], v[190:193], v[46:49]
	v_mfma_f32_16x16x32_bf16 v[42:45], v[158:161], v[190:193], v[42:45]
	v_mfma_f32_16x16x32_bf16 v[30:33], v[150:153], v[198:201], v[30:33]
	v_mfma_f32_16x16x32_bf16 v[26:29], v[158:161], v[198:201], v[26:29]
	v_mfma_f32_16x16x32_bf16 v[14:17], v[150:153], v[218:221], v[14:17]
	v_mfma_f32_16x16x32_bf16 v[10:13], v[158:161], v[218:221], v[10:13]
	s_setprio 0
	s_setprio 1
	v_mfma_f32_16x16x32_bf16 v[54:57], v[162:165], v[178:181], v[54:57]
	v_mfma_f32_16x16x32_bf16 v[50:53], v[170:173], v[178:181], v[50:53]
	v_mfma_f32_16x16x32_bf16 v[38:41], v[162:165], v[186:189], v[38:41]
	v_mfma_f32_16x16x32_bf16 v[34:37], v[170:173], v[186:189], v[34:37]
	v_mfma_f32_16x16x32_bf16 v[22:25], v[162:165], v[194:197], v[22:25]
	v_mfma_f32_16x16x32_bf16 v[18:21], v[170:173], v[194:197], v[18:21]
	v_mfma_f32_16x16x32_bf16 v[6:9], v[162:165], v[210:213], v[6:9]
	v_mfma_f32_16x16x32_bf16 v[2:5], v[170:173], v[210:213], v[2:5]
	v_mfma_f32_16x16x32_bf16 v[54:57], v[166:169], v[182:185], v[54:57]
	v_mfma_f32_16x16x32_bf16 v[50:53], v[174:177], v[182:185], v[50:53]
	v_mfma_f32_16x16x32_bf16 v[38:41], v[166:169], v[190:193], v[38:41]
	v_mfma_f32_16x16x32_bf16 v[34:37], v[174:177], v[190:193], v[34:37]
	v_mfma_f32_16x16x32_bf16 v[22:25], v[166:169], v[198:201], v[22:25]
	v_mfma_f32_16x16x32_bf16 v[18:21], v[174:177], v[198:201], v[18:21]
	v_mfma_f32_16x16x32_bf16 v[6:9], v[166:169], v[218:221], v[6:9]
	v_mfma_f32_16x16x32_bf16 v[2:5], v[174:177], v[218:221], v[2:5]
	s_setprio 0
	s_barrier
	s_add_i32 s3, 0, 0x18000
	s_add_i32 s42, 0, 0x1c000
	v_add_u32_e32 v158, s3, v143
	v_add_u32_e32 v174, s42, v143
	ds_read_b128 v[146:149], v158
	ds_read_b128 v[150:153], v158 offset:1024
	ds_read_b128 v[154:157], v158 offset:2048
	ds_read_b128 v[158:161], v158 offset:3072
	ds_read_b128 v[162:165], v174
	ds_read_b128 v[166:169], v174 offset:1024
	ds_read_b128 v[170:173], v174 offset:2048
	ds_read_b128 v[174:177], v174 offset:3072
	s_add_u32 s28, s28, s8
	s_addc_u32 s29, s29, s9
	s_mov_b32 m0, s63
	v_lshl_add_u64 v[228:229], s[28:29], 0, v[130:131]
	ds_read_b128 v[178:181], v145 offset:32768
	ds_read_b128 v[182:185], v145 offset:33792
	ds_read_b128 v[186:189], v145 offset:34816
	ds_read_b128 v[190:193], v145 offset:35840
	ds_read_b128 v[194:197], v145 offset:36864
	ds_read_b128 v[198:201], v145 offset:37888
	ds_read_b128 v[210:213], v145 offset:38912
	ds_read_b128 v[218:221], v145 offset:39936
	global_load_lds_dwordx4 v[228:229], off
	v_lshl_add_u64 v[228:229], s[28:29], 0, v[132:133]
	s_mov_b32 m0, s67
	s_nop 0
	global_load_lds_dwordx4 v[228:229], off
	s_waitcnt vmcnt(8)
	s_waitcnt lgkmcnt(0)
	s_setprio 1
	s_barrier
	s_waitcnt lgkmcnt(0)
	v_mfma_f32_16x16x32_bf16 v[122:125], v[146:149], v[178:181], v[122:125]
	v_mfma_f32_16x16x32_bf16 v[126:129], v[154:157], v[178:181], v[126:129]
	v_mfma_f32_16x16x32_bf16 v[110:113], v[146:149], v[186:189], v[110:113]
	v_mfma_f32_16x16x32_bf16 v[106:109], v[154:157], v[186:189], v[106:109]
	v_mfma_f32_16x16x32_bf16 v[94:97], v[146:149], v[194:197], v[94:97]
	v_mfma_f32_16x16x32_bf16 v[90:93], v[154:157], v[194:197], v[90:93]
	v_mfma_f32_16x16x32_bf16 v[78:81], v[146:149], v[210:213], v[78:81]
	v_mfma_f32_16x16x32_bf16 v[74:77], v[154:157], v[210:213], v[74:77]
	v_mfma_f32_16x16x32_bf16 v[122:125], v[150:153], v[182:185], v[122:125]
	v_mfma_f32_16x16x32_bf16 v[126:129], v[158:161], v[182:185], v[126:129]
	v_mfma_f32_16x16x32_bf16 v[110:113], v[150:153], v[190:193], v[110:113]
	v_mfma_f32_16x16x32_bf16 v[106:109], v[158:161], v[190:193], v[106:109]
	v_mfma_f32_16x16x32_bf16 v[94:97], v[150:153], v[198:201], v[94:97]
	v_mfma_f32_16x16x32_bf16 v[90:93], v[158:161], v[198:201], v[90:93]
	v_mfma_f32_16x16x32_bf16 v[78:81], v[150:153], v[218:221], v[78:81]
	v_mfma_f32_16x16x32_bf16 v[74:77], v[158:161], v[218:221], v[74:77]
	s_setprio 0
	s_setprio 1
	v_mfma_f32_16x16x32_bf16 v[118:121], v[162:165], v[178:181], v[118:121]
	v_mfma_f32_16x16x32_bf16 v[114:117], v[170:173], v[178:181], v[114:117]
	v_mfma_f32_16x16x32_bf16 v[102:105], v[162:165], v[186:189], v[102:105]
	v_mfma_f32_16x16x32_bf16 v[98:101], v[170:173], v[186:189], v[98:101]
	v_mfma_f32_16x16x32_bf16 v[86:89], v[162:165], v[194:197], v[86:89]
	v_mfma_f32_16x16x32_bf16 v[82:85], v[170:173], v[194:197], v[82:85]
	v_mfma_f32_16x16x32_bf16 v[70:73], v[162:165], v[210:213], v[70:73]
	v_mfma_f32_16x16x32_bf16 v[66:69], v[170:173], v[210:213], v[66:69]
	v_mfma_f32_16x16x32_bf16 v[118:121], v[166:169], v[182:185], v[118:121]
	v_mfma_f32_16x16x32_bf16 v[114:117], v[174:177], v[182:185], v[114:117]
	v_mfma_f32_16x16x32_bf16 v[102:105], v[166:169], v[190:193], v[102:105]
	v_mfma_f32_16x16x32_bf16 v[98:101], v[174:177], v[190:193], v[98:101]
	v_mfma_f32_16x16x32_bf16 v[86:89], v[166:169], v[198:201], v[86:89]
	v_mfma_f32_16x16x32_bf16 v[82:85], v[174:177], v[198:201], v[82:85]
	v_mfma_f32_16x16x32_bf16 v[70:73], v[166:169], v[218:221], v[70:73]
	v_mfma_f32_16x16x32_bf16 v[66:69], v[174:177], v[218:221], v[66:69]
	s_setprio 0
	s_barrier
; #define PG8_STAGE(bufoff, gbase, voff) do { _Pragma("unroll") for (int _i = 0; _i < 2; ++_i) \
;         __builtin_amdgcn_global_load_lds((const unsigned*)((const char*)(gbase) + (voff)[_i]), (PG8_LAS unsigned*)(lds + (bufoff) + ldsw + _i * 8192), 16, 0, 0); } while (0)
; #define PG8_LDA(dst, b, h) do { _Pragma("unroll") for (int m = 0; m < 4; ++m) _Pragma("unroll") for (int k = 0; k < 2; ++k) dst[m][k] = *(const PG8_LAS bf16x8*)(lds + PG8_SA(b, h) + aoff + m * 2048 + k * 1024); } while (0)
; #define PG8_MMA(ai, bj, At, Bt) do { __builtin_amdgcn_s_setprio(1); _Pragma("unroll") for (int m = 0; m < 4; ++m) _Pragma("unroll") for (int n = 0; n < 2; ++n) _Pragma("unroll") for (int k = 0; k < 2; ++k) \
;         acc[ai][bj][m][n] = __builtin_amdgcn_mfma_f32_16x16x32_bf16(Bt[n][k], At[m][k], acc[ai][bj][m][n], 0, 0, 0); __builtin_amdgcn_s_setprio(0); } while (0)
; #define PG8_WAIT_V(n) asm volatile("s_waitcnt vmcnt(" #n ")" ::: "memory")
; #define PG8_WAIT_L(n) asm volatile("s_waitcnt lgkmcnt(" #n ")" ::: "memory")
; #define PG8_BAR __builtin_amdgcn_s_barrier()
; #define PG8_SCHED __builtin_amdgcn_sched_barrier(0)
; template <class Epi, class Sched, bool ALIGN_EPI = false, bool SP2 = false, bool GRP = false>
; __device__ __forceinline__ void gemm_phase(PG8_LAS unsigned char* lds, const Gemm g, const Sched& S, const Epi& E) {
;     ...
;             PG8_LDA(At, 1, 1); PG8_STAGE(PG8_SB(1, 0), b3, voffB); PG8_STAGE(PG8_SB(1, 1), b3 + hstep, voffB); PG8_STAGE(PG8_SA(1, 0), a3, voffA);
;             PG8_WAIT_V(8); PG8_WAIT_L(0); PG8_BAR; PG8_MMA(1, 0, At, B0); PG8_MMA(1, 1, At, B1); PG8_BAR; PG8_SCHED;
	s_add_i32 s3, s3, s60
	v_lshl_add_u64 v[140:141], v[140:141], 0, s[36:37]
	s_mov_b32 m0, s3
	ds_read_b128 v[178:181], v145 offset:49152
	ds_read_b128 v[182:185], v145 offset:50176
	ds_read_b128 v[186:189], v145 offset:51200
	ds_read_b128 v[190:193], v145 offset:52224
	ds_read_b128 v[194:197], v145 offset:53248
	ds_read_b128 v[198:201], v145 offset:54272
	ds_read_b128 v[210:213], v145 offset:55296
	ds_read_b128 v[218:221], v145 offset:56320
	global_load_lds_dwordx4 v[140:141], off
	v_lshl_add_u64 v[140:141], v[202:203], 0, s[36:37]
	s_add_i32 m0, s3, 0x2000
	s_add_i32 s3, s42, s60
	global_load_lds_dwordx4 v[140:141], off
	v_lshl_add_u64 v[140:141], v[214:215], 0, s[36:37]
	s_mov_b32 m0, s3
	s_nop 0
	global_load_lds_dwordx4 v[140:141], off
	v_lshl_add_u64 v[140:141], v[222:223], 0, s[36:37]
	s_add_i32 m0, s3, 0x2000
	s_nop 0
	global_load_lds_dwordx4 v[140:141], off
	v_lshl_add_u64 v[140:141], v[224:225], 0, s[36:37]
	s_mov_b32 m0, s68
	s_nop 0
	global_load_lds_dwordx4 v[140:141], off
	v_lshl_add_u64 v[140:141], v[226:227], 0, s[36:37]
	s_mov_b32 m0, s69
	s_nop 0
	global_load_lds_dwordx4 v[140:141], off
	s_waitcnt vmcnt(8)
	s_waitcnt lgkmcnt(0)
	s_setprio 1
	s_barrier
	s_waitcnt lgkmcnt(0)
	v_mfma_f32_16x16x32_bf16 v[62:65], v[146:149], v[178:181], v[62:65]
	v_mfma_f32_16x16x32_bf16 v[58:61], v[154:157], v[178:181], v[58:61]
	v_mfma_f32_16x16x32_bf16 v[46:49], v[146:149], v[186:189], v[46:49]
	v_mfma_f32_16x16x32_bf16 v[42:45], v[154:157], v[186:189], v[42:45]
	v_mfma_f32_16x16x32_bf16 v[30:33], v[146:149], v[194:197], v[30:33]
	v_mfma_f32_16x16x32_bf16 v[26:29], v[154:157], v[194:197], v[26:29]
	v_mfma_f32_16x16x32_bf16 v[14:17], v[146:149], v[210:213], v[14:17]
	v_mfma_f32_16x16x32_bf16 v[10:13], v[154:157], v[210:213], v[10:13]
	v_mfma_f32_16x16x32_bf16 v[62:65], v[150:153], v[182:185], v[62:65]
	v_mfma_f32_16x16x32_bf16 v[58:61], v[158:161], v[182:185], v[58:61]
	v_mfma_f32_16x16x32_bf16 v[46:49], v[150:153], v[190:193], v[46:49]
	v_mfma_f32_16x16x32_bf16 v[42:45], v[158:161], v[190:193], v[42:45]
	v_mfma_f32_16x16x32_bf16 v[30:33], v[150:153], v[198:201], v[30:33]
	v_mfma_f32_16x16x32_bf16 v[26:29], v[158:161], v[198:201], v[26:29]
	v_mfma_f32_16x16x32_bf16 v[14:17], v[150:153], v[218:221], v[14:17]
	v_mfma_f32_16x16x32_bf16 v[10:13], v[158:161], v[218:221], v[10:13]
	s_setprio 0
	s_setprio 1
	v_mfma_f32_16x16x32_bf16 v[54:57], v[162:165], v[178:181], v[54:57]
	v_mfma_f32_16x16x32_bf16 v[50:53], v[170:173], v[178:181], v[50:53]
	v_mfma_f32_16x16x32_bf16 v[38:41], v[162:165], v[186:189], v[38:41]
	v_mfma_f32_16x16x32_bf16 v[34:37], v[170:173], v[186:189], v[34:37]
	v_mfma_f32_16x16x32_bf16 v[22:25], v[162:165], v[194:197], v[22:25]
	v_mfma_f32_16x16x32_bf16 v[18:21], v[170:173], v[194:197], v[18:21]
	v_mfma_f32_16x16x32_bf16 v[6:9], v[162:165], v[210:213], v[6:9]
	v_mfma_f32_16x16x32_bf16 v[2:5], v[170:173], v[210:213], v[2:5]
	v_mfma_f32_16x16x32_bf16 v[54:57], v[166:169], v[182:185], v[54:57]
	v_mfma_f32_16x16x32_bf16 v[50:53], v[174:177], v[182:185], v[50:53]
	v_mfma_f32_16x16x32_bf16 v[38:41], v[166:169], v[190:193], v[38:41]
	v_mfma_f32_16x16x32_bf16 v[34:37], v[174:177], v[190:193], v[34:37]
	v_mfma_f32_16x16x32_bf16 v[22:25], v[166:169], v[198:201], v[22:25]
	v_mfma_f32_16x16x32_bf16 v[18:21], v[174:177], v[198:201], v[18:21]
	v_mfma_f32_16x16x32_bf16 v[6:9], v[166:169], v[218:221], v[6:9]
	v_mfma_f32_16x16x32_bf16 v[2:5], v[174:177], v[218:221], v[2:5]
	s_setprio 0
	s_barrier
	s_add_u32 s26, s26, 0x100
	s_addc_u32 s27, s27, 0
	s_add_u32 s40, s40, 0x100
	s_addc_u32 s41, s41, 0
	s_cmp_ge_i32 s30, s70
	s_mov_b32 s3, s30
	s_cbranch_scc0 .LBB0_1021

; #define PG8_STAGE(bufoff, gbase, voff) do { _Pragma("unroll") for (int _i = 0; _i < 2; ++_i) \
;         __builtin_amdgcn_global_load_lds((const unsigned*)((const char*)(gbase) + (voff)[_i]), (PG8_LAS unsigned*)(lds + (bufoff) + ldsw + _i * 8192), 16, 0, 0); } while (0)
; #define PG8_LDA(dst, b, h) do { _Pragma("unroll") for (int m = 0; m < 4; ++m) _Pragma("unroll") for (int k = 0; k < 2; ++k) dst[m][k] = *(const PG8_LAS bf16x8*)(lds + PG8_SA(b, h) + aoff + m * 2048 + k * 1024); } while (0)
; #define PG8_LDB(dst, b, h) do { _Pragma("unroll") for (int n = 0; n < 2; ++n) _Pragma("unroll") for (int k = 0; k < 2; ++k) dst[n][k] = *(const PG8_LAS bf16x8*)(lds + PG8_SB(b, h) + boff + n * 2048 + k * 1024); } while (0)
; #define PG8_MMA(ai, bj, At, Bt) do { __builtin_amdgcn_s_setprio(1); _Pragma("unroll") for (int m = 0; m < 4; ++m) _Pragma("unroll") for (int n = 0; n < 2; ++n) _Pragma("unroll") for (int k = 0; k < 2; ++k) \
;         acc[ai][bj][m][n] = __builtin_amdgcn_mfma_f32_16x16x32_bf16(Bt[n][k], At[m][k], acc[ai][bj][m][n], 0, 0, 0); __builtin_amdgcn_s_setprio(0); } while (0)
; #define PG8_WAIT_V(n) asm volatile("s_waitcnt vmcnt(" #n ")" ::: "memory")
; #define PG8_WAIT_L(n) asm volatile("s_waitcnt lgkmcnt(" #n ")" ::: "memory")
; template <class Epi, class Sched, bool ALIGN_EPI = false, bool SP2 = false, bool GRP = false>
; __device__ __forceinline__ void gemm_phase(PG8_LAS unsigned char* lds, const Gemm g, const Sched& S, const Epi& E) {
;     ...
;             const bool last = (t == nt - 2);
;             const char* a1 = cA + (size_t)(t + 1) * kstep;
;             const char* a2 = last ? nA : cA + (size_t)(t + 2) * kstep; const char* b2 = last ? nB : cB + (size_t)(t + 2) * kstep;
;             const char* a3 = a2 + kstep; const char* b3 = b2 + kstep;
;             if (last && has_next) S.a_ready(nxt);
;             if constexpr (SP2) {
;             PG8_LDB(B0, 0, 0); PG8_LDB(B1, 0, 1); PG8_SCHED; PG8_LDA(At, 0, 0); PG8_STAGE(PG8_SA(1, 1), a1 + hstep, voffA);
;             PG8_WAIT_V(8); PG8_WAIT_L(0); PG8_BAR; PG8_MMA(0, 0, At, B0); PG8_MMA(0, 1, At, B1); PG8_BAR; PG8_SCHED;
;             PG8_LDA(At, 0, 1); PG8_STAGE(PG8_SB(0, 0), b2, voffB); PG8_STAGE(PG8_SB(0, 1), b2 + hstep, voffB); PG8_STAGE(PG8_SA(0, 0), a2, voffA);
;             PG8_WAIT_V(8); PG8_WAIT_L(0); PG8_BAR; PG8_MMA(1, 0, At, B0); PG8_MMA(1, 1, At, B1); PG8_BAR; PG8_SCHED;
.LBB0_1105:
	s_add_i32 s94, s84, 2
	s_add_u32 s48, s82, 0x80
	s_addc_u32 s49, s83, 0
	s_add_i32 s56, 0, 0x10000
	s_cmp_eq_u32 s3, s84
	s_cselect_b32 s85, s9, s49
	s_cselect_b32 s84, s8, s48
	v_add_u32_e32 v0, s56, v140
	s_cselect_b32 s49, s81, vcc_hi
	s_cselect_b32 s48, s80, vcc_lo
	s_add_i32 s89, 0, 0x14000
	ds_read_b128 v[142:145], v0
	ds_read_b128 v[146:149], v0 offset:1024
	ds_read_b128 v[150:153], v0 offset:2048
	ds_read_b128 v[154:157], v0 offset:3072
	v_add_u32_e32 v0, s89, v140
	ds_read_b128 v[158:161], v0
	ds_read_b128 v[162:165], v0 offset:1024
	ds_read_b128 v[166:169], v0 offset:2048
	ds_read_b128 v[170:173], v0 offset:3072
	v_lshl_add_u64 v[2:3], s[82:83], 0, v[136:137]
	s_add_i32 m0, s57, 0xc000
	ds_read_b128 v[174:177], v141
	ds_read_b128 v[178:181], v141 offset:1024
	ds_read_b128 v[182:185], v141 offset:2048
	ds_read_b128 v[190:193], v141 offset:3072
	ds_read_b128 v[194:197], v141 offset:4096
	ds_read_b128 v[198:201], v141 offset:5120
	ds_read_b128 v[210:213], v141 offset:6144
	ds_read_b128 v[218:221], v141 offset:7168
	global_load_lds_dwordx4 v[2:3], off
	v_lshl_add_u64 v[2:3], s[82:83], 0, v[138:139]
	s_add_i32 m0, s57, 0xe000
	s_nop 0
	global_load_lds_dwordx4 v[2:3], off
	s_waitcnt vmcnt(8)
	s_waitcnt lgkmcnt(0)
	s_setprio 1
	s_barrier
	s_waitcnt lgkmcnt(0)
	v_mfma_f32_16x16x32_bf16 v[128:131], v[142:145], v[174:177], v[128:131]
	v_mfma_f32_16x16x32_bf16 v[124:127], v[150:153], v[174:177], v[124:127]
	v_mfma_f32_16x16x32_bf16 v[112:115], v[142:145], v[182:185], v[112:115]
	v_mfma_f32_16x16x32_bf16 v[108:111], v[150:153], v[182:185], v[108:111]
	v_mfma_f32_16x16x32_bf16 v[96:99], v[142:145], v[194:197], v[96:99]
	v_mfma_f32_16x16x32_bf16 v[92:95], v[150:153], v[194:197], v[92:95]
	v_mfma_f32_16x16x32_bf16 v[80:83], v[142:145], v[210:213], v[80:83]
	v_mfma_f32_16x16x32_bf16 v[76:79], v[150:153], v[210:213], v[76:79]
	v_mfma_f32_16x16x32_bf16 v[128:131], v[146:149], v[178:181], v[128:131]
	v_mfma_f32_16x16x32_bf16 v[124:127], v[154:157], v[178:181], v[124:127]
	v_mfma_f32_16x16x32_bf16 v[112:115], v[146:149], v[190:193], v[112:115]
	v_mfma_f32_16x16x32_bf16 v[108:111], v[154:157], v[190:193], v[108:111]
	v_mfma_f32_16x16x32_bf16 v[96:99], v[146:149], v[198:201], v[96:99]
	v_mfma_f32_16x16x32_bf16 v[92:95], v[154:157], v[198:201], v[92:95]
	v_mfma_f32_16x16x32_bf16 v[80:83], v[146:149], v[218:221], v[80:83]
	v_mfma_f32_16x16x32_bf16 v[76:79], v[154:157], v[218:221], v[76:79]
	s_setprio 0
	s_setprio 1
	v_mfma_f32_16x16x32_bf16 v[120:123], v[158:161], v[174:177], v[120:123]
	v_mfma_f32_16x16x32_bf16 v[116:119], v[166:169], v[174:177], v[116:119]
	v_mfma_f32_16x16x32_bf16 v[104:107], v[158:161], v[182:185], v[104:107]
	v_mfma_f32_16x16x32_bf16 v[100:103], v[166:169], v[182:185], v[100:103]
	v_mfma_f32_16x16x32_bf16 v[88:91], v[158:161], v[194:197], v[88:91]
	v_mfma_f32_16x16x32_bf16 v[84:87], v[166:169], v[194:197], v[84:87]
	v_mfma_f32_16x16x32_bf16 v[72:75], v[158:161], v[210:213], v[72:75]
	v_mfma_f32_16x16x32_bf16 v[68:71], v[166:169], v[210:213], v[68:71]
	v_mfma_f32_16x16x32_bf16 v[120:123], v[162:165], v[178:181], v[120:123]
	v_mfma_f32_16x16x32_bf16 v[116:119], v[170:173], v[178:181], v[116:119]
	v_mfma_f32_16x16x32_bf16 v[104:107], v[162:165], v[190:193], v[104:107]
	v_mfma_f32_16x16x32_bf16 v[100:103], v[170:173], v[190:193], v[100:103]
	v_mfma_f32_16x16x32_bf16 v[88:91], v[162:165], v[198:201], v[88:91]
	v_mfma_f32_16x16x32_bf16 v[84:87], v[170:173], v[198:201], v[84:87]
	v_mfma_f32_16x16x32_bf16 v[72:75], v[162:165], v[218:221], v[72:75]
	v_mfma_f32_16x16x32_bf16 v[68:71], v[170:173], v[218:221], v[68:71]
	s_setprio 0
	s_barrier
	s_add_i32 s56, s56, s91
	v_lshl_add_u64 v[202:203], s[48:49], 0, v[132:133]
	s_mov_b32 m0, s56
	ds_read_b128 v[174:177], v141 offset:16384
	ds_read_b128 v[178:181], v141 offset:17408
	ds_read_b128 v[182:185], v141 offset:18432
	ds_read_b128 v[190:193], v141 offset:19456
	ds_read_b128 v[194:197], v141 offset:20480
	ds_read_b128 v[198:201], v141 offset:21504
	ds_read_b128 v[210:213], v141 offset:22528
	ds_read_b128 v[218:221], v141 offset:23552
	global_load_lds_dwordx4 v[202:203], off
	s_add_i32 m0, s56, 0x2000
	v_lshl_add_u64 v[214:215], s[48:49], 0, v[134:135]
	s_add_u32 s48, s48, s10
	s_addc_u32 s49, s49, s11
	s_add_i32 s56, s89, s91
	global_load_lds_dwordx4 v[214:215], off
	v_lshl_add_u64 v[222:223], s[48:49], 0, v[132:133]
	s_mov_b32 m0, s56
	v_lshl_add_u64 v[224:225], s[48:49], 0, v[134:135]
	global_load_lds_dwordx4 v[222:223], off
	s_add_i32 m0, s56, 0x2000
	v_lshl_add_u64 v[226:227], s[84:85], 0, v[132:133]
	global_load_lds_dwordx4 v[224:225], off
	s_mov_b32 m0, s57
	v_lshl_add_u64 v[228:229], s[84:85], 0, v[134:135]
	global_load_lds_dwordx4 v[226:227], off
	s_mov_b32 m0, s86
	s_nop 0
	global_load_lds_dwordx4 v[228:229], off
	s_waitcnt vmcnt(8)
	s_waitcnt lgkmcnt(0)
	s_setprio 1
	s_barrier
; #define PG8_STAGE(bufoff, gbase, voff) do { _Pragma("unroll") for (int _i = 0; _i < 2; ++_i) \
;         __builtin_amdgcn_global_load_lds((const unsigned*)((const char*)(gbase) + (voff)[_i]), (PG8_LAS unsigned*)(lds + (bufoff) + ldsw + _i * 8192), 16, 0, 0); } while (0)
; #define PG8_LDA(dst, b, h) do { _Pragma("unroll") for (int m = 0; m < 4; ++m) _Pragma("unroll") for (int k = 0; k < 2; ++k) dst[m][k] = *(const PG8_LAS bf16x8*)(lds + PG8_SA(b, h) + aoff + m * 2048 + k * 1024); } while (0)
; #define PG8_LDB(dst, b, h) do { _Pragma("unroll") for (int n = 0; n < 2; ++n) _Pragma("unroll") for (int k = 0; k < 2; ++k) dst[n][k] = *(const PG8_LAS bf16x8*)(lds + PG8_SB(b, h) + boff + n * 2048 + k * 1024); } while (0)
; #define PG8_MMA(ai, bj, At, Bt) do { __builtin_amdgcn_s_setprio(1); _Pragma("unroll") for (int m = 0; m < 4; ++m) _Pragma("unroll") for (int n = 0; n < 2; ++n) _Pragma("unroll") for (int k = 0; k < 2; ++k) \
;         acc[ai][bj][m][n] = __builtin_amdgcn_mfma_f32_16x16x32_bf16(Bt[n][k], At[m][k], acc[ai][bj][m][n], 0, 0, 0); __builtin_amdgcn_s_setprio(0); } while (0)
; #define PG8_WAIT_V(n) asm volatile("s_waitcnt vmcnt(" #n ")" ::: "memory")
; #define PG8_WAIT_L(n) asm volatile("s_waitcnt lgkmcnt(" #n ")" ::: "memory")
; #define PG8_BAR __builtin_amdgcn_s_barrier()
; #define PG8_SCHED __builtin_amdgcn_sched_barrier(0)
; template <class Epi, class Sched, bool ALIGN_EPI = false, bool SP2 = false, bool GRP = false>
; __device__ __forceinline__ void gemm_phase(PG8_LAS unsigned char* lds, const Gemm g, const Sched& S, const Epi& E) {
;     ...
;             PG8_WAIT_V(8); PG8_WAIT_L(0); PG8_BAR; PG8_MMA(1, 0, At, B0); PG8_MMA(1, 1, At, B1); PG8_BAR; PG8_SCHED;
;             PG8_LDB(B0, 1, 0); PG8_LDB(B1, 1, 1); PG8_SCHED; PG8_LDA(At, 1, 0); PG8_STAGE(PG8_SA(0, 1), a2 + hstep, voffA);
;             PG8_WAIT_V(8); PG8_WAIT_L(0); PG8_BAR; PG8_MMA(0, 0, At, B0); PG8_MMA(0, 1, At, B1); PG8_BAR; PG8_SCHED;
	s_waitcnt lgkmcnt(0)
	v_mfma_f32_16x16x32_bf16 v[64:67], v[142:145], v[174:177], v[64:67]
	v_mfma_f32_16x16x32_bf16 v[60:63], v[150:153], v[174:177], v[60:63]
	v_mfma_f32_16x16x32_bf16 v[48:51], v[142:145], v[182:185], v[48:51]
	v_mfma_f32_16x16x32_bf16 v[44:47], v[150:153], v[182:185], v[44:47]
	v_mfma_f32_16x16x32_bf16 v[32:35], v[142:145], v[194:197], v[32:35]
	v_mfma_f32_16x16x32_bf16 v[28:31], v[150:153], v[194:197], v[28:31]
	v_mfma_f32_16x16x32_bf16 v[16:19], v[142:145], v[210:213], v[16:19]
	v_mfma_f32_16x16x32_bf16 v[12:15], v[150:153], v[210:213], v[12:15]
	v_mfma_f32_16x16x32_bf16 v[64:67], v[146:149], v[178:181], v[64:67]
	v_mfma_f32_16x16x32_bf16 v[60:63], v[154:157], v[178:181], v[60:63]
	v_mfma_f32_16x16x32_bf16 v[48:51], v[146:149], v[190:193], v[48:51]
	v_mfma_f32_16x16x32_bf16 v[44:47], v[154:157], v[190:193], v[44:47]
	v_mfma_f32_16x16x32_bf16 v[32:35], v[146:149], v[198:201], v[32:35]
	v_mfma_f32_16x16x32_bf16 v[28:31], v[154:157], v[198:201], v[28:31]
	v_mfma_f32_16x16x32_bf16 v[16:19], v[146:149], v[218:221], v[16:19]
	v_mfma_f32_16x16x32_bf16 v[12:15], v[154:157], v[218:221], v[12:15]
	s_setprio 0
	s_setprio 1
	v_mfma_f32_16x16x32_bf16 v[56:59], v[158:161], v[174:177], v[56:59]
	v_mfma_f32_16x16x32_bf16 v[52:55], v[166:169], v[174:177], v[52:55]
	v_mfma_f32_16x16x32_bf16 v[40:43], v[158:161], v[182:185], v[40:43]
	v_mfma_f32_16x16x32_bf16 v[36:39], v[166:169], v[182:185], v[36:39]
	v_mfma_f32_16x16x32_bf16 v[24:27], v[158:161], v[194:197], v[24:27]
	v_mfma_f32_16x16x32_bf16 v[20:23], v[166:169], v[194:197], v[20:23]
	v_mfma_f32_16x16x32_bf16 v[8:11], v[158:161], v[210:213], v[8:11]
	v_mfma_f32_16x16x32_bf16 v[2:5], v[166:169], v[210:213], v[4:7]
	v_mfma_f32_16x16x32_bf16 v[56:59], v[162:165], v[178:181], v[56:59]
	v_mfma_f32_16x16x32_bf16 v[52:55], v[170:173], v[178:181], v[52:55]
	v_mfma_f32_16x16x32_bf16 v[40:43], v[162:165], v[190:193], v[40:43]
	v_mfma_f32_16x16x32_bf16 v[36:39], v[170:173], v[190:193], v[36:39]
	v_mfma_f32_16x16x32_bf16 v[24:27], v[162:165], v[198:201], v[24:27]
	v_mfma_f32_16x16x32_bf16 v[20:23], v[170:173], v[198:201], v[20:23]
	v_mfma_f32_16x16x32_bf16 v[8:11], v[162:165], v[218:221], v[8:11]
	v_mfma_f32_16x16x32_bf16 v[2:5], v[170:173], v[218:221], v[2:5]
	s_setprio 0
	s_barrier
	s_add_i32 s56, 0, 0x18000
	v_add_u32_e32 v0, s56, v140
	s_add_i32 s89, 0, 0x1c000
	ds_read_b128 v[142:145], v0
	ds_read_b128 v[146:149], v0 offset:1024
	ds_read_b128 v[150:153], v0 offset:2048
	ds_read_b128 v[154:157], v0 offset:3072
	v_add_u32_e32 v0, s89, v140
	ds_read_b128 v[158:161], v0
	ds_read_b128 v[162:165], v0 offset:1024
	ds_read_b128 v[166:169], v0 offset:2048
	ds_read_b128 v[170:173], v0 offset:3072
	s_add_u32 s48, s84, s10
	s_addc_u32 s49, s85, s11
	s_mov_b32 m0, s87
	v_lshl_add_u64 v[6:7], s[48:49], 0, v[132:133]
	ds_read_b128 v[174:177], v141 offset:32768
	ds_read_b128 v[178:181], v141 offset:33792
	ds_read_b128 v[182:185], v141 offset:34816
	ds_read_b128 v[190:193], v141 offset:35840
	ds_read_b128 v[194:197], v141 offset:36864
	ds_read_b128 v[198:201], v141 offset:37888
	ds_read_b128 v[210:213], v141 offset:38912
	ds_read_b128 v[218:221], v141 offset:39936
	global_load_lds_dwordx4 v[6:7], off
	v_lshl_add_u64 v[6:7], s[48:49], 0, v[134:135]
	s_mov_b32 m0, s40
	s_nop 0
	global_load_lds_dwordx4 v[6:7], off
	s_waitcnt vmcnt(8)
	s_waitcnt lgkmcnt(0)
	s_setprio 1
	s_barrier
	s_waitcnt lgkmcnt(0)
	v_mfma_f32_16x16x32_bf16 v[128:131], v[142:145], v[174:177], v[128:131]
	v_mfma_f32_16x16x32_bf16 v[124:127], v[150:153], v[174:177], v[124:127]
	v_mfma_f32_16x16x32_bf16 v[112:115], v[142:145], v[182:185], v[112:115]
	v_mfma_f32_16x16x32_bf16 v[108:111], v[150:153], v[182:185], v[108:111]
	v_mfma_f32_16x16x32_bf16 v[96:99], v[142:145], v[194:197], v[96:99]
	v_mfma_f32_16x16x32_bf16 v[92:95], v[150:153], v[194:197], v[92:95]
	v_mfma_f32_16x16x32_bf16 v[80:83], v[142:145], v[210:213], v[80:83]
	v_mfma_f32_16x16x32_bf16 v[76:79], v[150:153], v[210:213], v[76:79]
	v_mfma_f32_16x16x32_bf16 v[128:131], v[146:149], v[178:181], v[128:131]
	v_mfma_f32_16x16x32_bf16 v[124:127], v[154:157], v[178:181], v[124:127]
	v_mfma_f32_16x16x32_bf16 v[112:115], v[146:149], v[190:193], v[112:115]
	v_mfma_f32_16x16x32_bf16 v[108:111], v[154:157], v[190:193], v[108:111]
	v_mfma_f32_16x16x32_bf16 v[96:99], v[146:149], v[198:201], v[96:99]
	v_mfma_f32_16x16x32_bf16 v[92:95], v[154:157], v[198:201], v[92:95]
	v_mfma_f32_16x16x32_bf16 v[80:83], v[146:149], v[218:221], v[80:83]
	v_mfma_f32_16x16x32_bf16 v[76:79], v[154:157], v[218:221], v[76:79]
	s_setprio 0
	s_setprio 1
	v_mfma_f32_16x16x32_bf16 v[120:123], v[158:161], v[174:177], v[120:123]
	v_mfma_f32_16x16x32_bf16 v[116:119], v[166:169], v[174:177], v[116:119]
	v_mfma_f32_16x16x32_bf16 v[104:107], v[158:161], v[182:185], v[104:107]
	v_mfma_f32_16x16x32_bf16 v[100:103], v[166:169], v[182:185], v[100:103]
	v_mfma_f32_16x16x32_bf16 v[88:91], v[158:161], v[194:197], v[88:91]
	v_mfma_f32_16x16x32_bf16 v[84:87], v[166:169], v[194:197], v[84:87]
	v_mfma_f32_16x16x32_bf16 v[72:75], v[158:161], v[210:213], v[72:75]
	v_mfma_f32_16x16x32_bf16 v[68:71], v[166:169], v[210:213], v[68:71]
	v_mfma_f32_16x16x32_bf16 v[120:123], v[162:165], v[178:181], v[120:123]
	v_mfma_f32_16x16x32_bf16 v[116:119], v[170:173], v[178:181], v[116:119]
	v_mfma_f32_16x16x32_bf16 v[104:107], v[162:165], v[190:193], v[104:107]
	v_mfma_f32_16x16x32_bf16 v[100:103], v[170:173], v[190:193], v[100:103]
	v_mfma_f32_16x16x32_bf16 v[88:91], v[162:165], v[198:201], v[88:91]
	v_mfma_f32_16x16x32_bf16 v[84:87], v[170:173], v[198:201], v[84:87]
	v_mfma_f32_16x16x32_bf16 v[72:75], v[162:165], v[218:221], v[72:75]
	v_mfma_f32_16x16x32_bf16 v[68:71], v[170:173], v[218:221], v[68:71]
	s_setprio 0
	s_barrier
; #define PG8_STAGE(bufoff, gbase, voff) do { _Pragma("unroll") for (int _i = 0; _i < 2; ++_i) \
;         __builtin_amdgcn_global_load_lds((const unsigned*)((const char*)(gbase) + (voff)[_i]), (PG8_LAS unsigned*)(lds + (bufoff) + ldsw + _i * 8192), 16, 0, 0); } while (0)
; #define PG8_LDA(dst, b, h) do { _Pragma("unroll") for (int m = 0; m < 4; ++m) _Pragma("unroll") for (int k = 0; k < 2; ++k) dst[m][k] = *(const PG8_LAS bf16x8*)(lds + PG8_SA(b, h) + aoff + m * 2048 + k * 1024); } while (0)
; #define PG8_MMA(ai, bj, At, Bt) do { __builtin_amdgcn_s_setprio(1); _Pragma("unroll") for (int m = 0; m < 4; ++m) _Pragma("unroll") for (int n = 0; n < 2; ++n) _Pragma("unroll") for (int k = 0; k < 2; ++k) \
;         acc[ai][bj][m][n] = __builtin_amdgcn_mfma_f32_16x16x32_bf16(Bt[n][k], At[m][k], acc[ai][bj][m][n], 0, 0, 0); __builtin_amdgcn_s_setprio(0); } while (0)
; #define PG8_WAIT_V(n) asm volatile("s_waitcnt vmcnt(" #n ")" ::: "memory")
; #define PG8_WAIT_L(n) asm volatile("s_waitcnt lgkmcnt(" #n ")" ::: "memory")
; #define PG8_BAR __builtin_amdgcn_s_barrier()
; #define PG8_SCHED __builtin_amdgcn_sched_barrier(0)
; template <class Epi, class Sched, bool ALIGN_EPI = false, bool SP2 = false, bool GRP = false>
; __device__ __forceinline__ void gemm_phase(PG8_LAS unsigned char* lds, const Gemm g, const Sched& S, const Epi& E) {
;     ...
;         for (int t = 0; t < nt; t += 2) {
;     ...
;             PG8_LDA(At, 1, 1); PG8_STAGE(PG8_SB(1, 0), b3, voffB); PG8_STAGE(PG8_SB(1, 1), b3 + hstep, voffB); PG8_STAGE(PG8_SA(1, 0), a3, voffA);
;             PG8_WAIT_V(8); PG8_WAIT_L(0); PG8_BAR; PG8_MMA(1, 0, At, B0); PG8_MMA(1, 1, At, B1); PG8_BAR; PG8_SCHED;
	s_add_i32 s48, s56, s91
	v_lshl_add_u64 v[6:7], v[202:203], 0, s[36:37]
	s_mov_b32 m0, s48
	ds_read_b128 v[174:177], v141 offset:49152
	ds_read_b128 v[178:181], v141 offset:50176
	ds_read_b128 v[182:185], v141 offset:51200
	ds_read_b128 v[190:193], v141 offset:52224
	ds_read_b128 v[194:197], v141 offset:53248
	ds_read_b128 v[198:201], v141 offset:54272
	ds_read_b128 v[210:213], v141 offset:55296
	ds_read_b128 v[218:221], v141 offset:56320
	global_load_lds_dwordx4 v[6:7], off
	v_lshl_add_u64 v[6:7], v[214:215], 0, s[36:37]
	s_add_i32 m0, s48, 0x2000
	s_add_i32 s48, s89, s91
	global_load_lds_dwordx4 v[6:7], off
	v_lshl_add_u64 v[6:7], v[222:223], 0, s[36:37]
	s_mov_b32 m0, s48
	s_nop 0
	global_load_lds_dwordx4 v[6:7], off
	v_lshl_add_u64 v[6:7], v[224:225], 0, s[36:37]
	s_add_i32 m0, s48, 0x2000
	s_nop 0
	global_load_lds_dwordx4 v[6:7], off
	v_lshl_add_u64 v[6:7], v[226:227], 0, s[36:37]
	s_mov_b32 m0, s42
	s_nop 0
	global_load_lds_dwordx4 v[6:7], off
	v_lshl_add_u64 v[6:7], v[228:229], 0, s[36:37]
	s_mov_b32 m0, s43
	s_nop 0
	global_load_lds_dwordx4 v[6:7], off
	s_waitcnt vmcnt(8)
	s_waitcnt lgkmcnt(0)
	s_setprio 1
	s_barrier
	s_waitcnt lgkmcnt(0)
	v_mfma_f32_16x16x32_bf16 v[64:67], v[142:145], v[174:177], v[64:67]
	v_mfma_f32_16x16x32_bf16 v[60:63], v[150:153], v[174:177], v[60:63]
	v_mfma_f32_16x16x32_bf16 v[48:51], v[142:145], v[182:185], v[48:51]
	v_mfma_f32_16x16x32_bf16 v[44:47], v[150:153], v[182:185], v[44:47]
	v_mfma_f32_16x16x32_bf16 v[32:35], v[142:145], v[194:197], v[32:35]
	v_mfma_f32_16x16x32_bf16 v[28:31], v[150:153], v[194:197], v[28:31]
	v_mfma_f32_16x16x32_bf16 v[16:19], v[142:145], v[210:213], v[16:19]
	v_mfma_f32_16x16x32_bf16 v[12:15], v[150:153], v[210:213], v[12:15]
	v_mfma_f32_16x16x32_bf16 v[64:67], v[146:149], v[178:181], v[64:67]
	v_mfma_f32_16x16x32_bf16 v[60:63], v[154:157], v[178:181], v[60:63]
	v_mfma_f32_16x16x32_bf16 v[48:51], v[146:149], v[190:193], v[48:51]
	v_mfma_f32_16x16x32_bf16 v[44:47], v[154:157], v[190:193], v[44:47]
	v_mfma_f32_16x16x32_bf16 v[32:35], v[146:149], v[198:201], v[32:35]
	v_mfma_f32_16x16x32_bf16 v[28:31], v[154:157], v[198:201], v[28:31]
	v_mfma_f32_16x16x32_bf16 v[16:19], v[146:149], v[218:221], v[16:19]
	v_mfma_f32_16x16x32_bf16 v[12:15], v[154:157], v[218:221], v[12:15]
	s_setprio 0
	s_setprio 1
	v_mfma_f32_16x16x32_bf16 v[56:59], v[158:161], v[174:177], v[56:59]
	v_mfma_f32_16x16x32_bf16 v[52:55], v[166:169], v[174:177], v[52:55]
	v_mfma_f32_16x16x32_bf16 v[40:43], v[158:161], v[182:185], v[40:43]
	v_mfma_f32_16x16x32_bf16 v[36:39], v[166:169], v[182:185], v[36:39]
	v_mfma_f32_16x16x32_bf16 v[24:27], v[158:161], v[194:197], v[24:27]
	v_mfma_f32_16x16x32_bf16 v[20:23], v[166:169], v[194:197], v[20:23]
	v_mfma_f32_16x16x32_bf16 v[6:9], v[158:161], v[210:213], v[8:11]
	v_mfma_f32_16x16x32_bf16 v[2:5], v[166:169], v[210:213], v[2:5]
	v_mfma_f32_16x16x32_bf16 v[56:59], v[162:165], v[178:181], v[56:59]
	v_mfma_f32_16x16x32_bf16 v[52:55], v[170:173], v[178:181], v[52:55]
	v_mfma_f32_16x16x32_bf16 v[40:43], v[162:165], v[190:193], v[40:43]
	v_mfma_f32_16x16x32_bf16 v[36:39], v[170:173], v[190:193], v[36:39]
	v_mfma_f32_16x16x32_bf16 v[24:27], v[162:165], v[198:201], v[24:27]
	v_mfma_f32_16x16x32_bf16 v[20:23], v[170:173], v[198:201], v[20:23]
	v_mfma_f32_16x16x32_bf16 v[8:11], v[162:165], v[218:221], v[6:9]
	v_mfma_f32_16x16x32_bf16 v[4:7], v[170:173], v[218:221], v[2:5]
	s_setprio 0
	s_barrier
	s_add_u32 s82, s82, 0x100
	s_addc_u32 s83, s83, 0
	s_add_u32 vcc_lo, vcc_lo, 0x100
	s_addc_u32 vcc_hi, vcc_hi, 0
	s_cmp_ge_i32 s94, s96
	s_mov_b32 s84, s94
	s_cbranch_scc0 .LBB0_1105

; #define PG8_STAGE(bufoff, gbase, voff) do { _Pragma("unroll") for (int _i = 0; _i < 2; ++_i) \
;         __builtin_amdgcn_global_load_lds((const unsigned*)((const char*)(gbase) + (voff)[_i]), (PG8_LAS unsigned*)(lds + (bufoff) + ldsw + _i * 8192), 16, 0, 0); } while (0)
; #define PG8_LDA(dst, b, h) do { _Pragma("unroll") for (int m = 0; m < 4; ++m) _Pragma("unroll") for (int k = 0; k < 2; ++k) dst[m][k] = *(const PG8_LAS bf16x8*)(lds + PG8_SA(b, h) + aoff + m * 2048 + k * 1024); } while (0)
; #define PG8_LDB(dst, b, h) do { _Pragma("unroll") for (int n = 0; n < 2; ++n) _Pragma("unroll") for (int k = 0; k < 2; ++k) dst[n][k] = *(const PG8_LAS bf16x8*)(lds + PG8_SB(b, h) + boff + n * 2048 + k * 1024); } while (0)
; #define PG8_WAIT_V(n) asm volatile("s_waitcnt vmcnt(" #n ")" ::: "memory")
; #define PG8_WAIT_L(n) asm volatile("s_waitcnt lgkmcnt(" #n ")" ::: "memory")
; #define PG8_BAR __builtin_amdgcn_s_barrier()
; template <class Epi, class Sched, bool ALIGN_EPI = false, bool SP2 = false, bool GRP = false>
; __device__ __forceinline__ void gemm_phase(PG8_LAS unsigned char* lds, const Gemm g, const Sched& S, const Epi& E) {
;     ...
;         const bool has_next = S.next(ui + 1, nxt);
;         const char* nA = has_next ? (const char*)g.A + (size_t)nxt.pm * tstep : cA; const char* nB = has_next ? (const char*)g.Bt + (size_t)nxt.pn * tstep + (GRP ? (size_t)(nxt.pm >> 3) * g.bgs : (size_t)0) : cB;
;         for (int t = 0; t < nt; t += 2) {
;             const bool last = (t == nt - 2);
;             const char* a1 = cA + (size_t)(t + 1) * kstep;
;             const char* a2 = last ? nA : cA + (size_t)(t + 2) * kstep; const char* b2 = last ? nB : cB + (size_t)(t + 2) * kstep;
;             const char* a3 = a2 + kstep; const char* b3 = b2 + kstep;
;             if (last && has_next) S.a_ready(nxt);
;             if constexpr (SP2) {
;             PG8_LDB(B0, 0, 0); PG8_LDB(B1, 0, 1); PG8_SCHED; PG8_LDA(At, 0, 0); PG8_STAGE(PG8_SA(1, 1), a1 + hstep, voffA);
;             PG8_WAIT_V(8); PG8_WAIT_L(0); PG8_BAR; PG8_MMA(0, 0, At, B0); PG8_MMA(0, 1, At, B1); PG8_BAR; PG8_SCHED;
;             PG8_LDA(At, 0, 1); PG8_STAGE(PG8_SB(0, 0), b2, voffB); PG8_STAGE(PG8_SB(0, 1), b2 + hstep, voffB); PG8_STAGE(PG8_SA(0, 0), a2, voffA);
;             PG8_WAIT_V(8); PG8_WAIT_L(0); PG8_BAR; PG8_MMA(1, 0, At, B0); PG8_MMA(1, 1, At, B1); PG8_BAR; PG8_SCHED;
.LBB0_1190:
	s_add_i32 s94, s84, 2
	s_add_u32 s48, s82, 0x80
	s_addc_u32 s49, s83, 0
	s_add_i32 s56, 0, 0x10000
	s_cmp_eq_u32 s96, s84
	s_cselect_b32 s85, s9, s49
	s_cselect_b32 s84, s8, s48
	v_add_u32_e32 v0, s56, v140
	s_cselect_b32 s49, s81, vcc_hi
	s_cselect_b32 s48, s80, vcc_lo
	s_add_i32 s89, 0, 0x14000
	ds_read_b128 v[142:145], v0
	ds_read_b128 v[146:149], v0 offset:1024
	ds_read_b128 v[150:153], v0 offset:2048
	ds_read_b128 v[154:157], v0 offset:3072
	v_add_u32_e32 v0, s89, v140
	ds_read_b128 v[158:161], v0
	ds_read_b128 v[162:165], v0 offset:1024
	ds_read_b128 v[166:169], v0 offset:2048
	ds_read_b128 v[170:173], v0 offset:3072
	v_lshl_add_u64 v[2:3], s[82:83], 0, v[136:137]
	s_add_i32 m0, s57, 0xc000
	ds_read_b128 v[174:177], v141
	ds_read_b128 v[178:181], v141 offset:1024
	ds_read_b128 v[182:185], v141 offset:2048
	ds_read_b128 v[186:189], v141 offset:3072
	ds_read_b128 v[196:199], v141 offset:4096
	ds_read_b128 v[200:203], v141 offset:5120
	ds_read_b128 v[210:213], v141 offset:6144
	ds_read_b128 v[218:221], v141 offset:7168
	global_load_lds_dwordx4 v[2:3], off
	v_lshl_add_u64 v[2:3], s[82:83], 0, v[138:139]
	s_add_i32 m0, s57, 0xe000
	s_nop 0
	global_load_lds_dwordx4 v[2:3], off
	s_waitcnt vmcnt(8)
	s_waitcnt lgkmcnt(0)
	s_setprio 1
	s_barrier
	s_waitcnt lgkmcnt(0)
	v_mfma_f32_16x16x32_bf16 v[128:131], v[142:145], v[174:177], v[128:131]
	v_mfma_f32_16x16x32_bf16 v[124:127], v[150:153], v[174:177], v[124:127]
	v_mfma_f32_16x16x32_bf16 v[112:115], v[142:145], v[182:185], v[112:115]
	v_mfma_f32_16x16x32_bf16 v[108:111], v[150:153], v[182:185], v[108:111]
	v_mfma_f32_16x16x32_bf16 v[96:99], v[142:145], v[196:199], v[96:99]
	v_mfma_f32_16x16x32_bf16 v[92:95], v[150:153], v[196:199], v[92:95]
	v_mfma_f32_16x16x32_bf16 v[80:83], v[142:145], v[210:213], v[80:83]
	v_mfma_f32_16x16x32_bf16 v[76:79], v[150:153], v[210:213], v[76:79]
	v_mfma_f32_16x16x32_bf16 v[128:131], v[146:149], v[178:181], v[128:131]
	v_mfma_f32_16x16x32_bf16 v[124:127], v[154:157], v[178:181], v[124:127]
	v_mfma_f32_16x16x32_bf16 v[112:115], v[146:149], v[186:189], v[112:115]
	v_mfma_f32_16x16x32_bf16 v[108:111], v[154:157], v[186:189], v[108:111]
	v_mfma_f32_16x16x32_bf16 v[96:99], v[146:149], v[200:203], v[96:99]
	v_mfma_f32_16x16x32_bf16 v[92:95], v[154:157], v[200:203], v[92:95]
	v_mfma_f32_16x16x32_bf16 v[80:83], v[146:149], v[218:221], v[80:83]
	v_mfma_f32_16x16x32_bf16 v[76:79], v[154:157], v[218:221], v[76:79]
	s_setprio 0
	s_setprio 1
	v_mfma_f32_16x16x32_bf16 v[120:123], v[158:161], v[174:177], v[120:123]
	v_mfma_f32_16x16x32_bf16 v[116:119], v[166:169], v[174:177], v[116:119]
	v_mfma_f32_16x16x32_bf16 v[104:107], v[158:161], v[182:185], v[104:107]
	v_mfma_f32_16x16x32_bf16 v[100:103], v[166:169], v[182:185], v[100:103]
	v_mfma_f32_16x16x32_bf16 v[88:91], v[158:161], v[196:199], v[88:91]
	v_mfma_f32_16x16x32_bf16 v[84:87], v[166:169], v[196:199], v[84:87]
	v_mfma_f32_16x16x32_bf16 v[72:75], v[158:161], v[210:213], v[72:75]
	v_mfma_f32_16x16x32_bf16 v[68:71], v[166:169], v[210:213], v[68:71]
	v_mfma_f32_16x16x32_bf16 v[120:123], v[162:165], v[178:181], v[120:123]
	v_mfma_f32_16x16x32_bf16 v[116:119], v[170:173], v[178:181], v[116:119]
	v_mfma_f32_16x16x32_bf16 v[104:107], v[162:165], v[186:189], v[104:107]
	v_mfma_f32_16x16x32_bf16 v[100:103], v[170:173], v[186:189], v[100:103]
	v_mfma_f32_16x16x32_bf16 v[88:91], v[162:165], v[200:203], v[88:91]
	v_mfma_f32_16x16x32_bf16 v[84:87], v[170:173], v[200:203], v[84:87]
	v_mfma_f32_16x16x32_bf16 v[72:75], v[162:165], v[218:221], v[72:75]
	v_mfma_f32_16x16x32_bf16 v[68:71], v[170:173], v[218:221], v[68:71]
	s_setprio 0
	s_barrier
	s_add_i32 s56, s56, s91
	v_lshl_add_u64 v[190:191], s[48:49], 0, v[132:133]
	s_mov_b32 m0, s56
	ds_read_b128 v[174:177], v141 offset:16384
	ds_read_b128 v[178:181], v141 offset:17408
	ds_read_b128 v[182:185], v141 offset:18432
	ds_read_b128 v[186:189], v141 offset:19456
	ds_read_b128 v[196:199], v141 offset:20480
	ds_read_b128 v[200:203], v141 offset:21504
	ds_read_b128 v[210:213], v141 offset:22528
	ds_read_b128 v[218:221], v141 offset:23552
	global_load_lds_dwordx4 v[190:191], off
	s_add_i32 m0, s56, 0x2000
	v_lshl_add_u64 v[214:215], s[48:49], 0, v[134:135]
	s_add_u32 s48, s48, s70
	s_addc_u32 s49, s49, s71
	s_add_i32 s56, s89, s91
	global_load_lds_dwordx4 v[214:215], off
	v_lshl_add_u64 v[222:223], s[48:49], 0, v[132:133]
	s_mov_b32 m0, s56
	v_lshl_add_u64 v[224:225], s[48:49], 0, v[134:135]
	global_load_lds_dwordx4 v[222:223], off
	s_add_i32 m0, s56, 0x2000
	v_lshl_add_u64 v[226:227], s[84:85], 0, v[132:133]
	global_load_lds_dwordx4 v[224:225], off
	s_mov_b32 m0, s57
	v_lshl_add_u64 v[228:229], s[84:85], 0, v[134:135]
	global_load_lds_dwordx4 v[226:227], off
	s_mov_b32 m0, s86
	s_nop 0
	global_load_lds_dwordx4 v[228:229], off
	s_waitcnt vmcnt(8)
	s_waitcnt lgkmcnt(0)
	s_setprio 1
	s_barrier
; #define PG8_STAGE(bufoff, gbase, voff) do { _Pragma("unroll") for (int _i = 0; _i < 2; ++_i) \
;         __builtin_amdgcn_global_load_lds((const unsigned*)((const char*)(gbase) + (voff)[_i]), (PG8_LAS unsigned*)(lds + (bufoff) + ldsw + _i * 8192), 16, 0, 0); } while (0)
; #define PG8_LDA(dst, b, h) do { _Pragma("unroll") for (int m = 0; m < 4; ++m) _Pragma("unroll") for (int k = 0; k < 2; ++k) dst[m][k] = *(const PG8_LAS bf16x8*)(lds + PG8_SA(b, h) + aoff + m * 2048 + k * 1024); } while (0)
; #define PG8_LDB(dst, b, h) do { _Pragma("unroll") for (int n = 0; n < 2; ++n) _Pragma("unroll") for (int k = 0; k < 2; ++k) dst[n][k] = *(const PG8_LAS bf16x8*)(lds + PG8_SB(b, h) + boff + n * 2048 + k * 1024); } while (0)
; #define PG8_MMA(ai, bj, At, Bt) do { __builtin_amdgcn_s_setprio(1); _Pragma("unroll") for (int m = 0; m < 4; ++m) _Pragma("unroll") for (int n = 0; n < 2; ++n) _Pragma("unroll") for (int k = 0; k < 2; ++k) \
;         acc[ai][bj][m][n] = __builtin_amdgcn_mfma_f32_16x16x32_bf16(Bt[n][k], At[m][k], acc[ai][bj][m][n], 0, 0, 0); __builtin_amdgcn_s_setprio(0); } while (0)
; #define PG8_WAIT_V(n) asm volatile("s_waitcnt vmcnt(" #n ")" ::: "memory")
; #define PG8_WAIT_L(n) asm volatile("s_waitcnt lgkmcnt(" #n ")" ::: "memory")
; #define PG8_BAR __builtin_amdgcn_s_barrier()
; #define PG8_SCHED __builtin_amdgcn_sched_barrier(0)
; template <class Epi, class Sched, bool ALIGN_EPI = false, bool SP2 = false, bool GRP = false>
; __device__ __forceinline__ void gemm_phase(PG8_LAS unsigned char* lds, const Gemm g, const Sched& S, const Epi& E) {
;     ...
;             PG8_WAIT_V(8); PG8_WAIT_L(0); PG8_BAR; PG8_MMA(1, 0, At, B0); PG8_MMA(1, 1, At, B1); PG8_BAR; PG8_SCHED;
;             PG8_LDB(B0, 1, 0); PG8_LDB(B1, 1, 1); PG8_SCHED; PG8_LDA(At, 1, 0); PG8_STAGE(PG8_SA(0, 1), a2 + hstep, voffA);
;             PG8_WAIT_V(8); PG8_WAIT_L(0); PG8_BAR; PG8_MMA(0, 0, At, B0); PG8_MMA(0, 1, At, B1); PG8_BAR; PG8_SCHED;
	s_waitcnt lgkmcnt(0)
	v_mfma_f32_16x16x32_bf16 v[64:67], v[142:145], v[174:177], v[64:67]
	v_mfma_f32_16x16x32_bf16 v[60:63], v[150:153], v[174:177], v[60:63]
	v_mfma_f32_16x16x32_bf16 v[48:51], v[142:145], v[182:185], v[48:51]
	v_mfma_f32_16x16x32_bf16 v[44:47], v[150:153], v[182:185], v[44:47]
	v_mfma_f32_16x16x32_bf16 v[32:35], v[142:145], v[196:199], v[32:35]
	v_mfma_f32_16x16x32_bf16 v[28:31], v[150:153], v[196:199], v[28:31]
	v_mfma_f32_16x16x32_bf16 v[16:19], v[142:145], v[210:213], v[16:19]
	v_mfma_f32_16x16x32_bf16 v[12:15], v[150:153], v[210:213], v[12:15]
	v_mfma_f32_16x16x32_bf16 v[64:67], v[146:149], v[178:181], v[64:67]
	v_mfma_f32_16x16x32_bf16 v[60:63], v[154:157], v[178:181], v[60:63]
	v_mfma_f32_16x16x32_bf16 v[48:51], v[146:149], v[186:189], v[48:51]
	v_mfma_f32_16x16x32_bf16 v[44:47], v[154:157], v[186:189], v[44:47]
	v_mfma_f32_16x16x32_bf16 v[32:35], v[146:149], v[200:203], v[32:35]
	v_mfma_f32_16x16x32_bf16 v[28:31], v[154:157], v[200:203], v[28:31]
	v_mfma_f32_16x16x32_bf16 v[16:19], v[146:149], v[218:221], v[16:19]
	v_mfma_f32_16x16x32_bf16 v[12:15], v[154:157], v[218:221], v[12:15]
	s_setprio 0
	s_setprio 1
	v_mfma_f32_16x16x32_bf16 v[56:59], v[158:161], v[174:177], v[56:59]
	v_mfma_f32_16x16x32_bf16 v[52:55], v[166:169], v[174:177], v[52:55]
	v_mfma_f32_16x16x32_bf16 v[40:43], v[158:161], v[182:185], v[40:43]
	v_mfma_f32_16x16x32_bf16 v[36:39], v[166:169], v[182:185], v[36:39]
	v_mfma_f32_16x16x32_bf16 v[24:27], v[158:161], v[196:199], v[24:27]
	v_mfma_f32_16x16x32_bf16 v[20:23], v[166:169], v[196:199], v[20:23]
	v_mfma_f32_16x16x32_bf16 v[8:11], v[158:161], v[210:213], v[8:11]
	v_mfma_f32_16x16x32_bf16 v[2:5], v[166:169], v[210:213], v[4:7]
	v_mfma_f32_16x16x32_bf16 v[56:59], v[162:165], v[178:181], v[56:59]
	v_mfma_f32_16x16x32_bf16 v[52:55], v[170:173], v[178:181], v[52:55]
	v_mfma_f32_16x16x32_bf16 v[40:43], v[162:165], v[186:189], v[40:43]
	v_mfma_f32_16x16x32_bf16 v[36:39], v[170:173], v[186:189], v[36:39]
	v_mfma_f32_16x16x32_bf16 v[24:27], v[162:165], v[200:203], v[24:27]
	v_mfma_f32_16x16x32_bf16 v[20:23], v[170:173], v[200:203], v[20:23]
	v_mfma_f32_16x16x32_bf16 v[8:11], v[162:165], v[218:221], v[8:11]
	v_mfma_f32_16x16x32_bf16 v[2:5], v[170:173], v[218:221], v[2:5]
	s_setprio 0
	s_barrier
	s_add_i32 s56, 0, 0x18000
	v_add_u32_e32 v0, s56, v140
	s_add_i32 s89, 0, 0x1c000
	ds_read_b128 v[142:145], v0
	ds_read_b128 v[146:149], v0 offset:1024
	ds_read_b128 v[150:153], v0 offset:2048
	ds_read_b128 v[154:157], v0 offset:3072
	v_add_u32_e32 v0, s89, v140
	ds_read_b128 v[158:161], v0
	ds_read_b128 v[162:165], v0 offset:1024
	ds_read_b128 v[166:169], v0 offset:2048
	ds_read_b128 v[170:173], v0 offset:3072
	s_add_u32 s48, s84, s70
	s_addc_u32 s49, s85, s71
	s_mov_b32 m0, s87
	v_lshl_add_u64 v[6:7], s[48:49], 0, v[132:133]
	ds_read_b128 v[174:177], v141 offset:32768
	ds_read_b128 v[178:181], v141 offset:33792
	ds_read_b128 v[182:185], v141 offset:34816
	ds_read_b128 v[186:189], v141 offset:35840
	ds_read_b128 v[196:199], v141 offset:36864
	ds_read_b128 v[200:203], v141 offset:37888
	ds_read_b128 v[210:213], v141 offset:38912
	ds_read_b128 v[218:221], v141 offset:39936
	global_load_lds_dwordx4 v[6:7], off
	v_lshl_add_u64 v[6:7], s[48:49], 0, v[134:135]
	s_mov_b32 m0, s40
	s_nop 0
	global_load_lds_dwordx4 v[6:7], off
	s_waitcnt vmcnt(8)
	s_waitcnt lgkmcnt(0)
	s_setprio 1
	s_barrier
	s_waitcnt lgkmcnt(0)
	v_mfma_f32_16x16x32_bf16 v[128:131], v[142:145], v[174:177], v[128:131]
	v_mfma_f32_16x16x32_bf16 v[124:127], v[150:153], v[174:177], v[124:127]
	v_mfma_f32_16x16x32_bf16 v[112:115], v[142:145], v[182:185], v[112:115]
	v_mfma_f32_16x16x32_bf16 v[108:111], v[150:153], v[182:185], v[108:111]
	v_mfma_f32_16x16x32_bf16 v[96:99], v[142:145], v[196:199], v[96:99]
	v_mfma_f32_16x16x32_bf16 v[92:95], v[150:153], v[196:199], v[92:95]
	v_mfma_f32_16x16x32_bf16 v[80:83], v[142:145], v[210:213], v[80:83]
	v_mfma_f32_16x16x32_bf16 v[76:79], v[150:153], v[210:213], v[76:79]
	v_mfma_f32_16x16x32_bf16 v[128:131], v[146:149], v[178:181], v[128:131]
	v_mfma_f32_16x16x32_bf16 v[124:127], v[154:157], v[178:181], v[124:127]
	v_mfma_f32_16x16x32_bf16 v[112:115], v[146:149], v[186:189], v[112:115]
	v_mfma_f32_16x16x32_bf16 v[108:111], v[154:157], v[186:189], v[108:111]
	v_mfma_f32_16x16x32_bf16 v[96:99], v[146:149], v[200:203], v[96:99]
	v_mfma_f32_16x16x32_bf16 v[92:95], v[154:157], v[200:203], v[92:95]
	v_mfma_f32_16x16x32_bf16 v[80:83], v[146:149], v[218:221], v[80:83]
	v_mfma_f32_16x16x32_bf16 v[76:79], v[154:157], v[218:221], v[76:79]
	s_setprio 0
	s_setprio 1
	v_mfma_f32_16x16x32_bf16 v[120:123], v[158:161], v[174:177], v[120:123]
	v_mfma_f32_16x16x32_bf16 v[116:119], v[166:169], v[174:177], v[116:119]
	v_mfma_f32_16x16x32_bf16 v[104:107], v[158:161], v[182:185], v[104:107]
	v_mfma_f32_16x16x32_bf16 v[100:103], v[166:169], v[182:185], v[100:103]
	v_mfma_f32_16x16x32_bf16 v[88:91], v[158:161], v[196:199], v[88:91]
	v_mfma_f32_16x16x32_bf16 v[84:87], v[166:169], v[196:199], v[84:87]
	v_mfma_f32_16x16x32_bf16 v[72:75], v[158:161], v[210:213], v[72:75]
	v_mfma_f32_16x16x32_bf16 v[68:71], v[166:169], v[210:213], v[68:71]
	v_mfma_f32_16x16x32_bf16 v[120:123], v[162:165], v[178:181], v[120:123]
	v_mfma_f32_16x16x32_bf16 v[116:119], v[170:173], v[178:181], v[116:119]
	v_mfma_f32_16x16x32_bf16 v[104:107], v[162:165], v[186:189], v[104:107]
	v_mfma_f32_16x16x32_bf16 v[100:103], v[170:173], v[186:189], v[100:103]
	v_mfma_f32_16x16x32_bf16 v[88:91], v[162:165], v[200:203], v[88:91]
	v_mfma_f32_16x16x32_bf16 v[84:87], v[170:173], v[200:203], v[84:87]
	v_mfma_f32_16x16x32_bf16 v[72:75], v[162:165], v[218:221], v[72:75]
	v_mfma_f32_16x16x32_bf16 v[68:71], v[170:173], v[218:221], v[68:71]
	s_setprio 0
	s_barrier
; #define PG8_STAGE(bufoff, gbase, voff) do { _Pragma("unroll") for (int _i = 0; _i < 2; ++_i) \
;         __builtin_amdgcn_global_load_lds((const unsigned*)((const char*)(gbase) + (voff)[_i]), (PG8_LAS unsigned*)(lds + (bufoff) + ldsw + _i * 8192), 16, 0, 0); } while (0)
; #define PG8_LDA(dst, b, h) do { _Pragma("unroll") for (int m = 0; m < 4; ++m) _Pragma("unroll") for (int k = 0; k < 2; ++k) dst[m][k] = *(const PG8_LAS bf16x8*)(lds + PG8_SA(b, h) + aoff + m * 2048 + k * 1024); } while (0)
; #define PG8_MMA(ai, bj, At, Bt) do { __builtin_amdgcn_s_setprio(1); _Pragma("unroll") for (int m = 0; m < 4; ++m) _Pragma("unroll") for (int n = 0; n < 2; ++n) _Pragma("unroll") for (int k = 0; k < 2; ++k) \
;         acc[ai][bj][m][n] = __builtin_amdgcn_mfma_f32_16x16x32_bf16(Bt[n][k], At[m][k], acc[ai][bj][m][n], 0, 0, 0); __builtin_amdgcn_s_setprio(0); } while (0)
; #define PG8_WAIT_V(n) asm volatile("s_waitcnt vmcnt(" #n ")" ::: "memory")
; #define PG8_WAIT_L(n) asm volatile("s_waitcnt lgkmcnt(" #n ")" ::: "memory")
; #define PG8_BAR __builtin_amdgcn_s_barrier()
; #define PG8_SCHED __builtin_amdgcn_sched_barrier(0)
; template <class Epi, class Sched, bool ALIGN_EPI = false, bool SP2 = false, bool GRP = false>
; __device__ __forceinline__ void gemm_phase(PG8_LAS unsigned char* lds, const Gemm g, const Sched& S, const Epi& E) {
;     ...
;         for (int t = 0; t < nt; t += 2) {
;     ...
;             PG8_LDA(At, 1, 1); PG8_STAGE(PG8_SB(1, 0), b3, voffB); PG8_STAGE(PG8_SB(1, 1), b3 + hstep, voffB); PG8_STAGE(PG8_SA(1, 0), a3, voffA);
;             PG8_WAIT_V(8); PG8_WAIT_L(0); PG8_BAR; PG8_MMA(1, 0, At, B0); PG8_MMA(1, 1, At, B1); PG8_BAR; PG8_SCHED;
	s_add_i32 s48, s56, s91
	v_lshl_add_u64 v[6:7], v[190:191], 0, s[36:37]
	s_mov_b32 m0, s48
	ds_read_b128 v[174:177], v141 offset:49152
	ds_read_b128 v[178:181], v141 offset:50176
	ds_read_b128 v[182:185], v141 offset:51200
	ds_read_b128 v[186:189], v141 offset:52224
	ds_read_b128 v[196:199], v141 offset:53248
	ds_read_b128 v[200:203], v141 offset:54272
	ds_read_b128 v[210:213], v141 offset:55296
	ds_read_b128 v[218:221], v141 offset:56320
	global_load_lds_dwordx4 v[6:7], off
	v_lshl_add_u64 v[6:7], v[214:215], 0, s[36:37]
	s_add_i32 m0, s48, 0x2000
	s_add_i32 s48, s89, s91
	global_load_lds_dwordx4 v[6:7], off
	v_lshl_add_u64 v[6:7], v[222:223], 0, s[36:37]
	s_mov_b32 m0, s48
	s_nop 0
	global_load_lds_dwordx4 v[6:7], off
	v_lshl_add_u64 v[6:7], v[224:225], 0, s[36:37]
	s_add_i32 m0, s48, 0x2000
	s_nop 0
	global_load_lds_dwordx4 v[6:7], off
	v_lshl_add_u64 v[6:7], v[226:227], 0, s[36:37]
	s_mov_b32 m0, s42
	s_nop 0
	global_load_lds_dwordx4 v[6:7], off
	v_lshl_add_u64 v[6:7], v[228:229], 0, s[36:37]
	s_mov_b32 m0, s43
	s_nop 0
	global_load_lds_dwordx4 v[6:7], off
	s_waitcnt vmcnt(8)
	s_waitcnt lgkmcnt(0)
	s_setprio 1
	s_barrier
	s_waitcnt lgkmcnt(0)
	v_mfma_f32_16x16x32_bf16 v[64:67], v[142:145], v[174:177], v[64:67]
	v_mfma_f32_16x16x32_bf16 v[60:63], v[150:153], v[174:177], v[60:63]
	v_mfma_f32_16x16x32_bf16 v[48:51], v[142:145], v[182:185], v[48:51]
	v_mfma_f32_16x16x32_bf16 v[44:47], v[150:153], v[182:185], v[44:47]
	v_mfma_f32_16x16x32_bf16 v[32:35], v[142:145], v[196:199], v[32:35]
	v_mfma_f32_16x16x32_bf16 v[28:31], v[150:153], v[196:199], v[28:31]
	v_mfma_f32_16x16x32_bf16 v[16:19], v[142:145], v[210:213], v[16:19]
	v_mfma_f32_16x16x32_bf16 v[12:15], v[150:153], v[210:213], v[12:15]
	v_mfma_f32_16x16x32_bf16 v[64:67], v[146:149], v[178:181], v[64:67]
	v_mfma_f32_16x16x32_bf16 v[60:63], v[154:157], v[178:181], v[60:63]
	v_mfma_f32_16x16x32_bf16 v[48:51], v[146:149], v[186:189], v[48:51]
	v_mfma_f32_16x16x32_bf16 v[44:47], v[154:157], v[186:189], v[44:47]
	v_mfma_f32_16x16x32_bf16 v[32:35], v[146:149], v[200:203], v[32:35]
	v_mfma_f32_16x16x32_bf16 v[28:31], v[154:157], v[200:203], v[28:31]
	v_mfma_f32_16x16x32_bf16 v[16:19], v[146:149], v[218:221], v[16:19]
	v_mfma_f32_16x16x32_bf16 v[12:15], v[154:157], v[218:221], v[12:15]
	s_setprio 0
	s_setprio 1
	v_mfma_f32_16x16x32_bf16 v[56:59], v[158:161], v[174:177], v[56:59]
	v_mfma_f32_16x16x32_bf16 v[52:55], v[166:169], v[174:177], v[52:55]
	v_mfma_f32_16x16x32_bf16 v[40:43], v[158:161], v[182:185], v[40:43]
	v_mfma_f32_16x16x32_bf16 v[36:39], v[166:169], v[182:185], v[36:39]
	v_mfma_f32_16x16x32_bf16 v[24:27], v[158:161], v[196:199], v[24:27]
	v_mfma_f32_16x16x32_bf16 v[20:23], v[166:169], v[196:199], v[20:23]
	v_mfma_f32_16x16x32_bf16 v[6:9], v[158:161], v[210:213], v[8:11]
	v_mfma_f32_16x16x32_bf16 v[2:5], v[166:169], v[210:213], v[2:5]
	v_mfma_f32_16x16x32_bf16 v[56:59], v[162:165], v[178:181], v[56:59]
	v_mfma_f32_16x16x32_bf16 v[52:55], v[170:173], v[178:181], v[52:55]
	v_mfma_f32_16x16x32_bf16 v[40:43], v[162:165], v[186:189], v[40:43]
	v_mfma_f32_16x16x32_bf16 v[36:39], v[170:173], v[186:189], v[36:39]
	v_mfma_f32_16x16x32_bf16 v[24:27], v[162:165], v[200:203], v[24:27]
	v_mfma_f32_16x16x32_bf16 v[20:23], v[170:173], v[200:203], v[20:23]
	v_mfma_f32_16x16x32_bf16 v[8:11], v[162:165], v[218:221], v[6:9]
	v_mfma_f32_16x16x32_bf16 v[4:7], v[170:173], v[218:221], v[2:5]
	s_setprio 0
	s_barrier
	s_add_u32 s82, s82, 0x100
	s_addc_u32 s83, s83, 0
	s_add_u32 vcc_lo, vcc_lo, 0x100
	s_addc_u32 vcc_hi, vcc_hi, 0
	s_cmp_ge_i32 s94, s3
	s_mov_b32 s84, s94
	s_cbranch_scc0 .LBB0_1190
